# K-loop MFMA segments arrive at their closing barrier before lowering priority (s_barrier moved ahead of s_setprio 0)
# speedup vs baseline: 1.0128x; 1.0047x over previous
.Lrestag_187:
	ds_read_b128 v[162:165], v157
	ds_read_b128 v[170:173], v157 offset:1024
	ds_read_b128 v[174:177], v157 offset:2048
	ds_read_b128 v[178:181], v157 offset:3072
	ds_read_b128 v[182:185], v158
	ds_read_b128 v[186:189], v158 offset:1024
	ds_read_b128 v[190:193], v158 offset:2048
	ds_read_b128 v[194:197], v158 offset:3072
	s_add_u32 s26, s24, 0x100
	s_addc_u32 s27, s25, 0
	s_cmp_eq_u32 s59, 12
	s_cselect_b32 s31, s17, s27
	s_cselect_b32 s30, s55, s26
	s_cselect_b32 s29, s15, s58
	s_cselect_b32 s28, s56, s57
	s_add_i32 m0, s23, 0xc000
	ds_read_b128 v[198:201], v159
	ds_read_b128 v[202:205], v159 offset:1024
	ds_read_b128 v[206:209], v159 offset:2048
	ds_read_b128 v[210:213], v159 offset:3072
	ds_read_b128 v[214:217], v159 offset:4096
	ds_read_b128 v[218:221], v159 offset:5120
	ds_read_b128 v[222:225], v159 offset:6144
	ds_read_b128 v[226:229], v159 offset:7168
	global_load_lds_dwordx4 v142, s[24:25]
	s_add_i32 m0, s23, 0xe000
	s_nop 0
	global_load_lds_dwordx4 v144, s[24:25]
	s_nop 0
	s_waitcnt lgkmcnt(0)
	s_barrier
	s_setprio 1
	v_mfma_f32_16x16x32_bf16 v[124:127], v[162:165], v[198:201], 0
	v_mfma_f32_16x16x32_bf16 v[120:123], v[174:177], v[198:201], 0
	v_mfma_f32_16x16x32_bf16 v[112:115], v[162:165], v[206:209], 0
	v_mfma_f32_16x16x32_bf16 v[104:107], v[174:177], v[206:209], 0
	v_mfma_f32_16x16x32_bf16 v[96:99], v[162:165], v[214:217], 0
	v_mfma_f32_16x16x32_bf16 v[88:91], v[174:177], v[214:217], 0
	v_mfma_f32_16x16x32_bf16 v[80:83], v[162:165], v[222:225], 0
	v_mfma_f32_16x16x32_bf16 v[72:75], v[174:177], v[222:225], 0
	v_mfma_f32_16x16x32_bf16 v[124:127], v[170:173], v[202:205], v[124:127]
	v_mfma_f32_16x16x32_bf16 v[120:123], v[178:181], v[202:205], v[120:123]
	v_mfma_f32_16x16x32_bf16 v[112:115], v[170:173], v[210:213], v[112:115]
	v_mfma_f32_16x16x32_bf16 v[104:107], v[178:181], v[210:213], v[104:107]
	v_mfma_f32_16x16x32_bf16 v[96:99], v[170:173], v[218:221], v[96:99]
	v_mfma_f32_16x16x32_bf16 v[88:91], v[178:181], v[218:221], v[88:91]
	v_mfma_f32_16x16x32_bf16 v[80:83], v[170:173], v[226:229], v[80:83]
	v_mfma_f32_16x16x32_bf16 v[72:75], v[178:181], v[226:229], v[72:75]
	v_mfma_f32_16x16x32_bf16 v[116:119], v[182:185], v[198:201], 0
	v_mfma_f32_16x16x32_bf16 v[108:111], v[190:193], v[198:201], 0
	v_mfma_f32_16x16x32_bf16 v[100:103], v[182:185], v[206:209], 0
	v_mfma_f32_16x16x32_bf16 v[92:95], v[190:193], v[206:209], 0
	v_mfma_f32_16x16x32_bf16 v[84:87], v[182:185], v[214:217], 0
	v_mfma_f32_16x16x32_bf16 v[76:79], v[190:193], v[214:217], 0
	v_mfma_f32_16x16x32_bf16 v[68:71], v[182:185], v[222:225], 0
	v_mfma_f32_16x16x32_bf16 v[64:67], v[190:193], v[222:225], 0
	v_mfma_f32_16x16x32_bf16 v[116:119], v[186:189], v[202:205], v[116:119]
	v_mfma_f32_16x16x32_bf16 v[108:111], v[194:197], v[202:205], v[108:111]
	v_mfma_f32_16x16x32_bf16 v[100:103], v[186:189], v[210:213], v[100:103]
	v_mfma_f32_16x16x32_bf16 v[92:95], v[194:197], v[210:213], v[92:95]
	v_mfma_f32_16x16x32_bf16 v[84:87], v[186:189], v[218:221], v[84:87]
	v_mfma_f32_16x16x32_bf16 v[76:79], v[194:197], v[218:221], v[76:79]
	v_mfma_f32_16x16x32_bf16 v[68:71], v[186:189], v[226:229], v[68:71]
	v_mfma_f32_16x16x32_bf16 v[64:67], v[194:197], v[226:229], v[64:67]
	s_barrier
	s_setprio 0
	s_add_i32 s0, s51, s41
	v_lshl_add_u64 v[166:167], s[28:29], 0, v[130:131]
	s_mov_b32 m0, s0
	ds_read_b128 v[198:201], v159 offset:16384
	ds_read_b128 v[202:205], v159 offset:17408
	ds_read_b128 v[206:209], v159 offset:18432
	ds_read_b128 v[210:213], v159 offset:19456
	ds_read_b128 v[214:217], v159 offset:20480
	ds_read_b128 v[218:221], v159 offset:21504
	ds_read_b128 v[222:225], v159 offset:22528
	ds_read_b128 v[226:229], v159 offset:23552
	global_load_lds_dwordx4 v[166:167], off
	s_add_i32 m0, s0, 0x2000
	s_add_u32 s0, s28, 0x40000
	v_lshl_add_u64 v[230:231], s[28:29], 0, v[134:135]
	s_addc_u32 s1, s29, 0
	s_add_i32 s24, s52, s41
	global_load_lds_dwordx4 v[230:231], off
	s_mov_b32 m0, s24
	v_lshl_add_u64 v[234:235], s[30:31], 0, v[132:133]
	global_load_lds_dwordx4 v130, s[0:1]
	s_add_i32 m0, s24, 0x2000
	s_nop 0
	global_load_lds_dwordx4 v134, s[0:1]
	v_lshl_add_u64 v[232:233], s[30:31], 0, v[128:129]
	s_nop 0
	s_waitcnt lgkmcnt(0)
	s_barrier
	s_setprio 1
	v_mfma_f32_16x16x32_bf16 v[60:63], v[162:165], v[198:201], 0
	v_mfma_f32_16x16x32_bf16 v[56:59], v[174:177], v[198:201], 0
	v_mfma_f32_16x16x32_bf16 v[48:51], v[162:165], v[206:209], 0
	v_mfma_f32_16x16x32_bf16 v[40:43], v[174:177], v[206:209], 0
	v_mfma_f32_16x16x32_bf16 v[32:35], v[162:165], v[214:217], 0
	v_mfma_f32_16x16x32_bf16 v[24:27], v[174:177], v[214:217], 0
	v_mfma_f32_16x16x32_bf16 v[16:19], v[162:165], v[222:225], 0
	v_mfma_f32_16x16x32_bf16 v[8:11], v[174:177], v[222:225], 0
	v_mfma_f32_16x16x32_bf16 v[60:63], v[170:173], v[202:205], v[60:63]
	v_mfma_f32_16x16x32_bf16 v[56:59], v[178:181], v[202:205], v[56:59]
	v_mfma_f32_16x16x32_bf16 v[48:51], v[170:173], v[210:213], v[48:51]
	v_mfma_f32_16x16x32_bf16 v[40:43], v[178:181], v[210:213], v[40:43]
	v_mfma_f32_16x16x32_bf16 v[32:35], v[170:173], v[218:221], v[32:35]
	v_mfma_f32_16x16x32_bf16 v[24:27], v[178:181], v[218:221], v[24:27]
	v_mfma_f32_16x16x32_bf16 v[16:19], v[170:173], v[226:229], v[16:19]
	v_mfma_f32_16x16x32_bf16 v[8:11], v[178:181], v[226:229], v[8:11]
	v_mfma_f32_16x16x32_bf16 v[52:55], v[182:185], v[198:201], 0
	v_mfma_f32_16x16x32_bf16 v[44:47], v[190:193], v[198:201], 0
	v_mfma_f32_16x16x32_bf16 v[36:39], v[182:185], v[206:209], 0
	v_mfma_f32_16x16x32_bf16 v[28:31], v[190:193], v[206:209], 0
	v_mfma_f32_16x16x32_bf16 v[20:23], v[182:185], v[214:217], 0
	v_mfma_f32_16x16x32_bf16 v[12:15], v[190:193], v[214:217], 0
	v_mfma_f32_16x16x32_bf16 v[4:7], v[182:185], v[222:225], 0
	v_mfma_f32_16x16x32_bf16 v[0:3], v[190:193], v[222:225], 0
	v_mfma_f32_16x16x32_bf16 v[52:55], v[186:189], v[202:205], v[52:55]
	v_mfma_f32_16x16x32_bf16 v[44:47], v[194:197], v[202:205], v[44:47]
	v_mfma_f32_16x16x32_bf16 v[36:39], v[186:189], v[210:213], v[36:39]
	v_mfma_f32_16x16x32_bf16 v[28:31], v[194:197], v[210:213], v[28:31]
	v_mfma_f32_16x16x32_bf16 v[20:23], v[186:189], v[218:221], v[20:23]
	v_mfma_f32_16x16x32_bf16 v[12:15], v[194:197], v[218:221], v[12:15]
	v_mfma_f32_16x16x32_bf16 v[4:7], v[186:189], v[226:229], v[4:7]
	v_mfma_f32_16x16x32_bf16 v[0:3], v[194:197], v[226:229], v[0:3]
	s_barrier
	s_setprio 0
	s_add_i32 s24, 0, 0x18000
	v_add_u32_e32 v150, s24, v153
	s_add_i32 s25, 0, 0x1c000
	ds_read_b128 v[162:165], v150
	ds_read_b128 v[170:173], v150 offset:1024
	ds_read_b128 v[174:177], v150 offset:2048
	ds_read_b128 v[178:181], v150 offset:3072
	v_add_u32_e32 v150, s25, v153
	ds_read_b128 v[182:185], v150
	ds_read_b128 v[186:189], v150 offset:1024
	ds_read_b128 v[190:193], v150 offset:2048
	ds_read_b128 v[194:197], v150 offset:3072
	s_add_u32 s0, s30, 0x40000
	s_addc_u32 s1, s31, 0
	s_mov_b32 m0, s43
	ds_read_b128 v[198:201], v159 offset:32768
	ds_read_b128 v[202:205], v159 offset:33792
	ds_read_b128 v[206:209], v159 offset:34816
	ds_read_b128 v[210:213], v159 offset:35840
	ds_read_b128 v[214:217], v159 offset:36864
	ds_read_b128 v[218:221], v159 offset:37888
	ds_read_b128 v[222:225], v159 offset:38912
	ds_read_b128 v[226:229], v159 offset:39936
	global_load_lds_dwordx4 v128, s[0:1]
	s_mov_b32 m0, s44
	s_nop 0
	global_load_lds_dwordx4 v132, s[0:1]
	s_mov_b32 m0, s23
	s_nop 0
	global_load_lds_dwordx4 v[232:233], off
	s_mov_b32 m0, s42
	s_nop 0
	global_load_lds_dwordx4 v[234:235], off
	s_waitcnt vmcnt(8)
	s_waitcnt lgkmcnt(0)
	s_barrier
	s_setprio 1
	v_mfma_f32_16x16x32_bf16 v[124:127], v[162:165], v[198:201], v[124:127]
	v_mfma_f32_16x16x32_bf16 v[120:123], v[174:177], v[198:201], v[120:123]
	v_mfma_f32_16x16x32_bf16 v[112:115], v[162:165], v[206:209], v[112:115]
	v_mfma_f32_16x16x32_bf16 v[104:107], v[174:177], v[206:209], v[104:107]
	v_mfma_f32_16x16x32_bf16 v[96:99], v[162:165], v[214:217], v[96:99]
	v_mfma_f32_16x16x32_bf16 v[88:91], v[174:177], v[214:217], v[88:91]
	v_mfma_f32_16x16x32_bf16 v[80:83], v[162:165], v[222:225], v[80:83]
	v_mfma_f32_16x16x32_bf16 v[72:75], v[174:177], v[222:225], v[72:75]
	v_mfma_f32_16x16x32_bf16 v[124:127], v[170:173], v[202:205], v[124:127]
	v_mfma_f32_16x16x32_bf16 v[120:123], v[178:181], v[202:205], v[120:123]
	v_mfma_f32_16x16x32_bf16 v[112:115], v[170:173], v[210:213], v[112:115]
	v_mfma_f32_16x16x32_bf16 v[104:107], v[178:181], v[210:213], v[104:107]
	v_mfma_f32_16x16x32_bf16 v[96:99], v[170:173], v[218:221], v[96:99]
	v_mfma_f32_16x16x32_bf16 v[88:91], v[178:181], v[218:221], v[88:91]
	v_mfma_f32_16x16x32_bf16 v[80:83], v[170:173], v[226:229], v[80:83]
	v_mfma_f32_16x16x32_bf16 v[72:75], v[178:181], v[226:229], v[72:75]
	v_mfma_f32_16x16x32_bf16 v[116:119], v[182:185], v[198:201], v[116:119]
	v_mfma_f32_16x16x32_bf16 v[108:111], v[190:193], v[198:201], v[108:111]
	v_mfma_f32_16x16x32_bf16 v[100:103], v[182:185], v[206:209], v[100:103]
	v_mfma_f32_16x16x32_bf16 v[92:95], v[190:193], v[206:209], v[92:95]
	v_mfma_f32_16x16x32_bf16 v[84:87], v[182:185], v[214:217], v[84:87]
	v_mfma_f32_16x16x32_bf16 v[76:79], v[190:193], v[214:217], v[76:79]
	v_mfma_f32_16x16x32_bf16 v[68:71], v[182:185], v[222:225], v[68:71]
	v_mfma_f32_16x16x32_bf16 v[64:67], v[190:193], v[222:225], v[64:67]
	v_mfma_f32_16x16x32_bf16 v[116:119], v[186:189], v[202:205], v[116:119]
	v_mfma_f32_16x16x32_bf16 v[108:111], v[194:197], v[202:205], v[108:111]
	v_mfma_f32_16x16x32_bf16 v[100:103], v[186:189], v[210:213], v[100:103]
	v_mfma_f32_16x16x32_bf16 v[92:95], v[194:197], v[210:213], v[92:95]
	v_mfma_f32_16x16x32_bf16 v[84:87], v[186:189], v[218:221], v[84:87]
	v_mfma_f32_16x16x32_bf16 v[76:79], v[194:197], v[218:221], v[76:79]
	v_mfma_f32_16x16x32_bf16 v[68:71], v[186:189], v[226:229], v[68:71]
	v_mfma_f32_16x16x32_bf16 v[64:67], v[194:197], v[226:229], v[64:67]
	s_barrier
	s_setprio 0
	s_add_i32 s0, s24, s41
	v_lshl_add_u64 v[166:167], v[166:167], 0, s[8:9]
	s_mov_b32 m0, s0
	ds_read_b128 v[198:201], v159 offset:49152
	ds_read_b128 v[202:205], v159 offset:50176
	ds_read_b128 v[206:209], v159 offset:51200
	ds_read_b128 v[210:213], v159 offset:52224
	ds_read_b128 v[214:217], v159 offset:53248
	ds_read_b128 v[218:221], v159 offset:54272
	ds_read_b128 v[222:225], v159 offset:55296
	ds_read_b128 v[226:229], v159 offset:56320
	global_load_lds_dwordx4 v[166:167], off
	s_add_i32 m0, s0, 0x2000
	s_add_u32 s0, s28, 0x40080
	v_lshl_add_u64 v[166:167], v[230:231], 0, s[8:9]
	s_addc_u32 s1, s29, 0
	s_add_i32 s24, s25, s41
	global_load_lds_dwordx4 v[166:167], off
	s_mov_b32 m0, s24
	s_nop 0
	global_load_lds_dwordx4 v130, s[0:1]
	s_add_i32 m0, s24, 0x2000
	s_nop 0
	global_load_lds_dwordx4 v134, s[0:1]
	v_lshl_add_u64 v[166:167], v[232:233], 0, s[8:9]
	s_mov_b32 m0, s47
	s_nop 0
	global_load_lds_dwordx4 v[166:167], off
	v_lshl_add_u64 v[166:167], v[234:235], 0, s[8:9]
	s_mov_b32 m0, s48
	s_nop 0
	global_load_lds_dwordx4 v[166:167], off
	s_waitcnt vmcnt(6)
	s_waitcnt lgkmcnt(0)
	s_barrier
	s_setprio 1
	v_mfma_f32_16x16x32_bf16 v[60:63], v[162:165], v[198:201], v[60:63]
	v_mfma_f32_16x16x32_bf16 v[56:59], v[174:177], v[198:201], v[56:59]
	v_mfma_f32_16x16x32_bf16 v[48:51], v[162:165], v[206:209], v[48:51]
	v_mfma_f32_16x16x32_bf16 v[40:43], v[174:177], v[206:209], v[40:43]
	v_mfma_f32_16x16x32_bf16 v[32:35], v[162:165], v[214:217], v[32:35]
	v_mfma_f32_16x16x32_bf16 v[24:27], v[174:177], v[214:217], v[24:27]
	v_mfma_f32_16x16x32_bf16 v[16:19], v[162:165], v[222:225], v[16:19]
	v_mfma_f32_16x16x32_bf16 v[8:11], v[174:177], v[222:225], v[8:11]
	v_mfma_f32_16x16x32_bf16 v[60:63], v[170:173], v[202:205], v[60:63]
	v_mfma_f32_16x16x32_bf16 v[56:59], v[178:181], v[202:205], v[56:59]
	v_mfma_f32_16x16x32_bf16 v[48:51], v[170:173], v[210:213], v[48:51]
	v_mfma_f32_16x16x32_bf16 v[40:43], v[178:181], v[210:213], v[40:43]
	v_mfma_f32_16x16x32_bf16 v[32:35], v[170:173], v[218:221], v[32:35]
	v_mfma_f32_16x16x32_bf16 v[24:27], v[178:181], v[218:221], v[24:27]
	v_mfma_f32_16x16x32_bf16 v[16:19], v[170:173], v[226:229], v[16:19]
	v_mfma_f32_16x16x32_bf16 v[8:11], v[178:181], v[226:229], v[8:11]
	v_mfma_f32_16x16x32_bf16 v[52:55], v[182:185], v[198:201], v[52:55]
	v_mfma_f32_16x16x32_bf16 v[44:47], v[190:193], v[198:201], v[44:47]
	v_mfma_f32_16x16x32_bf16 v[36:39], v[182:185], v[206:209], v[36:39]
	v_mfma_f32_16x16x32_bf16 v[28:31], v[190:193], v[206:209], v[28:31]
	v_mfma_f32_16x16x32_bf16 v[20:23], v[182:185], v[214:217], v[20:23]
	v_mfma_f32_16x16x32_bf16 v[12:15], v[190:193], v[214:217], v[12:15]
	v_mfma_f32_16x16x32_bf16 v[4:7], v[182:185], v[222:225], v[4:7]
	v_mfma_f32_16x16x32_bf16 v[0:3], v[190:193], v[222:225], v[0:3]
	v_mfma_f32_16x16x32_bf16 v[52:55], v[186:189], v[202:205], v[52:55]
	v_mfma_f32_16x16x32_bf16 v[44:47], v[194:197], v[202:205], v[44:47]
	v_mfma_f32_16x16x32_bf16 v[36:39], v[186:189], v[210:213], v[36:39]
	v_mfma_f32_16x16x32_bf16 v[28:31], v[194:197], v[210:213], v[28:31]
	v_mfma_f32_16x16x32_bf16 v[20:23], v[186:189], v[218:221], v[20:23]
	v_mfma_f32_16x16x32_bf16 v[12:15], v[194:197], v[218:221], v[12:15]
	v_mfma_f32_16x16x32_bf16 v[4:7], v[186:189], v[226:229], v[4:7]
	v_mfma_f32_16x16x32_bf16 v[0:3], v[194:197], v[226:229], v[0:3]
	s_barrier
	s_setprio 0
	s_add_i32 s59, s59, 2
	s_add_u32 s57, s57, 0x100
	s_addc_u32 s58, s58, 0
	s_cmp_gt_u32 s59, 13
	s_mov_b64 s[24:25], s[26:27]
.LBB0_187:
	ds_read_b128 v[162:165], v157
	ds_read_b128 v[170:173], v157 offset:1024
	ds_read_b128 v[174:177], v157 offset:2048
	ds_read_b128 v[178:181], v157 offset:3072
	ds_read_b128 v[182:185], v158
	ds_read_b128 v[186:189], v158 offset:1024
	ds_read_b128 v[190:193], v158 offset:2048
	ds_read_b128 v[194:197], v158 offset:3072
	s_add_u32 s26, s24, 0x100
	s_addc_u32 s27, s25, 0
	s_cmp_eq_u32 s59, 12
	s_cselect_b32 s31, s17, s27
	s_cselect_b32 s30, s55, s26
	s_cselect_b32 s29, s15, s58
	s_cselect_b32 s28, s56, s57
	s_add_i32 m0, s23, 0xc000
	ds_read_b128 v[198:201], v159
	ds_read_b128 v[202:205], v159 offset:1024
	ds_read_b128 v[206:209], v159 offset:2048
	ds_read_b128 v[210:213], v159 offset:3072
	ds_read_b128 v[214:217], v159 offset:4096
	ds_read_b128 v[218:221], v159 offset:5120
	ds_read_b128 v[222:225], v159 offset:6144
	ds_read_b128 v[226:229], v159 offset:7168
	global_load_lds_dwordx4 v142, s[24:25]
	s_add_i32 m0, s23, 0xe000
	s_nop 0
	global_load_lds_dwordx4 v144, s[24:25]
	s_waitcnt vmcnt(8)
	s_waitcnt lgkmcnt(0)
	s_barrier
	s_setprio 1
	v_mfma_f32_16x16x32_bf16 v[124:127], v[162:165], v[198:201], v[124:127]
	v_mfma_f32_16x16x32_bf16 v[120:123], v[174:177], v[198:201], v[120:123]
	v_mfma_f32_16x16x32_bf16 v[112:115], v[162:165], v[206:209], v[112:115]
	v_mfma_f32_16x16x32_bf16 v[104:107], v[174:177], v[206:209], v[104:107]
	v_mfma_f32_16x16x32_bf16 v[96:99], v[162:165], v[214:217], v[96:99]
	v_mfma_f32_16x16x32_bf16 v[88:91], v[174:177], v[214:217], v[88:91]
	v_mfma_f32_16x16x32_bf16 v[80:83], v[162:165], v[222:225], v[80:83]
	v_mfma_f32_16x16x32_bf16 v[72:75], v[174:177], v[222:225], v[72:75]
	v_mfma_f32_16x16x32_bf16 v[124:127], v[170:173], v[202:205], v[124:127]
	v_mfma_f32_16x16x32_bf16 v[120:123], v[178:181], v[202:205], v[120:123]
	v_mfma_f32_16x16x32_bf16 v[112:115], v[170:173], v[210:213], v[112:115]
	v_mfma_f32_16x16x32_bf16 v[104:107], v[178:181], v[210:213], v[104:107]
	v_mfma_f32_16x16x32_bf16 v[96:99], v[170:173], v[218:221], v[96:99]
	v_mfma_f32_16x16x32_bf16 v[88:91], v[178:181], v[218:221], v[88:91]
	v_mfma_f32_16x16x32_bf16 v[80:83], v[170:173], v[226:229], v[80:83]
	v_mfma_f32_16x16x32_bf16 v[72:75], v[178:181], v[226:229], v[72:75]
	v_mfma_f32_16x16x32_bf16 v[116:119], v[182:185], v[198:201], v[116:119]
	v_mfma_f32_16x16x32_bf16 v[108:111], v[190:193], v[198:201], v[108:111]
	v_mfma_f32_16x16x32_bf16 v[100:103], v[182:185], v[206:209], v[100:103]
	v_mfma_f32_16x16x32_bf16 v[92:95], v[190:193], v[206:209], v[92:95]
	v_mfma_f32_16x16x32_bf16 v[84:87], v[182:185], v[214:217], v[84:87]
	v_mfma_f32_16x16x32_bf16 v[76:79], v[190:193], v[214:217], v[76:79]
	v_mfma_f32_16x16x32_bf16 v[68:71], v[182:185], v[222:225], v[68:71]
	v_mfma_f32_16x16x32_bf16 v[64:67], v[190:193], v[222:225], v[64:67]
	v_mfma_f32_16x16x32_bf16 v[116:119], v[186:189], v[202:205], v[116:119]
	v_mfma_f32_16x16x32_bf16 v[108:111], v[194:197], v[202:205], v[108:111]
	v_mfma_f32_16x16x32_bf16 v[100:103], v[186:189], v[210:213], v[100:103]
	v_mfma_f32_16x16x32_bf16 v[92:95], v[194:197], v[210:213], v[92:95]
	v_mfma_f32_16x16x32_bf16 v[84:87], v[186:189], v[218:221], v[84:87]
	v_mfma_f32_16x16x32_bf16 v[76:79], v[194:197], v[218:221], v[76:79]
	v_mfma_f32_16x16x32_bf16 v[68:71], v[186:189], v[226:229], v[68:71]
	v_mfma_f32_16x16x32_bf16 v[64:67], v[194:197], v[226:229], v[64:67]
	s_barrier
	s_setprio 0
	s_add_i32 s0, s51, s41
	v_lshl_add_u64 v[166:167], s[28:29], 0, v[130:131]
	s_mov_b32 m0, s0
	ds_read_b128 v[198:201], v159 offset:16384
	ds_read_b128 v[202:205], v159 offset:17408
	ds_read_b128 v[206:209], v159 offset:18432
	ds_read_b128 v[210:213], v159 offset:19456
	ds_read_b128 v[214:217], v159 offset:20480
	ds_read_b128 v[218:221], v159 offset:21504
	ds_read_b128 v[222:225], v159 offset:22528
	ds_read_b128 v[226:229], v159 offset:23552
	global_load_lds_dwordx4 v[166:167], off
	s_add_i32 m0, s0, 0x2000
	s_add_u32 s0, s28, 0x40000
	v_lshl_add_u64 v[230:231], s[28:29], 0, v[134:135]
	s_addc_u32 s1, s29, 0
	s_add_i32 s24, s52, s41
	global_load_lds_dwordx4 v[230:231], off
	s_mov_b32 m0, s24
	v_lshl_add_u64 v[234:235], s[30:31], 0, v[132:133]
	global_load_lds_dwordx4 v130, s[0:1]
	s_add_i32 m0, s24, 0x2000
	s_nop 0
	global_load_lds_dwordx4 v134, s[0:1]
	v_lshl_add_u64 v[232:233], s[30:31], 0, v[128:129]
	s_waitcnt vmcnt(6)
	s_waitcnt lgkmcnt(0)
	s_barrier
	s_setprio 1
	v_mfma_f32_16x16x32_bf16 v[60:63], v[162:165], v[198:201], v[60:63]
	v_mfma_f32_16x16x32_bf16 v[56:59], v[174:177], v[198:201], v[56:59]
	v_mfma_f32_16x16x32_bf16 v[48:51], v[162:165], v[206:209], v[48:51]
	v_mfma_f32_16x16x32_bf16 v[40:43], v[174:177], v[206:209], v[40:43]
	v_mfma_f32_16x16x32_bf16 v[32:35], v[162:165], v[214:217], v[32:35]
	v_mfma_f32_16x16x32_bf16 v[24:27], v[174:177], v[214:217], v[24:27]
	v_mfma_f32_16x16x32_bf16 v[16:19], v[162:165], v[222:225], v[16:19]
	v_mfma_f32_16x16x32_bf16 v[8:11], v[174:177], v[222:225], v[8:11]
	v_mfma_f32_16x16x32_bf16 v[60:63], v[170:173], v[202:205], v[60:63]
	v_mfma_f32_16x16x32_bf16 v[56:59], v[178:181], v[202:205], v[56:59]
	v_mfma_f32_16x16x32_bf16 v[48:51], v[170:173], v[210:213], v[48:51]
	v_mfma_f32_16x16x32_bf16 v[40:43], v[178:181], v[210:213], v[40:43]
	v_mfma_f32_16x16x32_bf16 v[32:35], v[170:173], v[218:221], v[32:35]
	v_mfma_f32_16x16x32_bf16 v[24:27], v[178:181], v[218:221], v[24:27]
	v_mfma_f32_16x16x32_bf16 v[16:19], v[170:173], v[226:229], v[16:19]
	v_mfma_f32_16x16x32_bf16 v[8:11], v[178:181], v[226:229], v[8:11]
	v_mfma_f32_16x16x32_bf16 v[52:55], v[182:185], v[198:201], v[52:55]
	v_mfma_f32_16x16x32_bf16 v[44:47], v[190:193], v[198:201], v[44:47]
	v_mfma_f32_16x16x32_bf16 v[36:39], v[182:185], v[206:209], v[36:39]
	v_mfma_f32_16x16x32_bf16 v[28:31], v[190:193], v[206:209], v[28:31]
	v_mfma_f32_16x16x32_bf16 v[20:23], v[182:185], v[214:217], v[20:23]
	v_mfma_f32_16x16x32_bf16 v[12:15], v[190:193], v[214:217], v[12:15]
	v_mfma_f32_16x16x32_bf16 v[4:7], v[182:185], v[222:225], v[4:7]
	v_mfma_f32_16x16x32_bf16 v[0:3], v[190:193], v[222:225], v[0:3]
	v_mfma_f32_16x16x32_bf16 v[52:55], v[186:189], v[202:205], v[52:55]
	v_mfma_f32_16x16x32_bf16 v[44:47], v[194:197], v[202:205], v[44:47]
	v_mfma_f32_16x16x32_bf16 v[36:39], v[186:189], v[210:213], v[36:39]
	v_mfma_f32_16x16x32_bf16 v[28:31], v[194:197], v[210:213], v[28:31]
	v_mfma_f32_16x16x32_bf16 v[20:23], v[186:189], v[218:221], v[20:23]
	v_mfma_f32_16x16x32_bf16 v[12:15], v[194:197], v[218:221], v[12:15]
	v_mfma_f32_16x16x32_bf16 v[4:7], v[186:189], v[226:229], v[4:7]
	v_mfma_f32_16x16x32_bf16 v[0:3], v[194:197], v[226:229], v[0:3]
	s_barrier
	s_setprio 0
	s_add_i32 s24, 0, 0x18000
	v_add_u32_e32 v150, s24, v153
	s_add_i32 s25, 0, 0x1c000
	ds_read_b128 v[162:165], v150
	ds_read_b128 v[170:173], v150 offset:1024
	ds_read_b128 v[174:177], v150 offset:2048
	ds_read_b128 v[178:181], v150 offset:3072
	v_add_u32_e32 v150, s25, v153
	ds_read_b128 v[182:185], v150
	ds_read_b128 v[186:189], v150 offset:1024
	ds_read_b128 v[190:193], v150 offset:2048
	ds_read_b128 v[194:197], v150 offset:3072
	s_add_u32 s0, s30, 0x40000
	s_addc_u32 s1, s31, 0
	s_mov_b32 m0, s43
	ds_read_b128 v[198:201], v159 offset:32768
	ds_read_b128 v[202:205], v159 offset:33792
	ds_read_b128 v[206:209], v159 offset:34816
	ds_read_b128 v[210:213], v159 offset:35840
	ds_read_b128 v[214:217], v159 offset:36864
	ds_read_b128 v[218:221], v159 offset:37888
	ds_read_b128 v[222:225], v159 offset:38912
	ds_read_b128 v[226:229], v159 offset:39936
	global_load_lds_dwordx4 v128, s[0:1]
	s_mov_b32 m0, s44
	s_nop 0
	global_load_lds_dwordx4 v132, s[0:1]
	s_mov_b32 m0, s23
	s_nop 0
	global_load_lds_dwordx4 v[232:233], off
	s_mov_b32 m0, s42
	s_nop 0
	global_load_lds_dwordx4 v[234:235], off
	s_waitcnt vmcnt(8)
	s_waitcnt lgkmcnt(0)
	s_barrier
	s_setprio 1
	v_mfma_f32_16x16x32_bf16 v[124:127], v[162:165], v[198:201], v[124:127]
	v_mfma_f32_16x16x32_bf16 v[120:123], v[174:177], v[198:201], v[120:123]
	v_mfma_f32_16x16x32_bf16 v[112:115], v[162:165], v[206:209], v[112:115]
	v_mfma_f32_16x16x32_bf16 v[104:107], v[174:177], v[206:209], v[104:107]
	v_mfma_f32_16x16x32_bf16 v[96:99], v[162:165], v[214:217], v[96:99]
	v_mfma_f32_16x16x32_bf16 v[88:91], v[174:177], v[214:217], v[88:91]
	v_mfma_f32_16x16x32_bf16 v[80:83], v[162:165], v[222:225], v[80:83]
	v_mfma_f32_16x16x32_bf16 v[72:75], v[174:177], v[222:225], v[72:75]
	v_mfma_f32_16x16x32_bf16 v[124:127], v[170:173], v[202:205], v[124:127]
	v_mfma_f32_16x16x32_bf16 v[120:123], v[178:181], v[202:205], v[120:123]
	v_mfma_f32_16x16x32_bf16 v[112:115], v[170:173], v[210:213], v[112:115]
	v_mfma_f32_16x16x32_bf16 v[104:107], v[178:181], v[210:213], v[104:107]
	v_mfma_f32_16x16x32_bf16 v[96:99], v[170:173], v[218:221], v[96:99]
	v_mfma_f32_16x16x32_bf16 v[88:91], v[178:181], v[218:221], v[88:91]
	v_mfma_f32_16x16x32_bf16 v[80:83], v[170:173], v[226:229], v[80:83]
	v_mfma_f32_16x16x32_bf16 v[72:75], v[178:181], v[226:229], v[72:75]
	v_mfma_f32_16x16x32_bf16 v[116:119], v[182:185], v[198:201], v[116:119]
	v_mfma_f32_16x16x32_bf16 v[108:111], v[190:193], v[198:201], v[108:111]
	v_mfma_f32_16x16x32_bf16 v[100:103], v[182:185], v[206:209], v[100:103]
	v_mfma_f32_16x16x32_bf16 v[92:95], v[190:193], v[206:209], v[92:95]
	v_mfma_f32_16x16x32_bf16 v[84:87], v[182:185], v[214:217], v[84:87]
	v_mfma_f32_16x16x32_bf16 v[76:79], v[190:193], v[214:217], v[76:79]
	v_mfma_f32_16x16x32_bf16 v[68:71], v[182:185], v[222:225], v[68:71]
	v_mfma_f32_16x16x32_bf16 v[64:67], v[190:193], v[222:225], v[64:67]
	v_mfma_f32_16x16x32_bf16 v[116:119], v[186:189], v[202:205], v[116:119]
	v_mfma_f32_16x16x32_bf16 v[108:111], v[194:197], v[202:205], v[108:111]
	v_mfma_f32_16x16x32_bf16 v[100:103], v[186:189], v[210:213], v[100:103]
	v_mfma_f32_16x16x32_bf16 v[92:95], v[194:197], v[210:213], v[92:95]
	v_mfma_f32_16x16x32_bf16 v[84:87], v[186:189], v[218:221], v[84:87]
	v_mfma_f32_16x16x32_bf16 v[76:79], v[194:197], v[218:221], v[76:79]
	v_mfma_f32_16x16x32_bf16 v[68:71], v[186:189], v[226:229], v[68:71]
	v_mfma_f32_16x16x32_bf16 v[64:67], v[194:197], v[226:229], v[64:67]
	s_barrier
	s_setprio 0
	s_add_i32 s0, s24, s41
	v_lshl_add_u64 v[166:167], v[166:167], 0, s[8:9]
	s_mov_b32 m0, s0
	ds_read_b128 v[198:201], v159 offset:49152
	ds_read_b128 v[202:205], v159 offset:50176
	ds_read_b128 v[206:209], v159 offset:51200
	ds_read_b128 v[210:213], v159 offset:52224
	ds_read_b128 v[214:217], v159 offset:53248
	ds_read_b128 v[218:221], v159 offset:54272
	ds_read_b128 v[222:225], v159 offset:55296
	ds_read_b128 v[226:229], v159 offset:56320
	global_load_lds_dwordx4 v[166:167], off
	s_add_i32 m0, s0, 0x2000
	s_add_u32 s0, s28, 0x40080
	v_lshl_add_u64 v[166:167], v[230:231], 0, s[8:9]
	s_addc_u32 s1, s29, 0
	s_add_i32 s24, s25, s41
	global_load_lds_dwordx4 v[166:167], off
	s_mov_b32 m0, s24
	s_nop 0
	global_load_lds_dwordx4 v130, s[0:1]
	s_add_i32 m0, s24, 0x2000
	s_nop 0
	global_load_lds_dwordx4 v134, s[0:1]
	v_lshl_add_u64 v[166:167], v[232:233], 0, s[8:9]
	s_mov_b32 m0, s47
	s_nop 0
	global_load_lds_dwordx4 v[166:167], off
	v_lshl_add_u64 v[166:167], v[234:235], 0, s[8:9]
	s_mov_b32 m0, s48
	s_nop 0
	global_load_lds_dwordx4 v[166:167], off
	s_waitcnt vmcnt(6)
	s_waitcnt lgkmcnt(0)
	s_barrier
	s_setprio 1
	v_mfma_f32_16x16x32_bf16 v[60:63], v[162:165], v[198:201], v[60:63]
	v_mfma_f32_16x16x32_bf16 v[56:59], v[174:177], v[198:201], v[56:59]
	v_mfma_f32_16x16x32_bf16 v[48:51], v[162:165], v[206:209], v[48:51]
	v_mfma_f32_16x16x32_bf16 v[40:43], v[174:177], v[206:209], v[40:43]
	v_mfma_f32_16x16x32_bf16 v[32:35], v[162:165], v[214:217], v[32:35]
	v_mfma_f32_16x16x32_bf16 v[24:27], v[174:177], v[214:217], v[24:27]
	v_mfma_f32_16x16x32_bf16 v[16:19], v[162:165], v[222:225], v[16:19]
	v_mfma_f32_16x16x32_bf16 v[8:11], v[174:177], v[222:225], v[8:11]
	v_mfma_f32_16x16x32_bf16 v[60:63], v[170:173], v[202:205], v[60:63]
	v_mfma_f32_16x16x32_bf16 v[56:59], v[178:181], v[202:205], v[56:59]
	v_mfma_f32_16x16x32_bf16 v[48:51], v[170:173], v[210:213], v[48:51]
	v_mfma_f32_16x16x32_bf16 v[40:43], v[178:181], v[210:213], v[40:43]
	v_mfma_f32_16x16x32_bf16 v[32:35], v[170:173], v[218:221], v[32:35]
	v_mfma_f32_16x16x32_bf16 v[24:27], v[178:181], v[218:221], v[24:27]
	v_mfma_f32_16x16x32_bf16 v[16:19], v[170:173], v[226:229], v[16:19]
	v_mfma_f32_16x16x32_bf16 v[8:11], v[178:181], v[226:229], v[8:11]
	v_mfma_f32_16x16x32_bf16 v[52:55], v[182:185], v[198:201], v[52:55]
	v_mfma_f32_16x16x32_bf16 v[44:47], v[190:193], v[198:201], v[44:47]
	v_mfma_f32_16x16x32_bf16 v[36:39], v[182:185], v[206:209], v[36:39]
	v_mfma_f32_16x16x32_bf16 v[28:31], v[190:193], v[206:209], v[28:31]
	v_mfma_f32_16x16x32_bf16 v[20:23], v[182:185], v[214:217], v[20:23]
	v_mfma_f32_16x16x32_bf16 v[12:15], v[190:193], v[214:217], v[12:15]
	v_mfma_f32_16x16x32_bf16 v[4:7], v[182:185], v[222:225], v[4:7]
	v_mfma_f32_16x16x32_bf16 v[0:3], v[190:193], v[222:225], v[0:3]
	v_mfma_f32_16x16x32_bf16 v[52:55], v[186:189], v[202:205], v[52:55]
	v_mfma_f32_16x16x32_bf16 v[44:47], v[194:197], v[202:205], v[44:47]
	v_mfma_f32_16x16x32_bf16 v[36:39], v[186:189], v[210:213], v[36:39]
	v_mfma_f32_16x16x32_bf16 v[28:31], v[194:197], v[210:213], v[28:31]
	v_mfma_f32_16x16x32_bf16 v[20:23], v[186:189], v[218:221], v[20:23]
	v_mfma_f32_16x16x32_bf16 v[12:15], v[194:197], v[218:221], v[12:15]
	v_mfma_f32_16x16x32_bf16 v[4:7], v[186:189], v[226:229], v[4:7]
	v_mfma_f32_16x16x32_bf16 v[0:3], v[194:197], v[226:229], v[0:3]
	s_barrier
	s_setprio 0
	s_add_i32 s59, s59, 2
	s_add_u32 s57, s57, 0x100
	s_addc_u32 s58, s58, 0
	s_cmp_gt_u32 s59, 13
	s_mov_b64 s[24:25], s[26:27]
	s_cbranch_scc0 .LBB0_187
	s_and_b64 vcc, exec, s[12:13]
	s_cbranch_vccz .LBB0_190
	s_barrier

.Lrestag_402:
	ds_read_b128 v[120:123], v205
	ds_read_b128 v[124:127], v205 offset:1024
	ds_read_b128 v[132:135], v205 offset:2048
	ds_read_b128 v[140:143], v205 offset:3072
	ds_read_b128 v[144:147], v206
	ds_read_b128 v[148:151], v206 offset:1024
	ds_read_b128 v[152:155], v206 offset:2048
	ds_read_b128 v[156:159], v206 offset:3072
	s_add_u32 s22, s20, 0x100
	s_addc_u32 s23, s21, 0
	s_cmp_eq_u32 s54, 6
	s_cselect_b32 s27, s7, s23
	s_cselect_b32 s26, s6, s22
	s_cselect_b32 s25, s19, s53
	s_cselect_b32 s24, s18, s52
	s_add_i32 m0, s35, 0xc000
	ds_read_b128 v[180:183], v207
	ds_read_b128 v[184:187], v207 offset:1024
	ds_read_b128 v[188:191], v207 offset:2048
	ds_read_b128 v[192:195], v207 offset:3072
	ds_read_b128 v[196:199], v207 offset:4096
	ds_read_b128 v[208:211], v207 offset:5120
	ds_read_b128 v[212:215], v207 offset:6144
	ds_read_b128 v[216:219], v207 offset:7168
	global_load_lds_dwordx4 v172, s[20:21]
	s_add_i32 m0, s35, 0xe000
	s_nop 0
	global_load_lds_dwordx4 v174, s[20:21]
	s_nop 0
	s_waitcnt lgkmcnt(0)
	s_barrier
	s_setprio 1
	v_mfma_f32_16x16x32_bf16 v[136:139], v[120:123], v[180:183], 0
	v_mfma_f32_16x16x32_bf16 v[128:131], v[132:135], v[180:183], 0
	v_mfma_f32_16x16x32_bf16 v[116:119], v[120:123], v[188:191], 0
	v_mfma_f32_16x16x32_bf16 v[112:115], v[132:135], v[188:191], 0
	v_mfma_f32_16x16x32_bf16 v[108:111], v[120:123], v[196:199], 0
	v_mfma_f32_16x16x32_bf16 v[104:107], v[132:135], v[196:199], 0
	v_mfma_f32_16x16x32_bf16 v[100:103], v[120:123], v[212:215], 0
	v_mfma_f32_16x16x32_bf16 v[96:99], v[132:135], v[212:215], 0
	v_mfma_f32_16x16x32_bf16 v[136:139], v[124:127], v[184:187], v[136:139]
	v_mfma_f32_16x16x32_bf16 v[128:131], v[140:143], v[184:187], v[128:131]
	v_mfma_f32_16x16x32_bf16 v[116:119], v[124:127], v[192:195], v[116:119]
	v_mfma_f32_16x16x32_bf16 v[112:115], v[140:143], v[192:195], v[112:115]
	v_mfma_f32_16x16x32_bf16 v[108:111], v[124:127], v[208:211], v[108:111]
	v_mfma_f32_16x16x32_bf16 v[104:107], v[140:143], v[208:211], v[104:107]
	v_mfma_f32_16x16x32_bf16 v[100:103], v[124:127], v[216:219], v[100:103]
	v_mfma_f32_16x16x32_bf16 v[96:99], v[140:143], v[216:219], v[96:99]
	v_mfma_f32_16x16x32_bf16 v[60:63], v[144:147], v[180:183], 0
	v_mfma_f32_16x16x32_bf16 v[56:59], v[152:155], v[180:183], 0
	v_mfma_f32_16x16x32_bf16 v[52:55], v[144:147], v[188:191], 0
	v_mfma_f32_16x16x32_bf16 v[48:51], v[152:155], v[188:191], 0
	v_mfma_f32_16x16x32_bf16 v[44:47], v[144:147], v[196:199], 0
	v_mfma_f32_16x16x32_bf16 v[40:43], v[152:155], v[196:199], 0
	v_mfma_f32_16x16x32_bf16 v[36:39], v[144:147], v[212:215], 0
	v_mfma_f32_16x16x32_bf16 v[32:35], v[152:155], v[212:215], 0
	v_mfma_f32_16x16x32_bf16 v[60:63], v[148:151], v[184:187], v[60:63]
	v_mfma_f32_16x16x32_bf16 v[56:59], v[156:159], v[184:187], v[56:59]
	v_mfma_f32_16x16x32_bf16 v[52:55], v[148:151], v[192:195], v[52:55]
	v_mfma_f32_16x16x32_bf16 v[48:51], v[156:159], v[192:195], v[48:51]
	v_mfma_f32_16x16x32_bf16 v[44:47], v[148:151], v[208:211], v[44:47]
	v_mfma_f32_16x16x32_bf16 v[40:43], v[156:159], v[208:211], v[40:43]
	v_mfma_f32_16x16x32_bf16 v[36:39], v[148:151], v[216:219], v[36:39]
	v_mfma_f32_16x16x32_bf16 v[32:35], v[156:159], v[216:219], v[32:35]
	s_barrier
	s_setprio 0
	s_add_i32 s0, s46, s34
	v_lshl_add_u64 v[200:201], s[24:25], 0, v[162:163]
	s_mov_b32 m0, s0
	ds_read_b128 v[180:183], v207 offset:16384
	ds_read_b128 v[184:187], v207 offset:17408
	ds_read_b128 v[188:191], v207 offset:18432
	ds_read_b128 v[192:195], v207 offset:19456
	ds_read_b128 v[196:199], v207 offset:20480
	ds_read_b128 v[208:211], v207 offset:21504
	ds_read_b128 v[212:215], v207 offset:22528
	ds_read_b128 v[216:219], v207 offset:23552
	global_load_lds_dwordx4 v[200:201], off
	s_add_i32 m0, s0, 0x2000
	s_add_u32 s0, s24, 0x28000
	v_lshl_add_u64 v[220:221], s[24:25], 0, v[166:167]
	s_addc_u32 s1, s25, 0
	s_add_i32 s20, s47, s34
	global_load_lds_dwordx4 v[220:221], off
	s_mov_b32 m0, s20
	v_lshl_add_u64 v[224:225], s[26:27], 0, v[164:165]
	global_load_lds_dwordx4 v162, s[0:1]
	s_add_i32 m0, s20, 0x2000
	s_nop 0
	global_load_lds_dwordx4 v166, s[0:1]
	v_lshl_add_u64 v[222:223], s[26:27], 0, v[160:161]
	s_nop 0
	s_waitcnt lgkmcnt(0)
	s_barrier
	s_setprio 1
	v_mfma_f32_16x16x32_bf16 v[92:95], v[120:123], v[180:183], 0
	v_mfma_f32_16x16x32_bf16 v[88:91], v[132:135], v[180:183], 0
	v_mfma_f32_16x16x32_bf16 v[84:87], v[120:123], v[188:191], 0
	v_mfma_f32_16x16x32_bf16 v[80:83], v[132:135], v[188:191], 0
	v_mfma_f32_16x16x32_bf16 v[76:79], v[120:123], v[196:199], 0
	v_mfma_f32_16x16x32_bf16 v[72:75], v[132:135], v[196:199], 0
	v_mfma_f32_16x16x32_bf16 v[68:71], v[120:123], v[212:215], 0
	v_mfma_f32_16x16x32_bf16 v[64:67], v[132:135], v[212:215], 0
	v_mfma_f32_16x16x32_bf16 v[92:95], v[124:127], v[184:187], v[92:95]
	v_mfma_f32_16x16x32_bf16 v[88:91], v[140:143], v[184:187], v[88:91]
	v_mfma_f32_16x16x32_bf16 v[84:87], v[124:127], v[192:195], v[84:87]
	v_mfma_f32_16x16x32_bf16 v[80:83], v[140:143], v[192:195], v[80:83]
	v_mfma_f32_16x16x32_bf16 v[76:79], v[124:127], v[208:211], v[76:79]
	v_mfma_f32_16x16x32_bf16 v[72:75], v[140:143], v[208:211], v[72:75]
	v_mfma_f32_16x16x32_bf16 v[68:71], v[124:127], v[216:219], v[68:71]
	v_mfma_f32_16x16x32_bf16 v[64:67], v[140:143], v[216:219], v[64:67]
	v_mfma_f32_16x16x32_bf16 v[28:31], v[144:147], v[180:183], 0
	v_mfma_f32_16x16x32_bf16 v[24:27], v[152:155], v[180:183], 0
	v_mfma_f32_16x16x32_bf16 v[20:23], v[144:147], v[188:191], 0
	v_mfma_f32_16x16x32_bf16 v[16:19], v[152:155], v[188:191], 0
	v_mfma_f32_16x16x32_bf16 v[12:15], v[144:147], v[196:199], 0
	v_mfma_f32_16x16x32_bf16 v[8:11], v[152:155], v[196:199], 0
	v_mfma_f32_16x16x32_bf16 v[4:7], v[144:147], v[212:215], 0
	v_mfma_f32_16x16x32_bf16 v[0:3], v[152:155], v[212:215], 0
	v_mfma_f32_16x16x32_bf16 v[28:31], v[148:151], v[184:187], v[28:31]
	v_mfma_f32_16x16x32_bf16 v[24:27], v[156:159], v[184:187], v[24:27]
	v_mfma_f32_16x16x32_bf16 v[20:23], v[148:151], v[192:195], v[20:23]
	v_mfma_f32_16x16x32_bf16 v[16:19], v[156:159], v[192:195], v[16:19]
	v_mfma_f32_16x16x32_bf16 v[12:15], v[148:151], v[208:211], v[12:15]
	v_mfma_f32_16x16x32_bf16 v[8:11], v[156:159], v[208:211], v[8:11]
	v_mfma_f32_16x16x32_bf16 v[4:7], v[148:151], v[216:219], v[4:7]
	v_mfma_f32_16x16x32_bf16 v[0:3], v[156:159], v[216:219], v[0:3]
	s_barrier
	s_setprio 0
	s_add_i32 s20, 0, 0x18000
	s_add_i32 s21, 0, 0x1c000
	v_add_u32_e32 v140, s20, v203
	v_add_u32_e32 v156, s21, v203
	ds_read_b128 v[120:123], v140
	ds_read_b128 v[124:127], v140 offset:1024
	ds_read_b128 v[132:135], v140 offset:2048
	ds_read_b128 v[140:143], v140 offset:3072
	ds_read_b128 v[144:147], v156
	ds_read_b128 v[148:151], v156 offset:1024
	ds_read_b128 v[152:155], v156 offset:2048
	ds_read_b128 v[156:159], v156 offset:3072
	s_add_u32 s0, s26, 0x28000
	s_addc_u32 s1, s27, 0
	s_mov_b32 m0, s37
	ds_read_b128 v[180:183], v207 offset:32768
	ds_read_b128 v[184:187], v207 offset:33792
	ds_read_b128 v[188:191], v207 offset:34816
	ds_read_b128 v[192:195], v207 offset:35840
	ds_read_b128 v[196:199], v207 offset:36864
	ds_read_b128 v[208:211], v207 offset:37888
	ds_read_b128 v[212:215], v207 offset:38912
	ds_read_b128 v[216:219], v207 offset:39936
	global_load_lds_dwordx4 v160, s[0:1]
	s_mov_b32 m0, s40
	s_nop 0
	global_load_lds_dwordx4 v164, s[0:1]
	s_mov_b32 m0, s35
	s_nop 0
	global_load_lds_dwordx4 v[222:223], off
	s_mov_b32 m0, s36
	s_nop 0
	global_load_lds_dwordx4 v[224:225], off
	s_waitcnt vmcnt(8)
	s_waitcnt lgkmcnt(0)
	s_barrier
	s_setprio 1
	v_mfma_f32_16x16x32_bf16 v[136:139], v[120:123], v[180:183], v[136:139]
	v_mfma_f32_16x16x32_bf16 v[128:131], v[132:135], v[180:183], v[128:131]
	v_mfma_f32_16x16x32_bf16 v[116:119], v[120:123], v[188:191], v[116:119]
	v_mfma_f32_16x16x32_bf16 v[112:115], v[132:135], v[188:191], v[112:115]
	v_mfma_f32_16x16x32_bf16 v[108:111], v[120:123], v[196:199], v[108:111]
	v_mfma_f32_16x16x32_bf16 v[104:107], v[132:135], v[196:199], v[104:107]
	v_mfma_f32_16x16x32_bf16 v[100:103], v[120:123], v[212:215], v[100:103]
	v_mfma_f32_16x16x32_bf16 v[96:99], v[132:135], v[212:215], v[96:99]
	v_mfma_f32_16x16x32_bf16 v[136:139], v[124:127], v[184:187], v[136:139]
	v_mfma_f32_16x16x32_bf16 v[128:131], v[140:143], v[184:187], v[128:131]
	v_mfma_f32_16x16x32_bf16 v[116:119], v[124:127], v[192:195], v[116:119]
	v_mfma_f32_16x16x32_bf16 v[112:115], v[140:143], v[192:195], v[112:115]
	v_mfma_f32_16x16x32_bf16 v[108:111], v[124:127], v[208:211], v[108:111]
	v_mfma_f32_16x16x32_bf16 v[104:107], v[140:143], v[208:211], v[104:107]
	v_mfma_f32_16x16x32_bf16 v[100:103], v[124:127], v[216:219], v[100:103]
	v_mfma_f32_16x16x32_bf16 v[96:99], v[140:143], v[216:219], v[96:99]
	v_mfma_f32_16x16x32_bf16 v[60:63], v[144:147], v[180:183], v[60:63]
	v_mfma_f32_16x16x32_bf16 v[56:59], v[152:155], v[180:183], v[56:59]
	v_mfma_f32_16x16x32_bf16 v[52:55], v[144:147], v[188:191], v[52:55]
	v_mfma_f32_16x16x32_bf16 v[48:51], v[152:155], v[188:191], v[48:51]
	v_mfma_f32_16x16x32_bf16 v[44:47], v[144:147], v[196:199], v[44:47]
	v_mfma_f32_16x16x32_bf16 v[40:43], v[152:155], v[196:199], v[40:43]
	v_mfma_f32_16x16x32_bf16 v[36:39], v[144:147], v[212:215], v[36:39]
	v_mfma_f32_16x16x32_bf16 v[32:35], v[152:155], v[212:215], v[32:35]
	v_mfma_f32_16x16x32_bf16 v[60:63], v[148:151], v[184:187], v[60:63]
	v_mfma_f32_16x16x32_bf16 v[56:59], v[156:159], v[184:187], v[56:59]
	v_mfma_f32_16x16x32_bf16 v[52:55], v[148:151], v[192:195], v[52:55]
	v_mfma_f32_16x16x32_bf16 v[48:51], v[156:159], v[192:195], v[48:51]
	v_mfma_f32_16x16x32_bf16 v[44:47], v[148:151], v[208:211], v[44:47]
	v_mfma_f32_16x16x32_bf16 v[40:43], v[156:159], v[208:211], v[40:43]
	v_mfma_f32_16x16x32_bf16 v[36:39], v[148:151], v[216:219], v[36:39]
	v_mfma_f32_16x16x32_bf16 v[32:35], v[156:159], v[216:219], v[32:35]
	s_barrier
	s_setprio 0
	s_add_i32 s0, s20, s34
	v_lshl_add_u64 v[200:201], v[200:201], 0, s[14:15]
	s_mov_b32 m0, s0
	ds_read_b128 v[180:183], v207 offset:49152
	ds_read_b128 v[184:187], v207 offset:50176
	ds_read_b128 v[188:191], v207 offset:51200
	ds_read_b128 v[192:195], v207 offset:52224
	ds_read_b128 v[196:199], v207 offset:53248
	ds_read_b128 v[208:211], v207 offset:54272
	ds_read_b128 v[212:215], v207 offset:55296
	ds_read_b128 v[216:219], v207 offset:56320
	global_load_lds_dwordx4 v[200:201], off
	s_add_i32 m0, s0, 0x2000
	s_add_u32 s0, s24, 0x28080
	v_lshl_add_u64 v[200:201], v[220:221], 0, s[14:15]
	s_addc_u32 s1, s25, 0
	s_add_i32 s20, s21, s34
	global_load_lds_dwordx4 v[200:201], off
	s_mov_b32 m0, s20
	s_nop 0
	global_load_lds_dwordx4 v162, s[0:1]
	s_add_i32 m0, s20, 0x2000
	s_nop 0
	global_load_lds_dwordx4 v166, s[0:1]
	v_lshl_add_u64 v[200:201], v[222:223], 0, s[14:15]
	s_mov_b32 m0, s42
	s_nop 0
	global_load_lds_dwordx4 v[200:201], off
	v_lshl_add_u64 v[200:201], v[224:225], 0, s[14:15]
	s_mov_b32 m0, s43
	s_nop 0
	global_load_lds_dwordx4 v[200:201], off
	s_waitcnt vmcnt(6)
	s_waitcnt lgkmcnt(0)
	s_barrier
	s_setprio 1
	v_mfma_f32_16x16x32_bf16 v[92:95], v[120:123], v[180:183], v[92:95]
	v_mfma_f32_16x16x32_bf16 v[88:91], v[132:135], v[180:183], v[88:91]
	v_mfma_f32_16x16x32_bf16 v[84:87], v[120:123], v[188:191], v[84:87]
	v_mfma_f32_16x16x32_bf16 v[80:83], v[132:135], v[188:191], v[80:83]
	v_mfma_f32_16x16x32_bf16 v[76:79], v[120:123], v[196:199], v[76:79]
	v_mfma_f32_16x16x32_bf16 v[72:75], v[132:135], v[196:199], v[72:75]
	v_mfma_f32_16x16x32_bf16 v[68:71], v[120:123], v[212:215], v[68:71]
	v_mfma_f32_16x16x32_bf16 v[64:67], v[132:135], v[212:215], v[64:67]
	v_mfma_f32_16x16x32_bf16 v[92:95], v[124:127], v[184:187], v[92:95]
	v_mfma_f32_16x16x32_bf16 v[88:91], v[140:143], v[184:187], v[88:91]
	v_mfma_f32_16x16x32_bf16 v[84:87], v[124:127], v[192:195], v[84:87]
	v_mfma_f32_16x16x32_bf16 v[80:83], v[140:143], v[192:195], v[80:83]
	v_mfma_f32_16x16x32_bf16 v[76:79], v[124:127], v[208:211], v[76:79]
	v_mfma_f32_16x16x32_bf16 v[72:75], v[140:143], v[208:211], v[72:75]
	v_mfma_f32_16x16x32_bf16 v[68:71], v[124:127], v[216:219], v[68:71]
	v_mfma_f32_16x16x32_bf16 v[64:67], v[140:143], v[216:219], v[64:67]
	v_mfma_f32_16x16x32_bf16 v[28:31], v[144:147], v[180:183], v[28:31]
	v_mfma_f32_16x16x32_bf16 v[24:27], v[152:155], v[180:183], v[24:27]
	v_mfma_f32_16x16x32_bf16 v[20:23], v[144:147], v[188:191], v[20:23]
	v_mfma_f32_16x16x32_bf16 v[16:19], v[152:155], v[188:191], v[16:19]
	v_mfma_f32_16x16x32_bf16 v[12:15], v[144:147], v[196:199], v[12:15]
	v_mfma_f32_16x16x32_bf16 v[8:11], v[152:155], v[196:199], v[8:11]
	v_mfma_f32_16x16x32_bf16 v[4:7], v[144:147], v[212:215], v[4:7]
	v_mfma_f32_16x16x32_bf16 v[0:3], v[152:155], v[212:215], v[0:3]
	v_mfma_f32_16x16x32_bf16 v[28:31], v[148:151], v[184:187], v[28:31]
	v_mfma_f32_16x16x32_bf16 v[24:27], v[156:159], v[184:187], v[24:27]
	v_mfma_f32_16x16x32_bf16 v[20:23], v[148:151], v[192:195], v[20:23]
	v_mfma_f32_16x16x32_bf16 v[16:19], v[156:159], v[192:195], v[16:19]
	v_mfma_f32_16x16x32_bf16 v[12:15], v[148:151], v[208:211], v[12:15]
	v_mfma_f32_16x16x32_bf16 v[8:11], v[156:159], v[208:211], v[8:11]
	v_mfma_f32_16x16x32_bf16 v[4:7], v[148:151], v[216:219], v[4:7]
	v_mfma_f32_16x16x32_bf16 v[0:3], v[156:159], v[216:219], v[0:3]
	s_barrier
	s_setprio 0
	s_add_i32 s54, s54, 2
	s_add_u32 s52, s52, 0x100
	s_addc_u32 s53, s53, 0
	s_cmp_gt_u32 s54, 7
	s_mov_b64 s[20:21], s[22:23]
.LBB0_402:
	ds_read_b128 v[120:123], v205
	ds_read_b128 v[124:127], v205 offset:1024
	ds_read_b128 v[132:135], v205 offset:2048
	ds_read_b128 v[140:143], v205 offset:3072
	ds_read_b128 v[144:147], v206
	ds_read_b128 v[148:151], v206 offset:1024
	ds_read_b128 v[152:155], v206 offset:2048
	ds_read_b128 v[156:159], v206 offset:3072
	s_add_u32 s22, s20, 0x100
	s_addc_u32 s23, s21, 0
	s_cmp_eq_u32 s54, 6
	s_cselect_b32 s27, s7, s23
	s_cselect_b32 s26, s6, s22
	s_cselect_b32 s25, s19, s53
	s_cselect_b32 s24, s18, s52
	s_add_i32 m0, s35, 0xc000
	ds_read_b128 v[180:183], v207
	ds_read_b128 v[184:187], v207 offset:1024
	ds_read_b128 v[188:191], v207 offset:2048
	ds_read_b128 v[192:195], v207 offset:3072
	ds_read_b128 v[196:199], v207 offset:4096
	ds_read_b128 v[208:211], v207 offset:5120
	ds_read_b128 v[212:215], v207 offset:6144
	ds_read_b128 v[216:219], v207 offset:7168
	global_load_lds_dwordx4 v172, s[20:21]
	s_add_i32 m0, s35, 0xe000
	s_nop 0
	global_load_lds_dwordx4 v174, s[20:21]
	s_waitcnt vmcnt(8)
	s_waitcnt lgkmcnt(0)
	s_barrier
	s_setprio 1
	v_mfma_f32_16x16x32_bf16 v[136:139], v[120:123], v[180:183], v[136:139]
	v_mfma_f32_16x16x32_bf16 v[128:131], v[132:135], v[180:183], v[128:131]
	v_mfma_f32_16x16x32_bf16 v[116:119], v[120:123], v[188:191], v[116:119]
	v_mfma_f32_16x16x32_bf16 v[112:115], v[132:135], v[188:191], v[112:115]
	v_mfma_f32_16x16x32_bf16 v[108:111], v[120:123], v[196:199], v[108:111]
	v_mfma_f32_16x16x32_bf16 v[104:107], v[132:135], v[196:199], v[104:107]
	v_mfma_f32_16x16x32_bf16 v[100:103], v[120:123], v[212:215], v[100:103]
	v_mfma_f32_16x16x32_bf16 v[96:99], v[132:135], v[212:215], v[96:99]
	v_mfma_f32_16x16x32_bf16 v[136:139], v[124:127], v[184:187], v[136:139]
	v_mfma_f32_16x16x32_bf16 v[128:131], v[140:143], v[184:187], v[128:131]
	v_mfma_f32_16x16x32_bf16 v[116:119], v[124:127], v[192:195], v[116:119]
	v_mfma_f32_16x16x32_bf16 v[112:115], v[140:143], v[192:195], v[112:115]
	v_mfma_f32_16x16x32_bf16 v[108:111], v[124:127], v[208:211], v[108:111]
	v_mfma_f32_16x16x32_bf16 v[104:107], v[140:143], v[208:211], v[104:107]
	v_mfma_f32_16x16x32_bf16 v[100:103], v[124:127], v[216:219], v[100:103]
	v_mfma_f32_16x16x32_bf16 v[96:99], v[140:143], v[216:219], v[96:99]
	v_mfma_f32_16x16x32_bf16 v[60:63], v[144:147], v[180:183], v[60:63]
	v_mfma_f32_16x16x32_bf16 v[56:59], v[152:155], v[180:183], v[56:59]
	v_mfma_f32_16x16x32_bf16 v[52:55], v[144:147], v[188:191], v[52:55]
	v_mfma_f32_16x16x32_bf16 v[48:51], v[152:155], v[188:191], v[48:51]
	v_mfma_f32_16x16x32_bf16 v[44:47], v[144:147], v[196:199], v[44:47]
	v_mfma_f32_16x16x32_bf16 v[40:43], v[152:155], v[196:199], v[40:43]
	v_mfma_f32_16x16x32_bf16 v[36:39], v[144:147], v[212:215], v[36:39]
	v_mfma_f32_16x16x32_bf16 v[32:35], v[152:155], v[212:215], v[32:35]
	v_mfma_f32_16x16x32_bf16 v[60:63], v[148:151], v[184:187], v[60:63]
	v_mfma_f32_16x16x32_bf16 v[56:59], v[156:159], v[184:187], v[56:59]
	v_mfma_f32_16x16x32_bf16 v[52:55], v[148:151], v[192:195], v[52:55]
	v_mfma_f32_16x16x32_bf16 v[48:51], v[156:159], v[192:195], v[48:51]
	v_mfma_f32_16x16x32_bf16 v[44:47], v[148:151], v[208:211], v[44:47]
	v_mfma_f32_16x16x32_bf16 v[40:43], v[156:159], v[208:211], v[40:43]
	v_mfma_f32_16x16x32_bf16 v[36:39], v[148:151], v[216:219], v[36:39]
	v_mfma_f32_16x16x32_bf16 v[32:35], v[156:159], v[216:219], v[32:35]
	s_barrier
	s_setprio 0
	s_add_i32 s0, s46, s34
	v_lshl_add_u64 v[200:201], s[24:25], 0, v[162:163]
	s_mov_b32 m0, s0
	ds_read_b128 v[180:183], v207 offset:16384
	ds_read_b128 v[184:187], v207 offset:17408
	ds_read_b128 v[188:191], v207 offset:18432
	ds_read_b128 v[192:195], v207 offset:19456
	ds_read_b128 v[196:199], v207 offset:20480
	ds_read_b128 v[208:211], v207 offset:21504
	ds_read_b128 v[212:215], v207 offset:22528
	ds_read_b128 v[216:219], v207 offset:23552
	global_load_lds_dwordx4 v[200:201], off
	s_add_i32 m0, s0, 0x2000
	s_add_u32 s0, s24, 0x28000
	v_lshl_add_u64 v[220:221], s[24:25], 0, v[166:167]
	s_addc_u32 s1, s25, 0
	s_add_i32 s20, s47, s34
	global_load_lds_dwordx4 v[220:221], off
	s_mov_b32 m0, s20
	v_lshl_add_u64 v[224:225], s[26:27], 0, v[164:165]
	global_load_lds_dwordx4 v162, s[0:1]
	s_add_i32 m0, s20, 0x2000
	s_nop 0
	global_load_lds_dwordx4 v166, s[0:1]
	v_lshl_add_u64 v[222:223], s[26:27], 0, v[160:161]
	s_waitcnt vmcnt(6)
	s_waitcnt lgkmcnt(0)
	s_barrier
	s_setprio 1
	v_mfma_f32_16x16x32_bf16 v[92:95], v[120:123], v[180:183], v[92:95]
	v_mfma_f32_16x16x32_bf16 v[88:91], v[132:135], v[180:183], v[88:91]
	v_mfma_f32_16x16x32_bf16 v[84:87], v[120:123], v[188:191], v[84:87]
	v_mfma_f32_16x16x32_bf16 v[80:83], v[132:135], v[188:191], v[80:83]
	v_mfma_f32_16x16x32_bf16 v[76:79], v[120:123], v[196:199], v[76:79]
	v_mfma_f32_16x16x32_bf16 v[72:75], v[132:135], v[196:199], v[72:75]
	v_mfma_f32_16x16x32_bf16 v[68:71], v[120:123], v[212:215], v[68:71]
	v_mfma_f32_16x16x32_bf16 v[64:67], v[132:135], v[212:215], v[64:67]
	v_mfma_f32_16x16x32_bf16 v[92:95], v[124:127], v[184:187], v[92:95]
	v_mfma_f32_16x16x32_bf16 v[88:91], v[140:143], v[184:187], v[88:91]
	v_mfma_f32_16x16x32_bf16 v[84:87], v[124:127], v[192:195], v[84:87]
	v_mfma_f32_16x16x32_bf16 v[80:83], v[140:143], v[192:195], v[80:83]
	v_mfma_f32_16x16x32_bf16 v[76:79], v[124:127], v[208:211], v[76:79]
	v_mfma_f32_16x16x32_bf16 v[72:75], v[140:143], v[208:211], v[72:75]
	v_mfma_f32_16x16x32_bf16 v[68:71], v[124:127], v[216:219], v[68:71]
	v_mfma_f32_16x16x32_bf16 v[64:67], v[140:143], v[216:219], v[64:67]
	v_mfma_f32_16x16x32_bf16 v[28:31], v[144:147], v[180:183], v[28:31]
	v_mfma_f32_16x16x32_bf16 v[24:27], v[152:155], v[180:183], v[24:27]
	v_mfma_f32_16x16x32_bf16 v[20:23], v[144:147], v[188:191], v[20:23]
	v_mfma_f32_16x16x32_bf16 v[16:19], v[152:155], v[188:191], v[16:19]
	v_mfma_f32_16x16x32_bf16 v[12:15], v[144:147], v[196:199], v[12:15]
	v_mfma_f32_16x16x32_bf16 v[8:11], v[152:155], v[196:199], v[8:11]
	v_mfma_f32_16x16x32_bf16 v[4:7], v[144:147], v[212:215], v[4:7]
	v_mfma_f32_16x16x32_bf16 v[0:3], v[152:155], v[212:215], v[0:3]
	v_mfma_f32_16x16x32_bf16 v[28:31], v[148:151], v[184:187], v[28:31]
	v_mfma_f32_16x16x32_bf16 v[24:27], v[156:159], v[184:187], v[24:27]
	v_mfma_f32_16x16x32_bf16 v[20:23], v[148:151], v[192:195], v[20:23]
	v_mfma_f32_16x16x32_bf16 v[16:19], v[156:159], v[192:195], v[16:19]
	v_mfma_f32_16x16x32_bf16 v[12:15], v[148:151], v[208:211], v[12:15]
	v_mfma_f32_16x16x32_bf16 v[8:11], v[156:159], v[208:211], v[8:11]
	v_mfma_f32_16x16x32_bf16 v[4:7], v[148:151], v[216:219], v[4:7]
	v_mfma_f32_16x16x32_bf16 v[0:3], v[156:159], v[216:219], v[0:3]
	s_barrier
	s_setprio 0
	s_add_i32 s20, 0, 0x18000
	s_add_i32 s21, 0, 0x1c000
	v_add_u32_e32 v140, s20, v203
	v_add_u32_e32 v156, s21, v203
	ds_read_b128 v[120:123], v140
	ds_read_b128 v[124:127], v140 offset:1024
	ds_read_b128 v[132:135], v140 offset:2048
	ds_read_b128 v[140:143], v140 offset:3072
	ds_read_b128 v[144:147], v156
	ds_read_b128 v[148:151], v156 offset:1024
	ds_read_b128 v[152:155], v156 offset:2048
	ds_read_b128 v[156:159], v156 offset:3072
	s_add_u32 s0, s26, 0x28000
	s_addc_u32 s1, s27, 0
	s_mov_b32 m0, s37
	ds_read_b128 v[180:183], v207 offset:32768
	ds_read_b128 v[184:187], v207 offset:33792
	ds_read_b128 v[188:191], v207 offset:34816
	ds_read_b128 v[192:195], v207 offset:35840
	ds_read_b128 v[196:199], v207 offset:36864
	ds_read_b128 v[208:211], v207 offset:37888
	ds_read_b128 v[212:215], v207 offset:38912
	ds_read_b128 v[216:219], v207 offset:39936
	global_load_lds_dwordx4 v160, s[0:1]
	s_mov_b32 m0, s40
	s_nop 0
	global_load_lds_dwordx4 v164, s[0:1]
	s_mov_b32 m0, s35
	s_nop 0
	global_load_lds_dwordx4 v[222:223], off
	s_mov_b32 m0, s36
	s_nop 0
	global_load_lds_dwordx4 v[224:225], off
	s_waitcnt vmcnt(8)
	s_waitcnt lgkmcnt(0)
	s_barrier
	s_setprio 1
	v_mfma_f32_16x16x32_bf16 v[136:139], v[120:123], v[180:183], v[136:139]
	v_mfma_f32_16x16x32_bf16 v[128:131], v[132:135], v[180:183], v[128:131]
	v_mfma_f32_16x16x32_bf16 v[116:119], v[120:123], v[188:191], v[116:119]
	v_mfma_f32_16x16x32_bf16 v[112:115], v[132:135], v[188:191], v[112:115]
	v_mfma_f32_16x16x32_bf16 v[108:111], v[120:123], v[196:199], v[108:111]
	v_mfma_f32_16x16x32_bf16 v[104:107], v[132:135], v[196:199], v[104:107]
	v_mfma_f32_16x16x32_bf16 v[100:103], v[120:123], v[212:215], v[100:103]
	v_mfma_f32_16x16x32_bf16 v[96:99], v[132:135], v[212:215], v[96:99]
	v_mfma_f32_16x16x32_bf16 v[136:139], v[124:127], v[184:187], v[136:139]
	v_mfma_f32_16x16x32_bf16 v[128:131], v[140:143], v[184:187], v[128:131]
	v_mfma_f32_16x16x32_bf16 v[116:119], v[124:127], v[192:195], v[116:119]
	v_mfma_f32_16x16x32_bf16 v[112:115], v[140:143], v[192:195], v[112:115]
	v_mfma_f32_16x16x32_bf16 v[108:111], v[124:127], v[208:211], v[108:111]
	v_mfma_f32_16x16x32_bf16 v[104:107], v[140:143], v[208:211], v[104:107]
	v_mfma_f32_16x16x32_bf16 v[100:103], v[124:127], v[216:219], v[100:103]
	v_mfma_f32_16x16x32_bf16 v[96:99], v[140:143], v[216:219], v[96:99]
	v_mfma_f32_16x16x32_bf16 v[60:63], v[144:147], v[180:183], v[60:63]
	v_mfma_f32_16x16x32_bf16 v[56:59], v[152:155], v[180:183], v[56:59]
	v_mfma_f32_16x16x32_bf16 v[52:55], v[144:147], v[188:191], v[52:55]
	v_mfma_f32_16x16x32_bf16 v[48:51], v[152:155], v[188:191], v[48:51]
	v_mfma_f32_16x16x32_bf16 v[44:47], v[144:147], v[196:199], v[44:47]
	v_mfma_f32_16x16x32_bf16 v[40:43], v[152:155], v[196:199], v[40:43]
	v_mfma_f32_16x16x32_bf16 v[36:39], v[144:147], v[212:215], v[36:39]
	v_mfma_f32_16x16x32_bf16 v[32:35], v[152:155], v[212:215], v[32:35]
	v_mfma_f32_16x16x32_bf16 v[60:63], v[148:151], v[184:187], v[60:63]
	v_mfma_f32_16x16x32_bf16 v[56:59], v[156:159], v[184:187], v[56:59]
	v_mfma_f32_16x16x32_bf16 v[52:55], v[148:151], v[192:195], v[52:55]
	v_mfma_f32_16x16x32_bf16 v[48:51], v[156:159], v[192:195], v[48:51]
	v_mfma_f32_16x16x32_bf16 v[44:47], v[148:151], v[208:211], v[44:47]
	v_mfma_f32_16x16x32_bf16 v[40:43], v[156:159], v[208:211], v[40:43]
	v_mfma_f32_16x16x32_bf16 v[36:39], v[148:151], v[216:219], v[36:39]
	v_mfma_f32_16x16x32_bf16 v[32:35], v[156:159], v[216:219], v[32:35]
	s_barrier
	s_setprio 0
	s_add_i32 s0, s20, s34
	v_lshl_add_u64 v[200:201], v[200:201], 0, s[14:15]
	s_mov_b32 m0, s0
	ds_read_b128 v[180:183], v207 offset:49152
	ds_read_b128 v[184:187], v207 offset:50176
	ds_read_b128 v[188:191], v207 offset:51200
	ds_read_b128 v[192:195], v207 offset:52224
	ds_read_b128 v[196:199], v207 offset:53248
	ds_read_b128 v[208:211], v207 offset:54272
	ds_read_b128 v[212:215], v207 offset:55296
	ds_read_b128 v[216:219], v207 offset:56320
	global_load_lds_dwordx4 v[200:201], off
	s_add_i32 m0, s0, 0x2000
	s_add_u32 s0, s24, 0x28080
	v_lshl_add_u64 v[200:201], v[220:221], 0, s[14:15]
	s_addc_u32 s1, s25, 0
	s_add_i32 s20, s21, s34
	global_load_lds_dwordx4 v[200:201], off
	s_mov_b32 m0, s20
	s_nop 0
	global_load_lds_dwordx4 v162, s[0:1]
	s_add_i32 m0, s20, 0x2000
	s_nop 0
	global_load_lds_dwordx4 v166, s[0:1]
	v_lshl_add_u64 v[200:201], v[222:223], 0, s[14:15]
	s_mov_b32 m0, s42
	s_nop 0
	global_load_lds_dwordx4 v[200:201], off
	v_lshl_add_u64 v[200:201], v[224:225], 0, s[14:15]
	s_mov_b32 m0, s43
	s_nop 0
	global_load_lds_dwordx4 v[200:201], off
	s_waitcnt vmcnt(6)
	s_waitcnt lgkmcnt(0)
	s_barrier
	s_setprio 1
	v_mfma_f32_16x16x32_bf16 v[92:95], v[120:123], v[180:183], v[92:95]
	v_mfma_f32_16x16x32_bf16 v[88:91], v[132:135], v[180:183], v[88:91]
	v_mfma_f32_16x16x32_bf16 v[84:87], v[120:123], v[188:191], v[84:87]
	v_mfma_f32_16x16x32_bf16 v[80:83], v[132:135], v[188:191], v[80:83]
	v_mfma_f32_16x16x32_bf16 v[76:79], v[120:123], v[196:199], v[76:79]
	v_mfma_f32_16x16x32_bf16 v[72:75], v[132:135], v[196:199], v[72:75]
	v_mfma_f32_16x16x32_bf16 v[68:71], v[120:123], v[212:215], v[68:71]
	v_mfma_f32_16x16x32_bf16 v[64:67], v[132:135], v[212:215], v[64:67]
	v_mfma_f32_16x16x32_bf16 v[92:95], v[124:127], v[184:187], v[92:95]
	v_mfma_f32_16x16x32_bf16 v[88:91], v[140:143], v[184:187], v[88:91]
	v_mfma_f32_16x16x32_bf16 v[84:87], v[124:127], v[192:195], v[84:87]
	v_mfma_f32_16x16x32_bf16 v[80:83], v[140:143], v[192:195], v[80:83]
	v_mfma_f32_16x16x32_bf16 v[76:79], v[124:127], v[208:211], v[76:79]
	v_mfma_f32_16x16x32_bf16 v[72:75], v[140:143], v[208:211], v[72:75]
	v_mfma_f32_16x16x32_bf16 v[68:71], v[124:127], v[216:219], v[68:71]
	v_mfma_f32_16x16x32_bf16 v[64:67], v[140:143], v[216:219], v[64:67]
	v_mfma_f32_16x16x32_bf16 v[28:31], v[144:147], v[180:183], v[28:31]
	v_mfma_f32_16x16x32_bf16 v[24:27], v[152:155], v[180:183], v[24:27]
	v_mfma_f32_16x16x32_bf16 v[20:23], v[144:147], v[188:191], v[20:23]
	v_mfma_f32_16x16x32_bf16 v[16:19], v[152:155], v[188:191], v[16:19]
	v_mfma_f32_16x16x32_bf16 v[12:15], v[144:147], v[196:199], v[12:15]
	v_mfma_f32_16x16x32_bf16 v[8:11], v[152:155], v[196:199], v[8:11]
	v_mfma_f32_16x16x32_bf16 v[4:7], v[144:147], v[212:215], v[4:7]
	v_mfma_f32_16x16x32_bf16 v[0:3], v[152:155], v[212:215], v[0:3]
	v_mfma_f32_16x16x32_bf16 v[28:31], v[148:151], v[184:187], v[28:31]
	v_mfma_f32_16x16x32_bf16 v[24:27], v[156:159], v[184:187], v[24:27]
	v_mfma_f32_16x16x32_bf16 v[20:23], v[148:151], v[192:195], v[20:23]
	v_mfma_f32_16x16x32_bf16 v[16:19], v[156:159], v[192:195], v[16:19]
	v_mfma_f32_16x16x32_bf16 v[12:15], v[148:151], v[208:211], v[12:15]
	v_mfma_f32_16x16x32_bf16 v[8:11], v[156:159], v[208:211], v[8:11]
	v_mfma_f32_16x16x32_bf16 v[4:7], v[148:151], v[216:219], v[4:7]
	v_mfma_f32_16x16x32_bf16 v[0:3], v[156:159], v[216:219], v[0:3]
	s_barrier
	s_setprio 0
	s_add_i32 s54, s54, 2
	s_add_u32 s52, s52, 0x100
	s_addc_u32 s53, s53, 0
	s_cmp_gt_u32 s54, 7
	s_mov_b64 s[20:21], s[22:23]
	s_cbranch_scc0 .LBB0_402
	s_and_b64 vcc, exec, s[16:17]
	s_cbranch_vccz .LBB0_405
	s_barrier

.Lrestag_480:
	ds_read_b128 v[100:103], v210
	ds_read_b128 v[116:119], v210 offset:1024
	ds_read_b128 v[136:139], v210 offset:2048
	ds_read_b128 v[140:143], v210 offset:3072
	ds_read_b128 v[144:147], v211
	ds_read_b128 v[148:151], v211 offset:1024
	ds_read_b128 v[152:155], v211 offset:2048
	ds_read_b128 v[178:181], v211 offset:3072
	s_add_u32 s36, s34, 0x1000000
	s_addc_u32 s37, s35, 0
	s_cmp_eq_u32 s65, 12
	s_cselect_b32 s44, s29, s36
	s_cselect_b32 s45, s23, s37
	s_cselect_b32 s42, s31, s63
	s_cselect_b32 s43, s21, s64
	s_add_u32 s40, s44, 0x800000
	s_addc_u32 s41, s45, 0
	s_add_i32 m0, s52, 0xc000
	ds_read_b128 v[182:185], v212
	ds_read_b128 v[186:189], v212 offset:1024
	ds_read_b128 v[190:193], v212 offset:2048
	ds_read_b128 v[194:197], v212 offset:3072
	ds_read_b128 v[198:201], v212 offset:4096
	ds_read_b128 v[202:205], v212 offset:5120
	ds_read_b128 v[214:217], v212 offset:6144
	ds_read_b128 v[218:221], v212 offset:7168
	global_load_lds_dwordx4 v170, s[34:35]
	s_add_i32 m0, s52, 0xe000
	s_nop 0
	global_load_lds_dwordx4 v172, s[34:35]
	s_nop 0
	s_waitcnt lgkmcnt(0)
	s_barrier
	s_setprio 1
	v_mfma_f32_16x16x32_bf16 v[132:135], v[100:103], v[182:185], 0
	v_mfma_f32_16x16x32_bf16 v[124:127], v[136:139], v[182:185], 0
	v_mfma_f32_16x16x32_bf16 v[112:115], v[100:103], v[190:193], 0
	v_mfma_f32_16x16x32_bf16 v[104:107], v[136:139], v[190:193], 0
	v_mfma_f32_16x16x32_bf16 v[92:95], v[100:103], v[198:201], 0
	v_mfma_f32_16x16x32_bf16 v[84:87], v[136:139], v[198:201], 0
	v_mfma_f32_16x16x32_bf16 v[76:79], v[100:103], v[214:217], 0
	v_mfma_f32_16x16x32_bf16 v[68:71], v[136:139], v[214:217], 0
	v_mfma_f32_16x16x32_bf16 v[132:135], v[116:119], v[186:189], v[132:135]
	v_mfma_f32_16x16x32_bf16 v[124:127], v[140:143], v[186:189], v[124:127]
	v_mfma_f32_16x16x32_bf16 v[112:115], v[116:119], v[194:197], v[112:115]
	v_mfma_f32_16x16x32_bf16 v[104:107], v[140:143], v[194:197], v[104:107]
	v_mfma_f32_16x16x32_bf16 v[92:95], v[116:119], v[202:205], v[92:95]
	v_mfma_f32_16x16x32_bf16 v[84:87], v[140:143], v[202:205], v[84:87]
	v_mfma_f32_16x16x32_bf16 v[76:79], v[116:119], v[218:221], v[76:79]
	v_mfma_f32_16x16x32_bf16 v[68:71], v[140:143], v[218:221], v[68:71]
	v_mfma_f32_16x16x32_bf16 v[128:131], v[144:147], v[182:185], 0
	v_mfma_f32_16x16x32_bf16 v[120:123], v[152:155], v[182:185], 0
	v_mfma_f32_16x16x32_bf16 v[108:111], v[144:147], v[190:193], 0
	v_mfma_f32_16x16x32_bf16 v[96:99], v[152:155], v[190:193], 0
	v_mfma_f32_16x16x32_bf16 v[88:91], v[144:147], v[198:201], 0
	v_mfma_f32_16x16x32_bf16 v[80:83], v[152:155], v[198:201], 0
	v_mfma_f32_16x16x32_bf16 v[72:75], v[144:147], v[214:217], 0
	v_mfma_f32_16x16x32_bf16 v[64:67], v[152:155], v[214:217], 0
	v_mfma_f32_16x16x32_bf16 v[128:131], v[148:151], v[186:189], v[128:131]
	v_mfma_f32_16x16x32_bf16 v[120:123], v[178:181], v[186:189], v[120:123]
	v_mfma_f32_16x16x32_bf16 v[108:111], v[148:151], v[194:197], v[108:111]
	v_mfma_f32_16x16x32_bf16 v[96:99], v[178:181], v[194:197], v[96:99]
	v_mfma_f32_16x16x32_bf16 v[88:91], v[148:151], v[202:205], v[88:91]
	v_mfma_f32_16x16x32_bf16 v[80:83], v[178:181], v[202:205], v[80:83]
	v_mfma_f32_16x16x32_bf16 v[72:75], v[148:151], v[218:221], v[72:75]
	v_mfma_f32_16x16x32_bf16 v[64:67], v[178:181], v[218:221], v[64:67]
	s_barrier
	s_setprio 0
	s_add_i32 s0, s60, s51
	v_lshl_add_u64 v[206:207], s[42:43], 0, v[158:159]
	s_mov_b32 m0, s0
	ds_read_b128 v[182:185], v212 offset:16384
	ds_read_b128 v[186:189], v212 offset:17408
	ds_read_b128 v[190:193], v212 offset:18432
	ds_read_b128 v[194:197], v212 offset:19456
	ds_read_b128 v[198:201], v212 offset:20480
	ds_read_b128 v[202:205], v212 offset:21504
	ds_read_b128 v[214:217], v212 offset:22528
	ds_read_b128 v[218:221], v212 offset:23552
	global_load_lds_dwordx4 v[206:207], off
	s_add_i32 m0, s0, 0x2000
	s_add_u32 s0, s42, 0x40000
	v_lshl_add_u64 v[222:223], s[42:43], 0, v[162:163]
	s_addc_u32 s1, s43, 0
	s_add_i32 s34, s61, s51
	global_load_lds_dwordx4 v[222:223], off
	s_mov_b32 m0, s34
	s_nop 0
	global_load_lds_dwordx4 v158, s[0:1]
	s_add_i32 m0, s34, 0x2000
	s_nop 0
	global_load_lds_dwordx4 v162, s[0:1]
	s_nop 0
	s_waitcnt lgkmcnt(0)
	s_barrier
	s_setprio 1
	v_mfma_f32_16x16x32_bf16 v[60:63], v[100:103], v[182:185], 0
	v_mfma_f32_16x16x32_bf16 v[52:55], v[136:139], v[182:185], 0
	v_mfma_f32_16x16x32_bf16 v[44:47], v[100:103], v[190:193], 0
	v_mfma_f32_16x16x32_bf16 v[36:39], v[136:139], v[190:193], 0
	v_mfma_f32_16x16x32_bf16 v[28:31], v[100:103], v[198:201], 0
	v_mfma_f32_16x16x32_bf16 v[20:23], v[136:139], v[198:201], 0
	v_mfma_f32_16x16x32_bf16 v[12:15], v[100:103], v[214:217], 0
	v_mfma_f32_16x16x32_bf16 v[4:7], v[136:139], v[214:217], 0
	v_mfma_f32_16x16x32_bf16 v[60:63], v[116:119], v[186:189], v[60:63]
	v_mfma_f32_16x16x32_bf16 v[52:55], v[140:143], v[186:189], v[52:55]
	v_mfma_f32_16x16x32_bf16 v[44:47], v[116:119], v[194:197], v[44:47]
	v_mfma_f32_16x16x32_bf16 v[36:39], v[140:143], v[194:197], v[36:39]
	v_mfma_f32_16x16x32_bf16 v[28:31], v[116:119], v[202:205], v[28:31]
	v_mfma_f32_16x16x32_bf16 v[20:23], v[140:143], v[202:205], v[20:23]
	v_mfma_f32_16x16x32_bf16 v[12:15], v[116:119], v[218:221], v[12:15]
	v_mfma_f32_16x16x32_bf16 v[4:7], v[140:143], v[218:221], v[4:7]
	v_mfma_f32_16x16x32_bf16 v[56:59], v[144:147], v[182:185], 0
	v_mfma_f32_16x16x32_bf16 v[48:51], v[152:155], v[182:185], 0
	v_mfma_f32_16x16x32_bf16 v[40:43], v[144:147], v[190:193], 0
	v_mfma_f32_16x16x32_bf16 v[32:35], v[152:155], v[190:193], 0
	v_mfma_f32_16x16x32_bf16 v[24:27], v[144:147], v[198:201], 0
	v_mfma_f32_16x16x32_bf16 v[16:19], v[152:155], v[198:201], 0
	v_mfma_f32_16x16x32_bf16 v[8:11], v[144:147], v[214:217], 0
	v_mfma_f32_16x16x32_bf16 v[0:3], v[152:155], v[214:217], 0
	v_mfma_f32_16x16x32_bf16 v[56:59], v[148:151], v[186:189], v[56:59]
	v_mfma_f32_16x16x32_bf16 v[48:51], v[178:181], v[186:189], v[48:51]
	v_mfma_f32_16x16x32_bf16 v[40:43], v[148:151], v[194:197], v[40:43]
	v_mfma_f32_16x16x32_bf16 v[32:35], v[178:181], v[194:197], v[32:35]
	v_mfma_f32_16x16x32_bf16 v[24:27], v[148:151], v[202:205], v[24:27]
	v_mfma_f32_16x16x32_bf16 v[16:19], v[178:181], v[202:205], v[16:19]
	v_mfma_f32_16x16x32_bf16 v[8:11], v[148:151], v[218:221], v[8:11]
	v_mfma_f32_16x16x32_bf16 v[0:3], v[178:181], v[218:221], v[0:3]
	s_barrier
	s_setprio 0
	s_add_i32 s34, 0, 0x18000
	s_add_i32 s35, 0, 0x1c000
	v_add_u32_e32 v140, s34, v209
	v_add_u32_e32 v178, s35, v209
	ds_read_b128 v[100:103], v140
	ds_read_b128 v[116:119], v140 offset:1024
	ds_read_b128 v[136:139], v140 offset:2048
	ds_read_b128 v[140:143], v140 offset:3072
	ds_read_b128 v[144:147], v178
	ds_read_b128 v[148:151], v178 offset:1024
	ds_read_b128 v[152:155], v178 offset:2048
	ds_read_b128 v[178:181], v178 offset:3072
	s_add_u32 s0, s44, 0x1000
	s_addc_u32 s1, s45, 0
	s_mov_b32 m0, s54
	ds_read_b128 v[182:185], v212 offset:32768
	ds_read_b128 v[186:189], v212 offset:33792
	ds_read_b128 v[190:193], v212 offset:34816
	ds_read_b128 v[194:197], v212 offset:35840
	ds_read_b128 v[198:201], v212 offset:36864
	ds_read_b128 v[202:205], v212 offset:37888
	ds_read_b128 v[214:217], v212 offset:38912
	ds_read_b128 v[218:221], v212 offset:39936
	global_load_lds_dwordx4 v156, s[0:1]
	s_mov_b32 m0, s55
	s_nop 0
	global_load_lds_dwordx4 v160, s[0:1]
	s_mov_b32 m0, s52
	s_nop 0
	global_load_lds_dwordx4 v156, s[44:45]
	s_mov_b32 m0, s53
	s_nop 0
	global_load_lds_dwordx4 v160, s[44:45]
	s_waitcnt vmcnt(8)
	s_waitcnt lgkmcnt(0)
	s_barrier
	s_setprio 1
	v_mfma_f32_16x16x32_bf16 v[132:135], v[100:103], v[182:185], v[132:135]
	v_mfma_f32_16x16x32_bf16 v[124:127], v[136:139], v[182:185], v[124:127]
	v_mfma_f32_16x16x32_bf16 v[112:115], v[100:103], v[190:193], v[112:115]
	v_mfma_f32_16x16x32_bf16 v[104:107], v[136:139], v[190:193], v[104:107]
	v_mfma_f32_16x16x32_bf16 v[92:95], v[100:103], v[198:201], v[92:95]
	v_mfma_f32_16x16x32_bf16 v[84:87], v[136:139], v[198:201], v[84:87]
	v_mfma_f32_16x16x32_bf16 v[76:79], v[100:103], v[214:217], v[76:79]
	v_mfma_f32_16x16x32_bf16 v[68:71], v[136:139], v[214:217], v[68:71]
	v_mfma_f32_16x16x32_bf16 v[132:135], v[116:119], v[186:189], v[132:135]
	v_mfma_f32_16x16x32_bf16 v[124:127], v[140:143], v[186:189], v[124:127]
	v_mfma_f32_16x16x32_bf16 v[112:115], v[116:119], v[194:197], v[112:115]
	v_mfma_f32_16x16x32_bf16 v[104:107], v[140:143], v[194:197], v[104:107]
	v_mfma_f32_16x16x32_bf16 v[92:95], v[116:119], v[202:205], v[92:95]
	v_mfma_f32_16x16x32_bf16 v[84:87], v[140:143], v[202:205], v[84:87]
	v_mfma_f32_16x16x32_bf16 v[76:79], v[116:119], v[218:221], v[76:79]
	v_mfma_f32_16x16x32_bf16 v[68:71], v[140:143], v[218:221], v[68:71]
	v_mfma_f32_16x16x32_bf16 v[128:131], v[144:147], v[182:185], v[128:131]
	v_mfma_f32_16x16x32_bf16 v[120:123], v[152:155], v[182:185], v[120:123]
	v_mfma_f32_16x16x32_bf16 v[108:111], v[144:147], v[190:193], v[108:111]
	v_mfma_f32_16x16x32_bf16 v[96:99], v[152:155], v[190:193], v[96:99]
	v_mfma_f32_16x16x32_bf16 v[88:91], v[144:147], v[198:201], v[88:91]
	v_mfma_f32_16x16x32_bf16 v[80:83], v[152:155], v[198:201], v[80:83]
	v_mfma_f32_16x16x32_bf16 v[72:75], v[144:147], v[214:217], v[72:75]
	v_mfma_f32_16x16x32_bf16 v[64:67], v[152:155], v[214:217], v[64:67]
	v_mfma_f32_16x16x32_bf16 v[128:131], v[148:151], v[186:189], v[128:131]
	v_mfma_f32_16x16x32_bf16 v[120:123], v[178:181], v[186:189], v[120:123]
	v_mfma_f32_16x16x32_bf16 v[108:111], v[148:151], v[194:197], v[108:111]
	v_mfma_f32_16x16x32_bf16 v[96:99], v[178:181], v[194:197], v[96:99]
	v_mfma_f32_16x16x32_bf16 v[88:91], v[148:151], v[202:205], v[88:91]
	v_mfma_f32_16x16x32_bf16 v[80:83], v[178:181], v[202:205], v[80:83]
	v_mfma_f32_16x16x32_bf16 v[72:75], v[148:151], v[218:221], v[72:75]
	v_mfma_f32_16x16x32_bf16 v[64:67], v[178:181], v[218:221], v[64:67]
	s_barrier
	s_setprio 0
	s_add_i32 s0, s34, s51
	v_lshl_add_u64 v[206:207], v[206:207], 0, s[16:17]
	s_mov_b32 m0, s0
	ds_read_b128 v[182:185], v212 offset:49152
	ds_read_b128 v[186:189], v212 offset:50176
	ds_read_b128 v[190:193], v212 offset:51200
	ds_read_b128 v[194:197], v212 offset:52224
	ds_read_b128 v[198:201], v212 offset:53248
	ds_read_b128 v[202:205], v212 offset:54272
	ds_read_b128 v[214:217], v212 offset:55296
	ds_read_b128 v[218:221], v212 offset:56320
	global_load_lds_dwordx4 v[206:207], off
	s_add_i32 m0, s0, 0x2000
	s_add_u32 s0, s42, 0x40080
	v_lshl_add_u64 v[206:207], v[222:223], 0, s[16:17]
	s_addc_u32 s1, s43, 0
	s_add_i32 s34, s35, s51
	global_load_lds_dwordx4 v[206:207], off
	s_mov_b32 m0, s34
	s_nop 0
	global_load_lds_dwordx4 v158, s[0:1]
	s_add_i32 m0, s34, 0x2000
	s_nop 0
	global_load_lds_dwordx4 v162, s[0:1]
	s_mov_b32 m0, s56
	s_nop 0
	global_load_lds_dwordx4 v156, s[40:41]
	s_mov_b32 m0, s57
	s_nop 0
	global_load_lds_dwordx4 v160, s[40:41]
	s_waitcnt vmcnt(6)
	s_waitcnt lgkmcnt(0)
	s_barrier
	s_setprio 1
	v_mfma_f32_16x16x32_bf16 v[60:63], v[100:103], v[182:185], v[60:63]
	v_mfma_f32_16x16x32_bf16 v[52:55], v[136:139], v[182:185], v[52:55]
	v_mfma_f32_16x16x32_bf16 v[44:47], v[100:103], v[190:193], v[44:47]
	v_mfma_f32_16x16x32_bf16 v[36:39], v[136:139], v[190:193], v[36:39]
	v_mfma_f32_16x16x32_bf16 v[28:31], v[100:103], v[198:201], v[28:31]
	v_mfma_f32_16x16x32_bf16 v[20:23], v[136:139], v[198:201], v[20:23]
	v_mfma_f32_16x16x32_bf16 v[12:15], v[100:103], v[214:217], v[12:15]
	v_mfma_f32_16x16x32_bf16 v[4:7], v[136:139], v[214:217], v[4:7]
	v_mfma_f32_16x16x32_bf16 v[60:63], v[116:119], v[186:189], v[60:63]
	v_mfma_f32_16x16x32_bf16 v[52:55], v[140:143], v[186:189], v[52:55]
	v_mfma_f32_16x16x32_bf16 v[44:47], v[116:119], v[194:197], v[44:47]
	v_mfma_f32_16x16x32_bf16 v[36:39], v[140:143], v[194:197], v[36:39]
	v_mfma_f32_16x16x32_bf16 v[28:31], v[116:119], v[202:205], v[28:31]
	v_mfma_f32_16x16x32_bf16 v[20:23], v[140:143], v[202:205], v[20:23]
	v_mfma_f32_16x16x32_bf16 v[12:15], v[116:119], v[218:221], v[12:15]
	v_mfma_f32_16x16x32_bf16 v[4:7], v[140:143], v[218:221], v[4:7]
	v_mfma_f32_16x16x32_bf16 v[56:59], v[144:147], v[182:185], v[56:59]
	v_mfma_f32_16x16x32_bf16 v[48:51], v[152:155], v[182:185], v[48:51]
	v_mfma_f32_16x16x32_bf16 v[40:43], v[144:147], v[190:193], v[40:43]
	v_mfma_f32_16x16x32_bf16 v[32:35], v[152:155], v[190:193], v[32:35]
	v_mfma_f32_16x16x32_bf16 v[24:27], v[144:147], v[198:201], v[24:27]
	v_mfma_f32_16x16x32_bf16 v[16:19], v[152:155], v[198:201], v[16:19]
	v_mfma_f32_16x16x32_bf16 v[8:11], v[144:147], v[214:217], v[8:11]
	v_mfma_f32_16x16x32_bf16 v[0:3], v[152:155], v[214:217], v[0:3]
	v_mfma_f32_16x16x32_bf16 v[56:59], v[148:151], v[186:189], v[56:59]
	v_mfma_f32_16x16x32_bf16 v[48:51], v[178:181], v[186:189], v[48:51]
	v_mfma_f32_16x16x32_bf16 v[40:43], v[148:151], v[194:197], v[40:43]
	v_mfma_f32_16x16x32_bf16 v[32:35], v[178:181], v[194:197], v[32:35]
	v_mfma_f32_16x16x32_bf16 v[24:27], v[148:151], v[202:205], v[24:27]
	v_mfma_f32_16x16x32_bf16 v[16:19], v[178:181], v[202:205], v[16:19]
	v_mfma_f32_16x16x32_bf16 v[8:11], v[148:151], v[218:221], v[8:11]
	v_mfma_f32_16x16x32_bf16 v[0:3], v[178:181], v[218:221], v[0:3]
	s_barrier
	s_setprio 0
	s_add_i32 s65, s65, 2
	s_add_u32 s63, s63, 0x100
	s_addc_u32 s64, s64, 0
	s_cmp_gt_u32 s65, 13
	s_mov_b64 s[34:35], s[36:37]
.LBB0_480:
	ds_read_b128 v[100:103], v210
	ds_read_b128 v[116:119], v210 offset:1024
	ds_read_b128 v[136:139], v210 offset:2048
	ds_read_b128 v[140:143], v210 offset:3072
	ds_read_b128 v[144:147], v211
	ds_read_b128 v[148:151], v211 offset:1024
	ds_read_b128 v[152:155], v211 offset:2048
	ds_read_b128 v[178:181], v211 offset:3072
	s_add_u32 s36, s34, 0x1000000
	s_addc_u32 s37, s35, 0
	s_cmp_eq_u32 s65, 12
	s_cselect_b32 s44, s29, s36
	s_cselect_b32 s45, s23, s37
	s_cselect_b32 s42, s31, s63
	s_cselect_b32 s43, s21, s64
	s_add_u32 s40, s44, 0x800000
	s_addc_u32 s41, s45, 0
	s_add_i32 m0, s52, 0xc000
	ds_read_b128 v[182:185], v212
	ds_read_b128 v[186:189], v212 offset:1024
	ds_read_b128 v[190:193], v212 offset:2048
	ds_read_b128 v[194:197], v212 offset:3072
	ds_read_b128 v[198:201], v212 offset:4096
	ds_read_b128 v[202:205], v212 offset:5120
	ds_read_b128 v[214:217], v212 offset:6144
	ds_read_b128 v[218:221], v212 offset:7168
	global_load_lds_dwordx4 v170, s[34:35]
	s_add_i32 m0, s52, 0xe000
	s_nop 0
	global_load_lds_dwordx4 v172, s[34:35]
	s_waitcnt vmcnt(8)
	s_waitcnt lgkmcnt(0)
	s_barrier
	s_setprio 1
	v_mfma_f32_16x16x32_bf16 v[132:135], v[100:103], v[182:185], v[132:135]
	v_mfma_f32_16x16x32_bf16 v[124:127], v[136:139], v[182:185], v[124:127]
	v_mfma_f32_16x16x32_bf16 v[112:115], v[100:103], v[190:193], v[112:115]
	v_mfma_f32_16x16x32_bf16 v[104:107], v[136:139], v[190:193], v[104:107]
	v_mfma_f32_16x16x32_bf16 v[92:95], v[100:103], v[198:201], v[92:95]
	v_mfma_f32_16x16x32_bf16 v[84:87], v[136:139], v[198:201], v[84:87]
	v_mfma_f32_16x16x32_bf16 v[76:79], v[100:103], v[214:217], v[76:79]
	v_mfma_f32_16x16x32_bf16 v[68:71], v[136:139], v[214:217], v[68:71]
	v_mfma_f32_16x16x32_bf16 v[132:135], v[116:119], v[186:189], v[132:135]
	v_mfma_f32_16x16x32_bf16 v[124:127], v[140:143], v[186:189], v[124:127]
	v_mfma_f32_16x16x32_bf16 v[112:115], v[116:119], v[194:197], v[112:115]
	v_mfma_f32_16x16x32_bf16 v[104:107], v[140:143], v[194:197], v[104:107]
	v_mfma_f32_16x16x32_bf16 v[92:95], v[116:119], v[202:205], v[92:95]
	v_mfma_f32_16x16x32_bf16 v[84:87], v[140:143], v[202:205], v[84:87]
	v_mfma_f32_16x16x32_bf16 v[76:79], v[116:119], v[218:221], v[76:79]
	v_mfma_f32_16x16x32_bf16 v[68:71], v[140:143], v[218:221], v[68:71]
	v_mfma_f32_16x16x32_bf16 v[128:131], v[144:147], v[182:185], v[128:131]
	v_mfma_f32_16x16x32_bf16 v[120:123], v[152:155], v[182:185], v[120:123]
	v_mfma_f32_16x16x32_bf16 v[108:111], v[144:147], v[190:193], v[108:111]
	v_mfma_f32_16x16x32_bf16 v[96:99], v[152:155], v[190:193], v[96:99]
	v_mfma_f32_16x16x32_bf16 v[88:91], v[144:147], v[198:201], v[88:91]
	v_mfma_f32_16x16x32_bf16 v[80:83], v[152:155], v[198:201], v[80:83]
	v_mfma_f32_16x16x32_bf16 v[72:75], v[144:147], v[214:217], v[72:75]
	v_mfma_f32_16x16x32_bf16 v[64:67], v[152:155], v[214:217], v[64:67]
	v_mfma_f32_16x16x32_bf16 v[128:131], v[148:151], v[186:189], v[128:131]
	v_mfma_f32_16x16x32_bf16 v[120:123], v[178:181], v[186:189], v[120:123]
	v_mfma_f32_16x16x32_bf16 v[108:111], v[148:151], v[194:197], v[108:111]
	v_mfma_f32_16x16x32_bf16 v[96:99], v[178:181], v[194:197], v[96:99]
	v_mfma_f32_16x16x32_bf16 v[88:91], v[148:151], v[202:205], v[88:91]
	v_mfma_f32_16x16x32_bf16 v[80:83], v[178:181], v[202:205], v[80:83]
	v_mfma_f32_16x16x32_bf16 v[72:75], v[148:151], v[218:221], v[72:75]
	v_mfma_f32_16x16x32_bf16 v[64:67], v[178:181], v[218:221], v[64:67]
	s_barrier
	s_setprio 0
	s_add_i32 s0, s60, s51
	v_lshl_add_u64 v[206:207], s[42:43], 0, v[158:159]
	s_mov_b32 m0, s0
	ds_read_b128 v[182:185], v212 offset:16384
	ds_read_b128 v[186:189], v212 offset:17408
	ds_read_b128 v[190:193], v212 offset:18432
	ds_read_b128 v[194:197], v212 offset:19456
	ds_read_b128 v[198:201], v212 offset:20480
	ds_read_b128 v[202:205], v212 offset:21504
	ds_read_b128 v[214:217], v212 offset:22528
	ds_read_b128 v[218:221], v212 offset:23552
	global_load_lds_dwordx4 v[206:207], off
	s_add_i32 m0, s0, 0x2000
	s_add_u32 s0, s42, 0x40000
	v_lshl_add_u64 v[222:223], s[42:43], 0, v[162:163]
	s_addc_u32 s1, s43, 0
	s_add_i32 s34, s61, s51
	global_load_lds_dwordx4 v[222:223], off
	s_mov_b32 m0, s34
	s_nop 0
	global_load_lds_dwordx4 v158, s[0:1]
	s_add_i32 m0, s34, 0x2000
	s_nop 0
	global_load_lds_dwordx4 v162, s[0:1]
	s_waitcnt vmcnt(6)
	s_waitcnt lgkmcnt(0)
	s_barrier
	s_setprio 1
	v_mfma_f32_16x16x32_bf16 v[60:63], v[100:103], v[182:185], v[60:63]
	v_mfma_f32_16x16x32_bf16 v[52:55], v[136:139], v[182:185], v[52:55]
	v_mfma_f32_16x16x32_bf16 v[44:47], v[100:103], v[190:193], v[44:47]
	v_mfma_f32_16x16x32_bf16 v[36:39], v[136:139], v[190:193], v[36:39]
	v_mfma_f32_16x16x32_bf16 v[28:31], v[100:103], v[198:201], v[28:31]
	v_mfma_f32_16x16x32_bf16 v[20:23], v[136:139], v[198:201], v[20:23]
	v_mfma_f32_16x16x32_bf16 v[12:15], v[100:103], v[214:217], v[12:15]
	v_mfma_f32_16x16x32_bf16 v[4:7], v[136:139], v[214:217], v[4:7]
	v_mfma_f32_16x16x32_bf16 v[60:63], v[116:119], v[186:189], v[60:63]
	v_mfma_f32_16x16x32_bf16 v[52:55], v[140:143], v[186:189], v[52:55]
	v_mfma_f32_16x16x32_bf16 v[44:47], v[116:119], v[194:197], v[44:47]
	v_mfma_f32_16x16x32_bf16 v[36:39], v[140:143], v[194:197], v[36:39]
	v_mfma_f32_16x16x32_bf16 v[28:31], v[116:119], v[202:205], v[28:31]
	v_mfma_f32_16x16x32_bf16 v[20:23], v[140:143], v[202:205], v[20:23]
	v_mfma_f32_16x16x32_bf16 v[12:15], v[116:119], v[218:221], v[12:15]
	v_mfma_f32_16x16x32_bf16 v[4:7], v[140:143], v[218:221], v[4:7]
	v_mfma_f32_16x16x32_bf16 v[56:59], v[144:147], v[182:185], v[56:59]
	v_mfma_f32_16x16x32_bf16 v[48:51], v[152:155], v[182:185], v[48:51]
	v_mfma_f32_16x16x32_bf16 v[40:43], v[144:147], v[190:193], v[40:43]
	v_mfma_f32_16x16x32_bf16 v[32:35], v[152:155], v[190:193], v[32:35]
	v_mfma_f32_16x16x32_bf16 v[24:27], v[144:147], v[198:201], v[24:27]
	v_mfma_f32_16x16x32_bf16 v[16:19], v[152:155], v[198:201], v[16:19]
	v_mfma_f32_16x16x32_bf16 v[8:11], v[144:147], v[214:217], v[8:11]
	v_mfma_f32_16x16x32_bf16 v[0:3], v[152:155], v[214:217], v[0:3]
	v_mfma_f32_16x16x32_bf16 v[56:59], v[148:151], v[186:189], v[56:59]
	v_mfma_f32_16x16x32_bf16 v[48:51], v[178:181], v[186:189], v[48:51]
	v_mfma_f32_16x16x32_bf16 v[40:43], v[148:151], v[194:197], v[40:43]
	v_mfma_f32_16x16x32_bf16 v[32:35], v[178:181], v[194:197], v[32:35]
	v_mfma_f32_16x16x32_bf16 v[24:27], v[148:151], v[202:205], v[24:27]
	v_mfma_f32_16x16x32_bf16 v[16:19], v[178:181], v[202:205], v[16:19]
	v_mfma_f32_16x16x32_bf16 v[8:11], v[148:151], v[218:221], v[8:11]
	v_mfma_f32_16x16x32_bf16 v[0:3], v[178:181], v[218:221], v[0:3]
	s_barrier
	s_setprio 0
	s_add_i32 s34, 0, 0x18000
	s_add_i32 s35, 0, 0x1c000
	v_add_u32_e32 v140, s34, v209
	v_add_u32_e32 v178, s35, v209
	ds_read_b128 v[100:103], v140
	ds_read_b128 v[116:119], v140 offset:1024
	ds_read_b128 v[136:139], v140 offset:2048
	ds_read_b128 v[140:143], v140 offset:3072
	ds_read_b128 v[144:147], v178
	ds_read_b128 v[148:151], v178 offset:1024
	ds_read_b128 v[152:155], v178 offset:2048
	ds_read_b128 v[178:181], v178 offset:3072
	s_add_u32 s0, s44, 0x1000
	s_addc_u32 s1, s45, 0
	s_mov_b32 m0, s54
	ds_read_b128 v[182:185], v212 offset:32768
	ds_read_b128 v[186:189], v212 offset:33792
	ds_read_b128 v[190:193], v212 offset:34816
	ds_read_b128 v[194:197], v212 offset:35840
	ds_read_b128 v[198:201], v212 offset:36864
	ds_read_b128 v[202:205], v212 offset:37888
	ds_read_b128 v[214:217], v212 offset:38912
	ds_read_b128 v[218:221], v212 offset:39936
	global_load_lds_dwordx4 v156, s[0:1]
	s_mov_b32 m0, s55
	s_nop 0
	global_load_lds_dwordx4 v160, s[0:1]
	s_mov_b32 m0, s52
	s_nop 0
	global_load_lds_dwordx4 v156, s[44:45]
	s_mov_b32 m0, s53
	s_nop 0
	global_load_lds_dwordx4 v160, s[44:45]
	s_waitcnt vmcnt(8)
	s_waitcnt lgkmcnt(0)
	s_barrier
	s_setprio 1
	v_mfma_f32_16x16x32_bf16 v[132:135], v[100:103], v[182:185], v[132:135]
	v_mfma_f32_16x16x32_bf16 v[124:127], v[136:139], v[182:185], v[124:127]
	v_mfma_f32_16x16x32_bf16 v[112:115], v[100:103], v[190:193], v[112:115]
	v_mfma_f32_16x16x32_bf16 v[104:107], v[136:139], v[190:193], v[104:107]
	v_mfma_f32_16x16x32_bf16 v[92:95], v[100:103], v[198:201], v[92:95]
	v_mfma_f32_16x16x32_bf16 v[84:87], v[136:139], v[198:201], v[84:87]
	v_mfma_f32_16x16x32_bf16 v[76:79], v[100:103], v[214:217], v[76:79]
	v_mfma_f32_16x16x32_bf16 v[68:71], v[136:139], v[214:217], v[68:71]
	v_mfma_f32_16x16x32_bf16 v[132:135], v[116:119], v[186:189], v[132:135]
	v_mfma_f32_16x16x32_bf16 v[124:127], v[140:143], v[186:189], v[124:127]
	v_mfma_f32_16x16x32_bf16 v[112:115], v[116:119], v[194:197], v[112:115]
	v_mfma_f32_16x16x32_bf16 v[104:107], v[140:143], v[194:197], v[104:107]
	v_mfma_f32_16x16x32_bf16 v[92:95], v[116:119], v[202:205], v[92:95]
	v_mfma_f32_16x16x32_bf16 v[84:87], v[140:143], v[202:205], v[84:87]
	v_mfma_f32_16x16x32_bf16 v[76:79], v[116:119], v[218:221], v[76:79]
	v_mfma_f32_16x16x32_bf16 v[68:71], v[140:143], v[218:221], v[68:71]
	v_mfma_f32_16x16x32_bf16 v[128:131], v[144:147], v[182:185], v[128:131]
	v_mfma_f32_16x16x32_bf16 v[120:123], v[152:155], v[182:185], v[120:123]
	v_mfma_f32_16x16x32_bf16 v[108:111], v[144:147], v[190:193], v[108:111]
	v_mfma_f32_16x16x32_bf16 v[96:99], v[152:155], v[190:193], v[96:99]
	v_mfma_f32_16x16x32_bf16 v[88:91], v[144:147], v[198:201], v[88:91]
	v_mfma_f32_16x16x32_bf16 v[80:83], v[152:155], v[198:201], v[80:83]
	v_mfma_f32_16x16x32_bf16 v[72:75], v[144:147], v[214:217], v[72:75]
	v_mfma_f32_16x16x32_bf16 v[64:67], v[152:155], v[214:217], v[64:67]
	v_mfma_f32_16x16x32_bf16 v[128:131], v[148:151], v[186:189], v[128:131]
	v_mfma_f32_16x16x32_bf16 v[120:123], v[178:181], v[186:189], v[120:123]
	v_mfma_f32_16x16x32_bf16 v[108:111], v[148:151], v[194:197], v[108:111]
	v_mfma_f32_16x16x32_bf16 v[96:99], v[178:181], v[194:197], v[96:99]
	v_mfma_f32_16x16x32_bf16 v[88:91], v[148:151], v[202:205], v[88:91]
	v_mfma_f32_16x16x32_bf16 v[80:83], v[178:181], v[202:205], v[80:83]
	v_mfma_f32_16x16x32_bf16 v[72:75], v[148:151], v[218:221], v[72:75]
	v_mfma_f32_16x16x32_bf16 v[64:67], v[178:181], v[218:221], v[64:67]
	s_barrier
	s_setprio 0
	s_add_i32 s0, s34, s51
	v_lshl_add_u64 v[206:207], v[206:207], 0, s[16:17]
	s_mov_b32 m0, s0
	ds_read_b128 v[182:185], v212 offset:49152
	ds_read_b128 v[186:189], v212 offset:50176
	ds_read_b128 v[190:193], v212 offset:51200
	ds_read_b128 v[194:197], v212 offset:52224
	ds_read_b128 v[198:201], v212 offset:53248
	ds_read_b128 v[202:205], v212 offset:54272
	ds_read_b128 v[214:217], v212 offset:55296
	ds_read_b128 v[218:221], v212 offset:56320
	global_load_lds_dwordx4 v[206:207], off
	s_add_i32 m0, s0, 0x2000
	s_add_u32 s0, s42, 0x40080
	v_lshl_add_u64 v[206:207], v[222:223], 0, s[16:17]
	s_addc_u32 s1, s43, 0
	s_add_i32 s34, s35, s51
	global_load_lds_dwordx4 v[206:207], off
	s_mov_b32 m0, s34
	s_nop 0
	global_load_lds_dwordx4 v158, s[0:1]
	s_add_i32 m0, s34, 0x2000
	s_nop 0
	global_load_lds_dwordx4 v162, s[0:1]
	s_mov_b32 m0, s56
	s_nop 0
	global_load_lds_dwordx4 v156, s[40:41]
	s_mov_b32 m0, s57
	s_nop 0
	global_load_lds_dwordx4 v160, s[40:41]
	s_waitcnt vmcnt(6)
	s_waitcnt lgkmcnt(0)
	s_barrier
	s_setprio 1
	v_mfma_f32_16x16x32_bf16 v[60:63], v[100:103], v[182:185], v[60:63]
	v_mfma_f32_16x16x32_bf16 v[52:55], v[136:139], v[182:185], v[52:55]
	v_mfma_f32_16x16x32_bf16 v[44:47], v[100:103], v[190:193], v[44:47]
	v_mfma_f32_16x16x32_bf16 v[36:39], v[136:139], v[190:193], v[36:39]
	v_mfma_f32_16x16x32_bf16 v[28:31], v[100:103], v[198:201], v[28:31]
	v_mfma_f32_16x16x32_bf16 v[20:23], v[136:139], v[198:201], v[20:23]
	v_mfma_f32_16x16x32_bf16 v[12:15], v[100:103], v[214:217], v[12:15]
	v_mfma_f32_16x16x32_bf16 v[4:7], v[136:139], v[214:217], v[4:7]
	v_mfma_f32_16x16x32_bf16 v[60:63], v[116:119], v[186:189], v[60:63]
	v_mfma_f32_16x16x32_bf16 v[52:55], v[140:143], v[186:189], v[52:55]
	v_mfma_f32_16x16x32_bf16 v[44:47], v[116:119], v[194:197], v[44:47]
	v_mfma_f32_16x16x32_bf16 v[36:39], v[140:143], v[194:197], v[36:39]
	v_mfma_f32_16x16x32_bf16 v[28:31], v[116:119], v[202:205], v[28:31]
	v_mfma_f32_16x16x32_bf16 v[20:23], v[140:143], v[202:205], v[20:23]
	v_mfma_f32_16x16x32_bf16 v[12:15], v[116:119], v[218:221], v[12:15]
	v_mfma_f32_16x16x32_bf16 v[4:7], v[140:143], v[218:221], v[4:7]
	v_mfma_f32_16x16x32_bf16 v[56:59], v[144:147], v[182:185], v[56:59]
	v_mfma_f32_16x16x32_bf16 v[48:51], v[152:155], v[182:185], v[48:51]
	v_mfma_f32_16x16x32_bf16 v[40:43], v[144:147], v[190:193], v[40:43]
	v_mfma_f32_16x16x32_bf16 v[32:35], v[152:155], v[190:193], v[32:35]
	v_mfma_f32_16x16x32_bf16 v[24:27], v[144:147], v[198:201], v[24:27]
	v_mfma_f32_16x16x32_bf16 v[16:19], v[152:155], v[198:201], v[16:19]
	v_mfma_f32_16x16x32_bf16 v[8:11], v[144:147], v[214:217], v[8:11]
	v_mfma_f32_16x16x32_bf16 v[0:3], v[152:155], v[214:217], v[0:3]
	v_mfma_f32_16x16x32_bf16 v[56:59], v[148:151], v[186:189], v[56:59]
	v_mfma_f32_16x16x32_bf16 v[48:51], v[178:181], v[186:189], v[48:51]
	v_mfma_f32_16x16x32_bf16 v[40:43], v[148:151], v[194:197], v[40:43]
	v_mfma_f32_16x16x32_bf16 v[32:35], v[178:181], v[194:197], v[32:35]
	v_mfma_f32_16x16x32_bf16 v[24:27], v[148:151], v[202:205], v[24:27]
	v_mfma_f32_16x16x32_bf16 v[16:19], v[178:181], v[202:205], v[16:19]
	v_mfma_f32_16x16x32_bf16 v[8:11], v[148:151], v[218:221], v[8:11]
	v_mfma_f32_16x16x32_bf16 v[0:3], v[178:181], v[218:221], v[0:3]
	s_barrier
	s_setprio 0
	s_add_i32 s65, s65, 2
	s_add_u32 s63, s63, 0x100
	s_addc_u32 s64, s64, 0
	s_cmp_gt_u32 s65, 13
	s_mov_b64 s[34:35], s[36:37]
	s_cbranch_scc0 .LBB0_480
	s_and_b64 vcc, exec, s[18:19]
	s_cbranch_vccz .LBB0_483
	s_barrier

.Lrestag_577:
	s_add_u32 s52, s50, 0x100
	s_addc_u32 s53, s51, 0
	s_add_i32 s0, 0, 0x10000
	s_cmp_eq_u32 s76, 12
	s_cselect_b32 s57, s43, s53
	s_cselect_b32 s56, s67, s52
	s_cselect_b32 s55, s41, s75
	s_cselect_b32 s54, s68, s69
	s_add_i32 s12, 0, 0x14000
	v_add_u32_e32 v154, s0, v188
	v_add_u32_e32 v166, s12, v188
	ds_read_b128 v[142:145], v154
	ds_read_b128 v[146:149], v154 offset:1024
	ds_read_b128 v[150:153], v154 offset:2048
	ds_read_b128 v[154:157], v154 offset:3072
	ds_read_b128 v[158:161], v166
	ds_read_b128 v[162:165], v166 offset:1024
	ds_read_b128 v[184:187], v166 offset:2048
	ds_read_b128 v[190:193], v166 offset:3072
	s_add_i32 m0, s49, 0xc000
	ds_read_b128 v[194:197], v189
	ds_read_b128 v[198:201], v189 offset:1024
	ds_read_b128 v[202:205], v189 offset:2048
	ds_read_b128 v[206:209], v189 offset:3072
	ds_read_b128 v[210:213], v189 offset:4096
	ds_read_b128 v[214:217], v189 offset:5120
	ds_read_b128 v[228:231], v189 offset:6144
	ds_read_b128 v[232:235], v189 offset:7168
	global_load_lds_dwordx4 v138, s[50:51]
	s_add_i32 m0, s49, 0xe000
	s_nop 0
	global_load_lds_dwordx4 v140, s[50:51]
	s_nop 0
	s_waitcnt lgkmcnt(0)
	s_barrier
	s_setprio 1
	v_mfma_f32_16x16x32_bf16 v[124:127], v[142:145], v[194:197], 0
	v_mfma_f32_16x16x32_bf16 v[120:123], v[150:153], v[194:197], 0
	v_mfma_f32_16x16x32_bf16 v[108:111], v[142:145], v[202:205], 0
	v_mfma_f32_16x16x32_bf16 v[104:107], v[150:153], v[202:205], 0
	v_mfma_f32_16x16x32_bf16 v[92:95], v[142:145], v[210:213], 0
	v_mfma_f32_16x16x32_bf16 v[88:91], v[150:153], v[210:213], 0
	v_mfma_f32_16x16x32_bf16 v[76:79], v[142:145], v[228:231], 0
	v_mfma_f32_16x16x32_bf16 v[72:75], v[150:153], v[228:231], 0
	v_mfma_f32_16x16x32_bf16 v[124:127], v[146:149], v[198:201], v[124:127]
	v_mfma_f32_16x16x32_bf16 v[120:123], v[154:157], v[198:201], v[120:123]
	v_mfma_f32_16x16x32_bf16 v[108:111], v[146:149], v[206:209], v[108:111]
	v_mfma_f32_16x16x32_bf16 v[104:107], v[154:157], v[206:209], v[104:107]
	v_mfma_f32_16x16x32_bf16 v[92:95], v[146:149], v[214:217], v[92:95]
	v_mfma_f32_16x16x32_bf16 v[88:91], v[154:157], v[214:217], v[88:91]
	v_mfma_f32_16x16x32_bf16 v[76:79], v[146:149], v[232:235], v[76:79]
	v_mfma_f32_16x16x32_bf16 v[72:75], v[154:157], v[232:235], v[72:75]
	v_mfma_f32_16x16x32_bf16 v[116:119], v[158:161], v[194:197], 0
	v_mfma_f32_16x16x32_bf16 v[112:115], v[184:187], v[194:197], 0
	v_mfma_f32_16x16x32_bf16 v[100:103], v[158:161], v[202:205], 0
	v_mfma_f32_16x16x32_bf16 v[96:99], v[184:187], v[202:205], 0
	v_mfma_f32_16x16x32_bf16 v[84:87], v[158:161], v[210:213], 0
	v_mfma_f32_16x16x32_bf16 v[80:83], v[184:187], v[210:213], 0
	v_mfma_f32_16x16x32_bf16 v[68:71], v[158:161], v[228:231], 0
	v_mfma_f32_16x16x32_bf16 v[64:67], v[184:187], v[228:231], 0
	v_mfma_f32_16x16x32_bf16 v[116:119], v[162:165], v[198:201], v[116:119]
	v_mfma_f32_16x16x32_bf16 v[112:115], v[190:193], v[198:201], v[112:115]
	v_mfma_f32_16x16x32_bf16 v[100:103], v[162:165], v[206:209], v[100:103]
	v_mfma_f32_16x16x32_bf16 v[96:99], v[190:193], v[206:209], v[96:99]
	v_mfma_f32_16x16x32_bf16 v[84:87], v[162:165], v[214:217], v[84:87]
	v_mfma_f32_16x16x32_bf16 v[80:83], v[190:193], v[214:217], v[80:83]
	v_mfma_f32_16x16x32_bf16 v[68:71], v[162:165], v[232:235], v[68:71]
	v_mfma_f32_16x16x32_bf16 v[64:67], v[190:193], v[232:235], v[64:67]
	s_barrier
	s_setprio 0
	s_add_i32 s0, s0, s59
	v_lshl_add_u64 v[166:167], s[54:55], 0, v[130:131]
	s_mov_b32 m0, s0
	ds_read_b128 v[194:197], v189 offset:16384
	ds_read_b128 v[198:201], v189 offset:17408
	ds_read_b128 v[202:205], v189 offset:18432
	ds_read_b128 v[206:209], v189 offset:19456
	ds_read_b128 v[210:213], v189 offset:20480
	ds_read_b128 v[214:217], v189 offset:21504
	ds_read_b128 v[228:231], v189 offset:22528
	ds_read_b128 v[232:235], v189 offset:23552
	global_load_lds_dwordx4 v[166:167], off
	s_add_i32 m0, s0, 0x2000
	s_add_u32 s0, s54, 0x40000
	v_lshl_add_u64 v[218:219], s[54:55], 0, v[134:135]
	s_addc_u32 s1, s55, 0
	s_add_i32 s12, s12, s59
	global_load_lds_dwordx4 v[218:219], off
	s_mov_b32 m0, s12
	v_lshl_add_u64 v[238:239], s[56:57], 0, v[132:133]
	global_load_lds_dwordx4 v130, s[0:1]
	s_add_i32 m0, s12, 0x2000
	s_nop 0
	global_load_lds_dwordx4 v134, s[0:1]
	v_lshl_add_u64 v[236:237], s[56:57], 0, v[128:129]
	s_nop 0
	s_waitcnt lgkmcnt(0)
	s_barrier
	s_setprio 1
	v_mfma_f32_16x16x32_bf16 v[60:63], v[142:145], v[194:197], 0
	v_mfma_f32_16x16x32_bf16 v[56:59], v[150:153], v[194:197], 0
	v_mfma_f32_16x16x32_bf16 v[44:47], v[142:145], v[202:205], 0
	v_mfma_f32_16x16x32_bf16 v[40:43], v[150:153], v[202:205], 0
	v_mfma_f32_16x16x32_bf16 v[28:31], v[142:145], v[210:213], 0
	v_mfma_f32_16x16x32_bf16 v[24:27], v[150:153], v[210:213], 0
	v_mfma_f32_16x16x32_bf16 v[12:15], v[142:145], v[228:231], 0
	v_mfma_f32_16x16x32_bf16 v[8:11], v[150:153], v[228:231], 0
	v_mfma_f32_16x16x32_bf16 v[60:63], v[146:149], v[198:201], v[60:63]
	v_mfma_f32_16x16x32_bf16 v[56:59], v[154:157], v[198:201], v[56:59]
	v_mfma_f32_16x16x32_bf16 v[44:47], v[146:149], v[206:209], v[44:47]
	v_mfma_f32_16x16x32_bf16 v[40:43], v[154:157], v[206:209], v[40:43]
	v_mfma_f32_16x16x32_bf16 v[28:31], v[146:149], v[214:217], v[28:31]
	v_mfma_f32_16x16x32_bf16 v[24:27], v[154:157], v[214:217], v[24:27]
	v_mfma_f32_16x16x32_bf16 v[12:15], v[146:149], v[232:235], v[12:15]
	v_mfma_f32_16x16x32_bf16 v[8:11], v[154:157], v[232:235], v[8:11]
	v_mfma_f32_16x16x32_bf16 v[52:55], v[158:161], v[194:197], 0
	v_mfma_f32_16x16x32_bf16 v[48:51], v[184:187], v[194:197], 0
	v_mfma_f32_16x16x32_bf16 v[36:39], v[158:161], v[202:205], 0
	v_mfma_f32_16x16x32_bf16 v[32:35], v[184:187], v[202:205], 0
	v_mfma_f32_16x16x32_bf16 v[20:23], v[158:161], v[210:213], 0
	v_mfma_f32_16x16x32_bf16 v[16:19], v[184:187], v[210:213], 0
	v_mfma_f32_16x16x32_bf16 v[4:7], v[158:161], v[228:231], 0
	v_mfma_f32_16x16x32_bf16 v[0:3], v[184:187], v[228:231], 0
	v_mfma_f32_16x16x32_bf16 v[52:55], v[162:165], v[198:201], v[52:55]
	v_mfma_f32_16x16x32_bf16 v[48:51], v[190:193], v[198:201], v[48:51]
	v_mfma_f32_16x16x32_bf16 v[36:39], v[162:165], v[206:209], v[36:39]
	v_mfma_f32_16x16x32_bf16 v[32:35], v[190:193], v[206:209], v[32:35]
	v_mfma_f32_16x16x32_bf16 v[20:23], v[162:165], v[214:217], v[20:23]
	v_mfma_f32_16x16x32_bf16 v[16:19], v[190:193], v[214:217], v[16:19]
	v_mfma_f32_16x16x32_bf16 v[4:7], v[162:165], v[232:235], v[4:7]
	v_mfma_f32_16x16x32_bf16 v[0:3], v[190:193], v[232:235], v[0:3]
	s_barrier
	s_setprio 0
	s_add_i32 s12, 0, 0x18000
	s_add_i32 s13, 0, 0x1c000
	v_add_u32_e32 v154, s12, v188
	v_add_u32_e32 v170, s13, v188
	ds_read_b128 v[142:145], v154
	ds_read_b128 v[146:149], v154 offset:1024
	ds_read_b128 v[150:153], v154 offset:2048
	ds_read_b128 v[154:157], v154 offset:3072
	ds_read_b128 v[158:161], v170
	ds_read_b128 v[162:165], v170 offset:1024
	ds_read_b128 v[184:187], v170 offset:2048
	ds_read_b128 v[190:193], v170 offset:3072
	s_add_u32 s0, s56, 0x40000
	s_addc_u32 s1, s57, 0
	s_mov_b32 m0, s61
	ds_read_b128 v[194:197], v189 offset:32768
	ds_read_b128 v[198:201], v189 offset:33792
	ds_read_b128 v[202:205], v189 offset:34816
	ds_read_b128 v[206:209], v189 offset:35840
	ds_read_b128 v[210:213], v189 offset:36864
	ds_read_b128 v[214:217], v189 offset:37888
	ds_read_b128 v[228:231], v189 offset:38912
	ds_read_b128 v[232:235], v189 offset:39936
	global_load_lds_dwordx4 v128, s[0:1]
	s_mov_b32 m0, s62
	s_nop 0
	global_load_lds_dwordx4 v132, s[0:1]
	s_mov_b32 m0, s49
	s_nop 0
	global_load_lds_dwordx4 v[236:237], off
	s_mov_b32 m0, s60
	s_nop 0
	global_load_lds_dwordx4 v[238:239], off
	s_waitcnt vmcnt(8)
	s_waitcnt lgkmcnt(0)
	s_barrier
	s_setprio 1
	v_mfma_f32_16x16x32_bf16 v[124:127], v[142:145], v[194:197], v[124:127]
	v_mfma_f32_16x16x32_bf16 v[120:123], v[150:153], v[194:197], v[120:123]
	v_mfma_f32_16x16x32_bf16 v[108:111], v[142:145], v[202:205], v[108:111]
	v_mfma_f32_16x16x32_bf16 v[104:107], v[150:153], v[202:205], v[104:107]
	v_mfma_f32_16x16x32_bf16 v[92:95], v[142:145], v[210:213], v[92:95]
	v_mfma_f32_16x16x32_bf16 v[88:91], v[150:153], v[210:213], v[88:91]
	v_mfma_f32_16x16x32_bf16 v[76:79], v[142:145], v[228:231], v[76:79]
	v_mfma_f32_16x16x32_bf16 v[72:75], v[150:153], v[228:231], v[72:75]
	v_mfma_f32_16x16x32_bf16 v[124:127], v[146:149], v[198:201], v[124:127]
	v_mfma_f32_16x16x32_bf16 v[120:123], v[154:157], v[198:201], v[120:123]
	v_mfma_f32_16x16x32_bf16 v[108:111], v[146:149], v[206:209], v[108:111]
	v_mfma_f32_16x16x32_bf16 v[104:107], v[154:157], v[206:209], v[104:107]
	v_mfma_f32_16x16x32_bf16 v[92:95], v[146:149], v[214:217], v[92:95]
	v_mfma_f32_16x16x32_bf16 v[88:91], v[154:157], v[214:217], v[88:91]
	v_mfma_f32_16x16x32_bf16 v[76:79], v[146:149], v[232:235], v[76:79]
	v_mfma_f32_16x16x32_bf16 v[72:75], v[154:157], v[232:235], v[72:75]
	v_mfma_f32_16x16x32_bf16 v[116:119], v[158:161], v[194:197], v[116:119]
	v_mfma_f32_16x16x32_bf16 v[112:115], v[184:187], v[194:197], v[112:115]
	v_mfma_f32_16x16x32_bf16 v[100:103], v[158:161], v[202:205], v[100:103]
	v_mfma_f32_16x16x32_bf16 v[96:99], v[184:187], v[202:205], v[96:99]
	v_mfma_f32_16x16x32_bf16 v[84:87], v[158:161], v[210:213], v[84:87]
	v_mfma_f32_16x16x32_bf16 v[80:83], v[184:187], v[210:213], v[80:83]
	v_mfma_f32_16x16x32_bf16 v[68:71], v[158:161], v[228:231], v[68:71]
	v_mfma_f32_16x16x32_bf16 v[64:67], v[184:187], v[228:231], v[64:67]
	v_mfma_f32_16x16x32_bf16 v[116:119], v[162:165], v[198:201], v[116:119]
	v_mfma_f32_16x16x32_bf16 v[112:115], v[190:193], v[198:201], v[112:115]
	v_mfma_f32_16x16x32_bf16 v[100:103], v[162:165], v[206:209], v[100:103]
	v_mfma_f32_16x16x32_bf16 v[96:99], v[190:193], v[206:209], v[96:99]
	v_mfma_f32_16x16x32_bf16 v[84:87], v[162:165], v[214:217], v[84:87]
	v_mfma_f32_16x16x32_bf16 v[80:83], v[190:193], v[214:217], v[80:83]
	v_mfma_f32_16x16x32_bf16 v[68:71], v[162:165], v[232:235], v[68:71]
	v_mfma_f32_16x16x32_bf16 v[64:67], v[190:193], v[232:235], v[64:67]
	s_barrier
	s_setprio 0
	s_add_i32 s0, s12, s59
	v_lshl_add_u64 v[166:167], v[166:167], 0, s[16:17]
	s_mov_b32 m0, s0
	ds_read_b128 v[194:197], v189 offset:49152
	ds_read_b128 v[198:201], v189 offset:50176
	ds_read_b128 v[202:205], v189 offset:51200
	ds_read_b128 v[206:209], v189 offset:52224
	ds_read_b128 v[210:213], v189 offset:53248
	ds_read_b128 v[214:217], v189 offset:54272
	ds_read_b128 v[228:231], v189 offset:55296
	ds_read_b128 v[232:235], v189 offset:56320
	global_load_lds_dwordx4 v[166:167], off
	s_add_i32 m0, s0, 0x2000
	s_add_u32 s0, s54, 0x40080
	v_lshl_add_u64 v[166:167], v[218:219], 0, s[16:17]
	s_addc_u32 s1, s55, 0
	s_add_i32 s12, s13, s59
	global_load_lds_dwordx4 v[166:167], off
	s_mov_b32 m0, s12
	s_nop 0
	global_load_lds_dwordx4 v130, s[0:1]
	s_add_i32 m0, s12, 0x2000
	s_nop 0
	global_load_lds_dwordx4 v134, s[0:1]
	v_lshl_add_u64 v[166:167], v[236:237], 0, s[16:17]
	s_mov_b32 m0, s64
	s_nop 0
	global_load_lds_dwordx4 v[166:167], off
	v_lshl_add_u64 v[166:167], v[238:239], 0, s[16:17]
	s_mov_b32 m0, s65
	s_nop 0
	global_load_lds_dwordx4 v[166:167], off
	s_waitcnt vmcnt(6)
	s_waitcnt lgkmcnt(0)
	s_barrier
	s_setprio 1
	v_mfma_f32_16x16x32_bf16 v[60:63], v[142:145], v[194:197], v[60:63]
	v_mfma_f32_16x16x32_bf16 v[56:59], v[150:153], v[194:197], v[56:59]
	v_mfma_f32_16x16x32_bf16 v[44:47], v[142:145], v[202:205], v[44:47]
	v_mfma_f32_16x16x32_bf16 v[40:43], v[150:153], v[202:205], v[40:43]
	v_mfma_f32_16x16x32_bf16 v[28:31], v[142:145], v[210:213], v[28:31]
	v_mfma_f32_16x16x32_bf16 v[24:27], v[150:153], v[210:213], v[24:27]
	v_mfma_f32_16x16x32_bf16 v[12:15], v[142:145], v[228:231], v[12:15]
	v_mfma_f32_16x16x32_bf16 v[8:11], v[150:153], v[228:231], v[8:11]
	v_mfma_f32_16x16x32_bf16 v[60:63], v[146:149], v[198:201], v[60:63]
	v_mfma_f32_16x16x32_bf16 v[56:59], v[154:157], v[198:201], v[56:59]
	v_mfma_f32_16x16x32_bf16 v[44:47], v[146:149], v[206:209], v[44:47]
	v_mfma_f32_16x16x32_bf16 v[40:43], v[154:157], v[206:209], v[40:43]
	v_mfma_f32_16x16x32_bf16 v[28:31], v[146:149], v[214:217], v[28:31]
	v_mfma_f32_16x16x32_bf16 v[24:27], v[154:157], v[214:217], v[24:27]
	v_mfma_f32_16x16x32_bf16 v[12:15], v[146:149], v[232:235], v[12:15]
	v_mfma_f32_16x16x32_bf16 v[8:11], v[154:157], v[232:235], v[8:11]
	v_mfma_f32_16x16x32_bf16 v[52:55], v[158:161], v[194:197], v[52:55]
	v_mfma_f32_16x16x32_bf16 v[48:51], v[184:187], v[194:197], v[48:51]
	v_mfma_f32_16x16x32_bf16 v[36:39], v[158:161], v[202:205], v[36:39]
	v_mfma_f32_16x16x32_bf16 v[32:35], v[184:187], v[202:205], v[32:35]
	v_mfma_f32_16x16x32_bf16 v[20:23], v[158:161], v[210:213], v[20:23]
	v_mfma_f32_16x16x32_bf16 v[16:19], v[184:187], v[210:213], v[16:19]
	v_mfma_f32_16x16x32_bf16 v[4:7], v[158:161], v[228:231], v[4:7]
	v_mfma_f32_16x16x32_bf16 v[0:3], v[184:187], v[228:231], v[0:3]
	v_mfma_f32_16x16x32_bf16 v[52:55], v[162:165], v[198:201], v[52:55]
	v_mfma_f32_16x16x32_bf16 v[48:51], v[190:193], v[198:201], v[48:51]
	v_mfma_f32_16x16x32_bf16 v[36:39], v[162:165], v[206:209], v[36:39]
	v_mfma_f32_16x16x32_bf16 v[32:35], v[190:193], v[206:209], v[32:35]
	v_mfma_f32_16x16x32_bf16 v[20:23], v[162:165], v[214:217], v[20:23]
	v_mfma_f32_16x16x32_bf16 v[16:19], v[190:193], v[214:217], v[16:19]
	v_mfma_f32_16x16x32_bf16 v[4:7], v[162:165], v[232:235], v[4:7]
	v_mfma_f32_16x16x32_bf16 v[0:3], v[190:193], v[232:235], v[0:3]
	s_barrier
	s_setprio 0
	s_add_i32 s76, s76, 2
	s_add_u32 s69, s69, 0x100
	s_addc_u32 s75, s75, 0
	s_cmp_gt_u32 s76, 13
	s_mov_b64 s[50:51], s[52:53]
.LBB0_577:
	s_add_u32 s52, s50, 0x100
	s_addc_u32 s53, s51, 0
	s_add_i32 s0, 0, 0x10000
	s_cmp_eq_u32 s76, 12
	s_cselect_b32 s57, s43, s53
	s_cselect_b32 s56, s67, s52
	s_cselect_b32 s55, s41, s75
	s_cselect_b32 s54, s68, s69
	s_add_i32 s12, 0, 0x14000
	v_add_u32_e32 v154, s0, v188
	v_add_u32_e32 v166, s12, v188
	ds_read_b128 v[142:145], v154
	ds_read_b128 v[146:149], v154 offset:1024
	ds_read_b128 v[150:153], v154 offset:2048
	ds_read_b128 v[154:157], v154 offset:3072
	ds_read_b128 v[158:161], v166
	ds_read_b128 v[162:165], v166 offset:1024
	ds_read_b128 v[184:187], v166 offset:2048
	ds_read_b128 v[190:193], v166 offset:3072
	s_add_i32 m0, s49, 0xc000
	ds_read_b128 v[194:197], v189
	ds_read_b128 v[198:201], v189 offset:1024
	ds_read_b128 v[202:205], v189 offset:2048
	ds_read_b128 v[206:209], v189 offset:3072
	ds_read_b128 v[210:213], v189 offset:4096
	ds_read_b128 v[214:217], v189 offset:5120
	ds_read_b128 v[228:231], v189 offset:6144
	ds_read_b128 v[232:235], v189 offset:7168
	global_load_lds_dwordx4 v138, s[50:51]
	s_add_i32 m0, s49, 0xe000
	s_nop 0
	global_load_lds_dwordx4 v140, s[50:51]
	s_waitcnt vmcnt(8)
	s_waitcnt lgkmcnt(0)
	s_barrier
	s_setprio 1
	v_mfma_f32_16x16x32_bf16 v[124:127], v[142:145], v[194:197], v[124:127]
	v_mfma_f32_16x16x32_bf16 v[120:123], v[150:153], v[194:197], v[120:123]
	v_mfma_f32_16x16x32_bf16 v[108:111], v[142:145], v[202:205], v[108:111]
	v_mfma_f32_16x16x32_bf16 v[104:107], v[150:153], v[202:205], v[104:107]
	v_mfma_f32_16x16x32_bf16 v[92:95], v[142:145], v[210:213], v[92:95]
	v_mfma_f32_16x16x32_bf16 v[88:91], v[150:153], v[210:213], v[88:91]
	v_mfma_f32_16x16x32_bf16 v[76:79], v[142:145], v[228:231], v[76:79]
	v_mfma_f32_16x16x32_bf16 v[72:75], v[150:153], v[228:231], v[72:75]
	v_mfma_f32_16x16x32_bf16 v[124:127], v[146:149], v[198:201], v[124:127]
	v_mfma_f32_16x16x32_bf16 v[120:123], v[154:157], v[198:201], v[120:123]
	v_mfma_f32_16x16x32_bf16 v[108:111], v[146:149], v[206:209], v[108:111]
	v_mfma_f32_16x16x32_bf16 v[104:107], v[154:157], v[206:209], v[104:107]
	v_mfma_f32_16x16x32_bf16 v[92:95], v[146:149], v[214:217], v[92:95]
	v_mfma_f32_16x16x32_bf16 v[88:91], v[154:157], v[214:217], v[88:91]
	v_mfma_f32_16x16x32_bf16 v[76:79], v[146:149], v[232:235], v[76:79]
	v_mfma_f32_16x16x32_bf16 v[72:75], v[154:157], v[232:235], v[72:75]
	v_mfma_f32_16x16x32_bf16 v[116:119], v[158:161], v[194:197], v[116:119]
	v_mfma_f32_16x16x32_bf16 v[112:115], v[184:187], v[194:197], v[112:115]
	v_mfma_f32_16x16x32_bf16 v[100:103], v[158:161], v[202:205], v[100:103]
	v_mfma_f32_16x16x32_bf16 v[96:99], v[184:187], v[202:205], v[96:99]
	v_mfma_f32_16x16x32_bf16 v[84:87], v[158:161], v[210:213], v[84:87]
	v_mfma_f32_16x16x32_bf16 v[80:83], v[184:187], v[210:213], v[80:83]
	v_mfma_f32_16x16x32_bf16 v[68:71], v[158:161], v[228:231], v[68:71]
	v_mfma_f32_16x16x32_bf16 v[64:67], v[184:187], v[228:231], v[64:67]
	v_mfma_f32_16x16x32_bf16 v[116:119], v[162:165], v[198:201], v[116:119]
	v_mfma_f32_16x16x32_bf16 v[112:115], v[190:193], v[198:201], v[112:115]
	v_mfma_f32_16x16x32_bf16 v[100:103], v[162:165], v[206:209], v[100:103]
	v_mfma_f32_16x16x32_bf16 v[96:99], v[190:193], v[206:209], v[96:99]
	v_mfma_f32_16x16x32_bf16 v[84:87], v[162:165], v[214:217], v[84:87]
	v_mfma_f32_16x16x32_bf16 v[80:83], v[190:193], v[214:217], v[80:83]
	v_mfma_f32_16x16x32_bf16 v[68:71], v[162:165], v[232:235], v[68:71]
	v_mfma_f32_16x16x32_bf16 v[64:67], v[190:193], v[232:235], v[64:67]
	s_barrier
	s_setprio 0
	s_add_i32 s0, s0, s59
	v_lshl_add_u64 v[166:167], s[54:55], 0, v[130:131]
	s_mov_b32 m0, s0
	ds_read_b128 v[194:197], v189 offset:16384
	ds_read_b128 v[198:201], v189 offset:17408
	ds_read_b128 v[202:205], v189 offset:18432
	ds_read_b128 v[206:209], v189 offset:19456
	ds_read_b128 v[210:213], v189 offset:20480
	ds_read_b128 v[214:217], v189 offset:21504
	ds_read_b128 v[228:231], v189 offset:22528
	ds_read_b128 v[232:235], v189 offset:23552
	global_load_lds_dwordx4 v[166:167], off
	s_add_i32 m0, s0, 0x2000
	s_add_u32 s0, s54, 0x40000
	v_lshl_add_u64 v[218:219], s[54:55], 0, v[134:135]
	s_addc_u32 s1, s55, 0
	s_add_i32 s12, s12, s59
	global_load_lds_dwordx4 v[218:219], off
	s_mov_b32 m0, s12
	v_lshl_add_u64 v[238:239], s[56:57], 0, v[132:133]
	global_load_lds_dwordx4 v130, s[0:1]
	s_add_i32 m0, s12, 0x2000
	s_nop 0
	global_load_lds_dwordx4 v134, s[0:1]
	v_lshl_add_u64 v[236:237], s[56:57], 0, v[128:129]
	s_waitcnt vmcnt(6)
	s_waitcnt lgkmcnt(0)
	s_barrier
	s_setprio 1
	v_mfma_f32_16x16x32_bf16 v[60:63], v[142:145], v[194:197], v[60:63]
	v_mfma_f32_16x16x32_bf16 v[56:59], v[150:153], v[194:197], v[56:59]
	v_mfma_f32_16x16x32_bf16 v[44:47], v[142:145], v[202:205], v[44:47]
	v_mfma_f32_16x16x32_bf16 v[40:43], v[150:153], v[202:205], v[40:43]
	v_mfma_f32_16x16x32_bf16 v[28:31], v[142:145], v[210:213], v[28:31]
	v_mfma_f32_16x16x32_bf16 v[24:27], v[150:153], v[210:213], v[24:27]
	v_mfma_f32_16x16x32_bf16 v[12:15], v[142:145], v[228:231], v[12:15]
	v_mfma_f32_16x16x32_bf16 v[8:11], v[150:153], v[228:231], v[8:11]
	v_mfma_f32_16x16x32_bf16 v[60:63], v[146:149], v[198:201], v[60:63]
	v_mfma_f32_16x16x32_bf16 v[56:59], v[154:157], v[198:201], v[56:59]
	v_mfma_f32_16x16x32_bf16 v[44:47], v[146:149], v[206:209], v[44:47]
	v_mfma_f32_16x16x32_bf16 v[40:43], v[154:157], v[206:209], v[40:43]
	v_mfma_f32_16x16x32_bf16 v[28:31], v[146:149], v[214:217], v[28:31]
	v_mfma_f32_16x16x32_bf16 v[24:27], v[154:157], v[214:217], v[24:27]
	v_mfma_f32_16x16x32_bf16 v[12:15], v[146:149], v[232:235], v[12:15]
	v_mfma_f32_16x16x32_bf16 v[8:11], v[154:157], v[232:235], v[8:11]
	v_mfma_f32_16x16x32_bf16 v[52:55], v[158:161], v[194:197], v[52:55]
	v_mfma_f32_16x16x32_bf16 v[48:51], v[184:187], v[194:197], v[48:51]
	v_mfma_f32_16x16x32_bf16 v[36:39], v[158:161], v[202:205], v[36:39]
	v_mfma_f32_16x16x32_bf16 v[32:35], v[184:187], v[202:205], v[32:35]
	v_mfma_f32_16x16x32_bf16 v[20:23], v[158:161], v[210:213], v[20:23]
	v_mfma_f32_16x16x32_bf16 v[16:19], v[184:187], v[210:213], v[16:19]
	v_mfma_f32_16x16x32_bf16 v[4:7], v[158:161], v[228:231], v[4:7]
	v_mfma_f32_16x16x32_bf16 v[0:3], v[184:187], v[228:231], v[0:3]
	v_mfma_f32_16x16x32_bf16 v[52:55], v[162:165], v[198:201], v[52:55]
	v_mfma_f32_16x16x32_bf16 v[48:51], v[190:193], v[198:201], v[48:51]
	v_mfma_f32_16x16x32_bf16 v[36:39], v[162:165], v[206:209], v[36:39]
	v_mfma_f32_16x16x32_bf16 v[32:35], v[190:193], v[206:209], v[32:35]
	v_mfma_f32_16x16x32_bf16 v[20:23], v[162:165], v[214:217], v[20:23]
	v_mfma_f32_16x16x32_bf16 v[16:19], v[190:193], v[214:217], v[16:19]
	v_mfma_f32_16x16x32_bf16 v[4:7], v[162:165], v[232:235], v[4:7]
	v_mfma_f32_16x16x32_bf16 v[0:3], v[190:193], v[232:235], v[0:3]
	s_barrier
	s_setprio 0
	s_add_i32 s12, 0, 0x18000
	s_add_i32 s13, 0, 0x1c000
	v_add_u32_e32 v154, s12, v188
	v_add_u32_e32 v170, s13, v188
	ds_read_b128 v[142:145], v154
	ds_read_b128 v[146:149], v154 offset:1024
	ds_read_b128 v[150:153], v154 offset:2048
	ds_read_b128 v[154:157], v154 offset:3072
	ds_read_b128 v[158:161], v170
	ds_read_b128 v[162:165], v170 offset:1024
	ds_read_b128 v[184:187], v170 offset:2048
	ds_read_b128 v[190:193], v170 offset:3072
	s_add_u32 s0, s56, 0x40000
	s_addc_u32 s1, s57, 0
	s_mov_b32 m0, s61
	ds_read_b128 v[194:197], v189 offset:32768
	ds_read_b128 v[198:201], v189 offset:33792
	ds_read_b128 v[202:205], v189 offset:34816
	ds_read_b128 v[206:209], v189 offset:35840
	ds_read_b128 v[210:213], v189 offset:36864
	ds_read_b128 v[214:217], v189 offset:37888
	ds_read_b128 v[228:231], v189 offset:38912
	ds_read_b128 v[232:235], v189 offset:39936
	global_load_lds_dwordx4 v128, s[0:1]
	s_mov_b32 m0, s62
	s_nop 0
	global_load_lds_dwordx4 v132, s[0:1]
	s_mov_b32 m0, s49
	s_nop 0
	global_load_lds_dwordx4 v[236:237], off
	s_mov_b32 m0, s60
	s_nop 0
	global_load_lds_dwordx4 v[238:239], off
	s_waitcnt vmcnt(8)
	s_waitcnt lgkmcnt(0)
	s_barrier
	s_setprio 1
	v_mfma_f32_16x16x32_bf16 v[124:127], v[142:145], v[194:197], v[124:127]
	v_mfma_f32_16x16x32_bf16 v[120:123], v[150:153], v[194:197], v[120:123]
	v_mfma_f32_16x16x32_bf16 v[108:111], v[142:145], v[202:205], v[108:111]
	v_mfma_f32_16x16x32_bf16 v[104:107], v[150:153], v[202:205], v[104:107]
	v_mfma_f32_16x16x32_bf16 v[92:95], v[142:145], v[210:213], v[92:95]
	v_mfma_f32_16x16x32_bf16 v[88:91], v[150:153], v[210:213], v[88:91]
	v_mfma_f32_16x16x32_bf16 v[76:79], v[142:145], v[228:231], v[76:79]
	v_mfma_f32_16x16x32_bf16 v[72:75], v[150:153], v[228:231], v[72:75]
	v_mfma_f32_16x16x32_bf16 v[124:127], v[146:149], v[198:201], v[124:127]
	v_mfma_f32_16x16x32_bf16 v[120:123], v[154:157], v[198:201], v[120:123]
	v_mfma_f32_16x16x32_bf16 v[108:111], v[146:149], v[206:209], v[108:111]
	v_mfma_f32_16x16x32_bf16 v[104:107], v[154:157], v[206:209], v[104:107]
	v_mfma_f32_16x16x32_bf16 v[92:95], v[146:149], v[214:217], v[92:95]
	v_mfma_f32_16x16x32_bf16 v[88:91], v[154:157], v[214:217], v[88:91]
	v_mfma_f32_16x16x32_bf16 v[76:79], v[146:149], v[232:235], v[76:79]
	v_mfma_f32_16x16x32_bf16 v[72:75], v[154:157], v[232:235], v[72:75]
	v_mfma_f32_16x16x32_bf16 v[116:119], v[158:161], v[194:197], v[116:119]
	v_mfma_f32_16x16x32_bf16 v[112:115], v[184:187], v[194:197], v[112:115]
	v_mfma_f32_16x16x32_bf16 v[100:103], v[158:161], v[202:205], v[100:103]
	v_mfma_f32_16x16x32_bf16 v[96:99], v[184:187], v[202:205], v[96:99]
	v_mfma_f32_16x16x32_bf16 v[84:87], v[158:161], v[210:213], v[84:87]
	v_mfma_f32_16x16x32_bf16 v[80:83], v[184:187], v[210:213], v[80:83]
	v_mfma_f32_16x16x32_bf16 v[68:71], v[158:161], v[228:231], v[68:71]
	v_mfma_f32_16x16x32_bf16 v[64:67], v[184:187], v[228:231], v[64:67]
	v_mfma_f32_16x16x32_bf16 v[116:119], v[162:165], v[198:201], v[116:119]
	v_mfma_f32_16x16x32_bf16 v[112:115], v[190:193], v[198:201], v[112:115]
	v_mfma_f32_16x16x32_bf16 v[100:103], v[162:165], v[206:209], v[100:103]
	v_mfma_f32_16x16x32_bf16 v[96:99], v[190:193], v[206:209], v[96:99]
	v_mfma_f32_16x16x32_bf16 v[84:87], v[162:165], v[214:217], v[84:87]
	v_mfma_f32_16x16x32_bf16 v[80:83], v[190:193], v[214:217], v[80:83]
	v_mfma_f32_16x16x32_bf16 v[68:71], v[162:165], v[232:235], v[68:71]
	v_mfma_f32_16x16x32_bf16 v[64:67], v[190:193], v[232:235], v[64:67]
	s_barrier
	s_setprio 0
	s_add_i32 s0, s12, s59
	v_lshl_add_u64 v[166:167], v[166:167], 0, s[16:17]
	s_mov_b32 m0, s0
	ds_read_b128 v[194:197], v189 offset:49152
	ds_read_b128 v[198:201], v189 offset:50176
	ds_read_b128 v[202:205], v189 offset:51200
	ds_read_b128 v[206:209], v189 offset:52224
	ds_read_b128 v[210:213], v189 offset:53248
	ds_read_b128 v[214:217], v189 offset:54272
	ds_read_b128 v[228:231], v189 offset:55296
	ds_read_b128 v[232:235], v189 offset:56320
	global_load_lds_dwordx4 v[166:167], off
	s_add_i32 m0, s0, 0x2000
	s_add_u32 s0, s54, 0x40080
	v_lshl_add_u64 v[166:167], v[218:219], 0, s[16:17]
	s_addc_u32 s1, s55, 0
	s_add_i32 s12, s13, s59
	global_load_lds_dwordx4 v[166:167], off
	s_mov_b32 m0, s12
	s_nop 0
	global_load_lds_dwordx4 v130, s[0:1]
	s_add_i32 m0, s12, 0x2000
	s_nop 0
	global_load_lds_dwordx4 v134, s[0:1]
	v_lshl_add_u64 v[166:167], v[236:237], 0, s[16:17]
	s_mov_b32 m0, s64
	s_nop 0
	global_load_lds_dwordx4 v[166:167], off
	v_lshl_add_u64 v[166:167], v[238:239], 0, s[16:17]
	s_mov_b32 m0, s65
	s_nop 0
	global_load_lds_dwordx4 v[166:167], off
	s_waitcnt vmcnt(6)
	s_waitcnt lgkmcnt(0)
	s_barrier
	s_setprio 1
	v_mfma_f32_16x16x32_bf16 v[60:63], v[142:145], v[194:197], v[60:63]
	v_mfma_f32_16x16x32_bf16 v[56:59], v[150:153], v[194:197], v[56:59]
	v_mfma_f32_16x16x32_bf16 v[44:47], v[142:145], v[202:205], v[44:47]
	v_mfma_f32_16x16x32_bf16 v[40:43], v[150:153], v[202:205], v[40:43]
	v_mfma_f32_16x16x32_bf16 v[28:31], v[142:145], v[210:213], v[28:31]
	v_mfma_f32_16x16x32_bf16 v[24:27], v[150:153], v[210:213], v[24:27]
	v_mfma_f32_16x16x32_bf16 v[12:15], v[142:145], v[228:231], v[12:15]
	v_mfma_f32_16x16x32_bf16 v[8:11], v[150:153], v[228:231], v[8:11]
	v_mfma_f32_16x16x32_bf16 v[60:63], v[146:149], v[198:201], v[60:63]
	v_mfma_f32_16x16x32_bf16 v[56:59], v[154:157], v[198:201], v[56:59]
	v_mfma_f32_16x16x32_bf16 v[44:47], v[146:149], v[206:209], v[44:47]
	v_mfma_f32_16x16x32_bf16 v[40:43], v[154:157], v[206:209], v[40:43]
	v_mfma_f32_16x16x32_bf16 v[28:31], v[146:149], v[214:217], v[28:31]
	v_mfma_f32_16x16x32_bf16 v[24:27], v[154:157], v[214:217], v[24:27]
	v_mfma_f32_16x16x32_bf16 v[12:15], v[146:149], v[232:235], v[12:15]
	v_mfma_f32_16x16x32_bf16 v[8:11], v[154:157], v[232:235], v[8:11]
	v_mfma_f32_16x16x32_bf16 v[52:55], v[158:161], v[194:197], v[52:55]
	v_mfma_f32_16x16x32_bf16 v[48:51], v[184:187], v[194:197], v[48:51]
	v_mfma_f32_16x16x32_bf16 v[36:39], v[158:161], v[202:205], v[36:39]
	v_mfma_f32_16x16x32_bf16 v[32:35], v[184:187], v[202:205], v[32:35]
	v_mfma_f32_16x16x32_bf16 v[20:23], v[158:161], v[210:213], v[20:23]
	v_mfma_f32_16x16x32_bf16 v[16:19], v[184:187], v[210:213], v[16:19]
	v_mfma_f32_16x16x32_bf16 v[4:7], v[158:161], v[228:231], v[4:7]
	v_mfma_f32_16x16x32_bf16 v[0:3], v[184:187], v[228:231], v[0:3]
	v_mfma_f32_16x16x32_bf16 v[52:55], v[162:165], v[198:201], v[52:55]
	v_mfma_f32_16x16x32_bf16 v[48:51], v[190:193], v[198:201], v[48:51]
	v_mfma_f32_16x16x32_bf16 v[36:39], v[162:165], v[206:209], v[36:39]
	v_mfma_f32_16x16x32_bf16 v[32:35], v[190:193], v[206:209], v[32:35]
	v_mfma_f32_16x16x32_bf16 v[20:23], v[162:165], v[214:217], v[20:23]
	v_mfma_f32_16x16x32_bf16 v[16:19], v[190:193], v[214:217], v[16:19]
	v_mfma_f32_16x16x32_bf16 v[4:7], v[162:165], v[232:235], v[4:7]
	v_mfma_f32_16x16x32_bf16 v[0:3], v[190:193], v[232:235], v[0:3]
	s_barrier
	s_setprio 0
	s_add_i32 s76, s76, 2
	s_add_u32 s69, s69, 0x100
	s_addc_u32 s75, s75, 0
	s_cmp_gt_u32 s76, 13
	s_mov_b64 s[50:51], s[52:53]
	s_cbranch_scc0 .LBB0_577
	s_and_b64 vcc, exec, s[36:37]
	s_cbranch_vccz .LBB0_580
	s_barrier

.Lrestag_601:
	s_add_u32 s48, s46, 0x100
	s_addc_u32 s49, s47, 0
	s_add_i32 s0, 0, 0x10000
	s_cmp_eq_u32 s66, 12
	s_cselect_b32 s53, s37, s49
	s_cselect_b32 s52, s62, s48
	v_add_u32_e32 v146, s0, v149
	s_cselect_b32 s51, s35, s65
	s_cselect_b32 s50, s63, s64
	s_add_i32 s12, 0, 0x14000
	ds_read_b128 v[128:131], v146
	ds_read_b128 v[132:135], v146 offset:1024
	ds_read_b128 v[152:155], v146 offset:2048
	ds_read_b128 v[156:159], v146 offset:3072
	v_add_u32_e32 v146, s12, v149
	ds_read_b128 v[160:163], v146
	ds_read_b128 v[164:167], v146 offset:1024
	ds_read_b128 v[184:187], v146 offset:2048
	ds_read_b128 v[188:191], v146 offset:3072
	s_add_i32 m0, s45, 0xc000
	ds_read_b128 v[192:195], v151
	ds_read_b128 v[196:199], v151 offset:1024
	ds_read_b128 v[200:203], v151 offset:2048
	ds_read_b128 v[204:207], v151 offset:3072
	ds_read_b128 v[208:211], v151 offset:4096
	ds_read_b128 v[212:215], v151 offset:5120
	ds_read_b128 v[216:219], v151 offset:6144
	ds_read_b128 v[228:231], v151 offset:7168
	global_load_lds_dwordx4 v142, s[46:47]
	s_add_i32 m0, s45, 0xe000
	s_nop 0
	global_load_lds_dwordx4 v144, s[46:47]
	s_nop 0
	s_waitcnt lgkmcnt(0)
	s_barrier
	s_setprio 1
	v_mfma_f32_16x16x32_bf16 v[124:127], v[128:131], v[192:195], 0
	v_mfma_f32_16x16x32_bf16 v[120:123], v[152:155], v[192:195], 0
	v_mfma_f32_16x16x32_bf16 v[116:119], v[128:131], v[200:203], 0
	v_mfma_f32_16x16x32_bf16 v[112:115], v[152:155], v[200:203], 0
	v_mfma_f32_16x16x32_bf16 v[108:111], v[128:131], v[208:211], 0
	v_mfma_f32_16x16x32_bf16 v[104:107], v[152:155], v[208:211], 0
	v_mfma_f32_16x16x32_bf16 v[100:103], v[128:131], v[216:219], 0
	v_mfma_f32_16x16x32_bf16 v[96:99], v[152:155], v[216:219], 0
	v_mfma_f32_16x16x32_bf16 v[124:127], v[132:135], v[196:199], v[124:127]
	v_mfma_f32_16x16x32_bf16 v[120:123], v[156:159], v[196:199], v[120:123]
	v_mfma_f32_16x16x32_bf16 v[116:119], v[132:135], v[204:207], v[116:119]
	v_mfma_f32_16x16x32_bf16 v[112:115], v[156:159], v[204:207], v[112:115]
	v_mfma_f32_16x16x32_bf16 v[108:111], v[132:135], v[212:215], v[108:111]
	v_mfma_f32_16x16x32_bf16 v[104:107], v[156:159], v[212:215], v[104:107]
	v_mfma_f32_16x16x32_bf16 v[100:103], v[132:135], v[228:231], v[100:103]
	v_mfma_f32_16x16x32_bf16 v[96:99], v[156:159], v[228:231], v[96:99]
	v_mfma_f32_16x16x32_bf16 v[68:71], v[160:163], v[192:195], 0
	v_mfma_f32_16x16x32_bf16 v[60:63], v[184:187], v[192:195], 0
	v_mfma_f32_16x16x32_bf16 v[52:55], v[160:163], v[200:203], 0
	v_mfma_f32_16x16x32_bf16 v[48:51], v[184:187], v[200:203], 0
	v_mfma_f32_16x16x32_bf16 v[44:47], v[160:163], v[208:211], 0
	v_mfma_f32_16x16x32_bf16 v[40:43], v[184:187], v[208:211], 0
	v_mfma_f32_16x16x32_bf16 v[36:39], v[160:163], v[216:219], 0
	v_mfma_f32_16x16x32_bf16 v[32:35], v[184:187], v[216:219], 0
	v_mfma_f32_16x16x32_bf16 v[68:71], v[164:167], v[196:199], v[68:71]
	v_mfma_f32_16x16x32_bf16 v[60:63], v[188:191], v[196:199], v[60:63]
	v_mfma_f32_16x16x32_bf16 v[52:55], v[164:167], v[204:207], v[52:55]
	v_mfma_f32_16x16x32_bf16 v[48:51], v[188:191], v[204:207], v[48:51]
	v_mfma_f32_16x16x32_bf16 v[44:47], v[164:167], v[212:215], v[44:47]
	v_mfma_f32_16x16x32_bf16 v[40:43], v[188:191], v[212:215], v[40:43]
	v_mfma_f32_16x16x32_bf16 v[36:39], v[164:167], v[228:231], v[36:39]
	v_mfma_f32_16x16x32_bf16 v[32:35], v[188:191], v[228:231], v[32:35]
	s_barrier
	s_setprio 0
	s_add_i32 s0, s0, s55
	v_lshl_add_u64 v[146:147], s[50:51], 0, v[170:171]
	s_mov_b32 m0, s0
	ds_read_b128 v[192:195], v151 offset:16384
	ds_read_b128 v[196:199], v151 offset:17408
	ds_read_b128 v[200:203], v151 offset:18432
	ds_read_b128 v[204:207], v151 offset:19456
	ds_read_b128 v[208:211], v151 offset:20480
	ds_read_b128 v[212:215], v151 offset:21504
	ds_read_b128 v[216:219], v151 offset:22528
	ds_read_b128 v[228:231], v151 offset:23552
	global_load_lds_dwordx4 v[146:147], off
	s_add_i32 m0, s0, 0x2000
	s_add_u32 s0, s50, 0x40000
	v_lshl_add_u64 v[232:233], s[50:51], 0, v[140:141]
	s_addc_u32 s1, s51, 0
	s_add_i32 s12, s12, s55
	global_load_lds_dwordx4 v[232:233], off
	s_mov_b32 m0, s12
	v_lshl_add_u64 v[236:237], s[52:53], 0, v[138:139]
	global_load_lds_dwordx4 v170, s[0:1]
	s_add_i32 m0, s12, 0x2000
	s_nop 0
	global_load_lds_dwordx4 v140, s[0:1]
	v_lshl_add_u64 v[234:235], s[52:53], 0, v[136:137]
	s_nop 0
	s_waitcnt lgkmcnt(0)
	s_barrier
	s_setprio 1
	v_mfma_f32_16x16x32_bf16 v[92:95], v[128:131], v[192:195], 0
	v_mfma_f32_16x16x32_bf16 v[88:91], v[152:155], v[192:195], 0
	v_mfma_f32_16x16x32_bf16 v[84:87], v[128:131], v[200:203], 0
	v_mfma_f32_16x16x32_bf16 v[80:83], v[152:155], v[200:203], 0
	v_mfma_f32_16x16x32_bf16 v[76:79], v[128:131], v[208:211], 0
	v_mfma_f32_16x16x32_bf16 v[72:75], v[152:155], v[208:211], 0
	v_mfma_f32_16x16x32_bf16 v[64:67], v[128:131], v[216:219], 0
	v_mfma_f32_16x16x32_bf16 v[56:59], v[152:155], v[216:219], 0
	v_mfma_f32_16x16x32_bf16 v[92:95], v[132:135], v[196:199], v[92:95]
	v_mfma_f32_16x16x32_bf16 v[88:91], v[156:159], v[196:199], v[88:91]
	v_mfma_f32_16x16x32_bf16 v[84:87], v[132:135], v[204:207], v[84:87]
	v_mfma_f32_16x16x32_bf16 v[80:83], v[156:159], v[204:207], v[80:83]
	v_mfma_f32_16x16x32_bf16 v[76:79], v[132:135], v[212:215], v[76:79]
	v_mfma_f32_16x16x32_bf16 v[72:75], v[156:159], v[212:215], v[72:75]
	v_mfma_f32_16x16x32_bf16 v[64:67], v[132:135], v[228:231], v[64:67]
	v_mfma_f32_16x16x32_bf16 v[56:59], v[156:159], v[228:231], v[56:59]
	v_mfma_f32_16x16x32_bf16 v[28:31], v[160:163], v[192:195], 0
	v_mfma_f32_16x16x32_bf16 v[24:27], v[184:187], v[192:195], 0
	v_mfma_f32_16x16x32_bf16 v[20:23], v[160:163], v[200:203], 0
	v_mfma_f32_16x16x32_bf16 v[16:19], v[184:187], v[200:203], 0
	v_mfma_f32_16x16x32_bf16 v[12:15], v[160:163], v[208:211], 0
	v_mfma_f32_16x16x32_bf16 v[8:11], v[184:187], v[208:211], 0
	v_mfma_f32_16x16x32_bf16 v[4:7], v[160:163], v[216:219], 0
	v_mfma_f32_16x16x32_bf16 v[0:3], v[184:187], v[216:219], 0
	v_mfma_f32_16x16x32_bf16 v[28:31], v[164:167], v[196:199], v[28:31]
	v_mfma_f32_16x16x32_bf16 v[24:27], v[188:191], v[196:199], v[24:27]
	v_mfma_f32_16x16x32_bf16 v[20:23], v[164:167], v[204:207], v[20:23]
	v_mfma_f32_16x16x32_bf16 v[16:19], v[188:191], v[204:207], v[16:19]
	v_mfma_f32_16x16x32_bf16 v[12:15], v[164:167], v[212:215], v[12:15]
	v_mfma_f32_16x16x32_bf16 v[8:11], v[188:191], v[212:215], v[8:11]
	v_mfma_f32_16x16x32_bf16 v[4:7], v[164:167], v[228:231], v[4:7]
	v_mfma_f32_16x16x32_bf16 v[0:3], v[188:191], v[228:231], v[0:3]
	s_barrier
	s_setprio 0
	s_add_i32 s12, 0, 0x18000
	s_add_i32 s13, 0, 0x1c000
	v_add_u32_e32 v156, s12, v149
	v_add_u32_e32 v188, s13, v149
	ds_read_b128 v[128:131], v156
	ds_read_b128 v[132:135], v156 offset:1024
	ds_read_b128 v[152:155], v156 offset:2048
	ds_read_b128 v[156:159], v156 offset:3072
	ds_read_b128 v[160:163], v188
	ds_read_b128 v[164:167], v188 offset:1024
	ds_read_b128 v[184:187], v188 offset:2048
	ds_read_b128 v[188:191], v188 offset:3072
	s_add_u32 s0, s52, 0x40000
	s_addc_u32 s1, s53, 0
	s_mov_b32 m0, s57
	ds_read_b128 v[192:195], v151 offset:32768
	ds_read_b128 v[196:199], v151 offset:33792
	ds_read_b128 v[200:203], v151 offset:34816
	ds_read_b128 v[204:207], v151 offset:35840
	ds_read_b128 v[208:211], v151 offset:36864
	ds_read_b128 v[212:215], v151 offset:37888
	ds_read_b128 v[216:219], v151 offset:38912
	ds_read_b128 v[228:231], v151 offset:39936
	global_load_lds_dwordx4 v136, s[0:1]
	s_mov_b32 m0, s58
	s_nop 0
	global_load_lds_dwordx4 v138, s[0:1]
	s_mov_b32 m0, s45
	s_nop 0
	global_load_lds_dwordx4 v[234:235], off
	s_mov_b32 m0, s56
	s_nop 0
	global_load_lds_dwordx4 v[236:237], off
	s_waitcnt vmcnt(8)
	s_waitcnt lgkmcnt(0)
	s_barrier
	s_setprio 1
	v_mfma_f32_16x16x32_bf16 v[124:127], v[128:131], v[192:195], v[124:127]
	v_mfma_f32_16x16x32_bf16 v[120:123], v[152:155], v[192:195], v[120:123]
	v_mfma_f32_16x16x32_bf16 v[116:119], v[128:131], v[200:203], v[116:119]
	v_mfma_f32_16x16x32_bf16 v[112:115], v[152:155], v[200:203], v[112:115]
	v_mfma_f32_16x16x32_bf16 v[108:111], v[128:131], v[208:211], v[108:111]
	v_mfma_f32_16x16x32_bf16 v[104:107], v[152:155], v[208:211], v[104:107]
	v_mfma_f32_16x16x32_bf16 v[100:103], v[128:131], v[216:219], v[100:103]
	v_mfma_f32_16x16x32_bf16 v[96:99], v[152:155], v[216:219], v[96:99]
	v_mfma_f32_16x16x32_bf16 v[124:127], v[132:135], v[196:199], v[124:127]
	v_mfma_f32_16x16x32_bf16 v[120:123], v[156:159], v[196:199], v[120:123]
	v_mfma_f32_16x16x32_bf16 v[116:119], v[132:135], v[204:207], v[116:119]
	v_mfma_f32_16x16x32_bf16 v[112:115], v[156:159], v[204:207], v[112:115]
	v_mfma_f32_16x16x32_bf16 v[108:111], v[132:135], v[212:215], v[108:111]
	v_mfma_f32_16x16x32_bf16 v[104:107], v[156:159], v[212:215], v[104:107]
	v_mfma_f32_16x16x32_bf16 v[100:103], v[132:135], v[228:231], v[100:103]
	v_mfma_f32_16x16x32_bf16 v[96:99], v[156:159], v[228:231], v[96:99]
	v_mfma_f32_16x16x32_bf16 v[68:71], v[160:163], v[192:195], v[68:71]
	v_mfma_f32_16x16x32_bf16 v[60:63], v[184:187], v[192:195], v[60:63]
	v_mfma_f32_16x16x32_bf16 v[52:55], v[160:163], v[200:203], v[52:55]
	v_mfma_f32_16x16x32_bf16 v[48:51], v[184:187], v[200:203], v[48:51]
	v_mfma_f32_16x16x32_bf16 v[44:47], v[160:163], v[208:211], v[44:47]
	v_mfma_f32_16x16x32_bf16 v[40:43], v[184:187], v[208:211], v[40:43]
	v_mfma_f32_16x16x32_bf16 v[36:39], v[160:163], v[216:219], v[36:39]
	v_mfma_f32_16x16x32_bf16 v[32:35], v[184:187], v[216:219], v[32:35]
	v_mfma_f32_16x16x32_bf16 v[68:71], v[164:167], v[196:199], v[68:71]
	v_mfma_f32_16x16x32_bf16 v[60:63], v[188:191], v[196:199], v[60:63]
	v_mfma_f32_16x16x32_bf16 v[52:55], v[164:167], v[204:207], v[52:55]
	v_mfma_f32_16x16x32_bf16 v[48:51], v[188:191], v[204:207], v[48:51]
	v_mfma_f32_16x16x32_bf16 v[44:47], v[164:167], v[212:215], v[44:47]
	v_mfma_f32_16x16x32_bf16 v[40:43], v[188:191], v[212:215], v[40:43]
	v_mfma_f32_16x16x32_bf16 v[36:39], v[164:167], v[228:231], v[36:39]
	v_mfma_f32_16x16x32_bf16 v[32:35], v[188:191], v[228:231], v[32:35]
	s_barrier
	s_setprio 0
	s_add_i32 s0, s12, s55
	v_lshl_add_u64 v[146:147], v[146:147], 0, s[16:17]
	s_mov_b32 m0, s0
	ds_read_b128 v[192:195], v151 offset:49152
	ds_read_b128 v[196:199], v151 offset:50176
	ds_read_b128 v[200:203], v151 offset:51200
	ds_read_b128 v[204:207], v151 offset:52224
	ds_read_b128 v[208:211], v151 offset:53248
	ds_read_b128 v[212:215], v151 offset:54272
	ds_read_b128 v[216:219], v151 offset:55296
	ds_read_b128 v[228:231], v151 offset:56320
	global_load_lds_dwordx4 v[146:147], off
	s_add_i32 m0, s0, 0x2000
	s_add_u32 s0, s50, 0x40080
	v_lshl_add_u64 v[146:147], v[232:233], 0, s[16:17]
	s_addc_u32 s1, s51, 0
	s_add_i32 s12, s13, s55
	global_load_lds_dwordx4 v[146:147], off
	s_mov_b32 m0, s12
	s_nop 0
	global_load_lds_dwordx4 v170, s[0:1]
	s_add_i32 m0, s12, 0x2000
	s_nop 0
	global_load_lds_dwordx4 v140, s[0:1]
	v_lshl_add_u64 v[146:147], v[234:235], 0, s[16:17]
	s_mov_b32 m0, s59
	s_nop 0
	global_load_lds_dwordx4 v[146:147], off
	v_lshl_add_u64 v[146:147], v[236:237], 0, s[16:17]
	s_mov_b32 m0, s60
	s_nop 0
	global_load_lds_dwordx4 v[146:147], off
	s_waitcnt vmcnt(6)
	s_waitcnt lgkmcnt(0)
	s_barrier
	s_setprio 1
	v_mfma_f32_16x16x32_bf16 v[92:95], v[128:131], v[192:195], v[92:95]
	v_mfma_f32_16x16x32_bf16 v[88:91], v[152:155], v[192:195], v[88:91]
	v_mfma_f32_16x16x32_bf16 v[84:87], v[128:131], v[200:203], v[84:87]
	v_mfma_f32_16x16x32_bf16 v[80:83], v[152:155], v[200:203], v[80:83]
	v_mfma_f32_16x16x32_bf16 v[76:79], v[128:131], v[208:211], v[76:79]
	v_mfma_f32_16x16x32_bf16 v[72:75], v[152:155], v[208:211], v[72:75]
	v_mfma_f32_16x16x32_bf16 v[64:67], v[128:131], v[216:219], v[64:67]
	v_mfma_f32_16x16x32_bf16 v[56:59], v[152:155], v[216:219], v[56:59]
	v_mfma_f32_16x16x32_bf16 v[92:95], v[132:135], v[196:199], v[92:95]
	v_mfma_f32_16x16x32_bf16 v[88:91], v[156:159], v[196:199], v[88:91]
	v_mfma_f32_16x16x32_bf16 v[84:87], v[132:135], v[204:207], v[84:87]
	v_mfma_f32_16x16x32_bf16 v[80:83], v[156:159], v[204:207], v[80:83]
	v_mfma_f32_16x16x32_bf16 v[76:79], v[132:135], v[212:215], v[76:79]
	v_mfma_f32_16x16x32_bf16 v[72:75], v[156:159], v[212:215], v[72:75]
	v_mfma_f32_16x16x32_bf16 v[64:67], v[132:135], v[228:231], v[64:67]
	v_mfma_f32_16x16x32_bf16 v[56:59], v[156:159], v[228:231], v[56:59]
	v_mfma_f32_16x16x32_bf16 v[28:31], v[160:163], v[192:195], v[28:31]
	v_mfma_f32_16x16x32_bf16 v[24:27], v[184:187], v[192:195], v[24:27]
	v_mfma_f32_16x16x32_bf16 v[20:23], v[160:163], v[200:203], v[20:23]
	v_mfma_f32_16x16x32_bf16 v[16:19], v[184:187], v[200:203], v[16:19]
	v_mfma_f32_16x16x32_bf16 v[12:15], v[160:163], v[208:211], v[12:15]
	v_mfma_f32_16x16x32_bf16 v[8:11], v[184:187], v[208:211], v[8:11]
	v_mfma_f32_16x16x32_bf16 v[4:7], v[160:163], v[216:219], v[4:7]
	v_mfma_f32_16x16x32_bf16 v[0:3], v[184:187], v[216:219], v[0:3]
	v_mfma_f32_16x16x32_bf16 v[28:31], v[164:167], v[196:199], v[28:31]
	v_mfma_f32_16x16x32_bf16 v[24:27], v[188:191], v[196:199], v[24:27]
	v_mfma_f32_16x16x32_bf16 v[20:23], v[164:167], v[204:207], v[20:23]
	v_mfma_f32_16x16x32_bf16 v[16:19], v[188:191], v[204:207], v[16:19]
	v_mfma_f32_16x16x32_bf16 v[12:15], v[164:167], v[212:215], v[12:15]
	v_mfma_f32_16x16x32_bf16 v[8:11], v[188:191], v[212:215], v[8:11]
	v_mfma_f32_16x16x32_bf16 v[4:7], v[164:167], v[228:231], v[4:7]
	v_mfma_f32_16x16x32_bf16 v[0:3], v[188:191], v[228:231], v[0:3]
	s_barrier
	s_setprio 0
	s_add_i32 s66, s66, 2
	s_add_u32 s64, s64, 0x100
	s_addc_u32 s65, s65, 0
	s_cmp_gt_u32 s66, 13
	s_mov_b64 s[46:47], s[48:49]
.LBB0_601:
	s_add_u32 s48, s46, 0x100
	s_addc_u32 s49, s47, 0
	s_add_i32 s0, 0, 0x10000
	s_cmp_eq_u32 s66, 12
	s_cselect_b32 s53, s37, s49
	s_cselect_b32 s52, s62, s48
	v_add_u32_e32 v146, s0, v149
	s_cselect_b32 s51, s35, s65
	s_cselect_b32 s50, s63, s64
	s_add_i32 s12, 0, 0x14000
	ds_read_b128 v[128:131], v146
	ds_read_b128 v[132:135], v146 offset:1024
	ds_read_b128 v[152:155], v146 offset:2048
	ds_read_b128 v[156:159], v146 offset:3072
	v_add_u32_e32 v146, s12, v149
	ds_read_b128 v[160:163], v146
	ds_read_b128 v[164:167], v146 offset:1024
	ds_read_b128 v[184:187], v146 offset:2048
	ds_read_b128 v[188:191], v146 offset:3072
	s_add_i32 m0, s45, 0xc000
	ds_read_b128 v[192:195], v151
	ds_read_b128 v[196:199], v151 offset:1024
	ds_read_b128 v[200:203], v151 offset:2048
	ds_read_b128 v[204:207], v151 offset:3072
	ds_read_b128 v[208:211], v151 offset:4096
	ds_read_b128 v[212:215], v151 offset:5120
	ds_read_b128 v[216:219], v151 offset:6144
	ds_read_b128 v[228:231], v151 offset:7168
	global_load_lds_dwordx4 v142, s[46:47]
	s_add_i32 m0, s45, 0xe000
	s_nop 0
	global_load_lds_dwordx4 v144, s[46:47]
	s_waitcnt vmcnt(8)
	s_waitcnt lgkmcnt(0)
	s_barrier
	s_setprio 1
	v_mfma_f32_16x16x32_bf16 v[124:127], v[128:131], v[192:195], v[124:127]
	v_mfma_f32_16x16x32_bf16 v[120:123], v[152:155], v[192:195], v[120:123]
	v_mfma_f32_16x16x32_bf16 v[116:119], v[128:131], v[200:203], v[116:119]
	v_mfma_f32_16x16x32_bf16 v[112:115], v[152:155], v[200:203], v[112:115]
	v_mfma_f32_16x16x32_bf16 v[108:111], v[128:131], v[208:211], v[108:111]
	v_mfma_f32_16x16x32_bf16 v[104:107], v[152:155], v[208:211], v[104:107]
	v_mfma_f32_16x16x32_bf16 v[100:103], v[128:131], v[216:219], v[100:103]
	v_mfma_f32_16x16x32_bf16 v[96:99], v[152:155], v[216:219], v[96:99]
	v_mfma_f32_16x16x32_bf16 v[124:127], v[132:135], v[196:199], v[124:127]
	v_mfma_f32_16x16x32_bf16 v[120:123], v[156:159], v[196:199], v[120:123]
	v_mfma_f32_16x16x32_bf16 v[116:119], v[132:135], v[204:207], v[116:119]
	v_mfma_f32_16x16x32_bf16 v[112:115], v[156:159], v[204:207], v[112:115]
	v_mfma_f32_16x16x32_bf16 v[108:111], v[132:135], v[212:215], v[108:111]
	v_mfma_f32_16x16x32_bf16 v[104:107], v[156:159], v[212:215], v[104:107]
	v_mfma_f32_16x16x32_bf16 v[100:103], v[132:135], v[228:231], v[100:103]
	v_mfma_f32_16x16x32_bf16 v[96:99], v[156:159], v[228:231], v[96:99]
	v_mfma_f32_16x16x32_bf16 v[68:71], v[160:163], v[192:195], v[68:71]
	v_mfma_f32_16x16x32_bf16 v[60:63], v[184:187], v[192:195], v[60:63]
	v_mfma_f32_16x16x32_bf16 v[52:55], v[160:163], v[200:203], v[52:55]
	v_mfma_f32_16x16x32_bf16 v[48:51], v[184:187], v[200:203], v[48:51]
	v_mfma_f32_16x16x32_bf16 v[44:47], v[160:163], v[208:211], v[44:47]
	v_mfma_f32_16x16x32_bf16 v[40:43], v[184:187], v[208:211], v[40:43]
	v_mfma_f32_16x16x32_bf16 v[36:39], v[160:163], v[216:219], v[36:39]
	v_mfma_f32_16x16x32_bf16 v[32:35], v[184:187], v[216:219], v[32:35]
	v_mfma_f32_16x16x32_bf16 v[68:71], v[164:167], v[196:199], v[68:71]
	v_mfma_f32_16x16x32_bf16 v[60:63], v[188:191], v[196:199], v[60:63]
	v_mfma_f32_16x16x32_bf16 v[52:55], v[164:167], v[204:207], v[52:55]
	v_mfma_f32_16x16x32_bf16 v[48:51], v[188:191], v[204:207], v[48:51]
	v_mfma_f32_16x16x32_bf16 v[44:47], v[164:167], v[212:215], v[44:47]
	v_mfma_f32_16x16x32_bf16 v[40:43], v[188:191], v[212:215], v[40:43]
	v_mfma_f32_16x16x32_bf16 v[36:39], v[164:167], v[228:231], v[36:39]
	v_mfma_f32_16x16x32_bf16 v[32:35], v[188:191], v[228:231], v[32:35]
	s_barrier
	s_setprio 0
	s_add_i32 s0, s0, s55
	v_lshl_add_u64 v[146:147], s[50:51], 0, v[170:171]
	s_mov_b32 m0, s0
	ds_read_b128 v[192:195], v151 offset:16384
	ds_read_b128 v[196:199], v151 offset:17408
	ds_read_b128 v[200:203], v151 offset:18432
	ds_read_b128 v[204:207], v151 offset:19456
	ds_read_b128 v[208:211], v151 offset:20480
	ds_read_b128 v[212:215], v151 offset:21504
	ds_read_b128 v[216:219], v151 offset:22528
	ds_read_b128 v[228:231], v151 offset:23552
	global_load_lds_dwordx4 v[146:147], off
	s_add_i32 m0, s0, 0x2000
	s_add_u32 s0, s50, 0x40000
	v_lshl_add_u64 v[232:233], s[50:51], 0, v[140:141]
	s_addc_u32 s1, s51, 0
	s_add_i32 s12, s12, s55
	global_load_lds_dwordx4 v[232:233], off
	s_mov_b32 m0, s12
	v_lshl_add_u64 v[236:237], s[52:53], 0, v[138:139]
	global_load_lds_dwordx4 v170, s[0:1]
	s_add_i32 m0, s12, 0x2000
	s_nop 0
	global_load_lds_dwordx4 v140, s[0:1]
	v_lshl_add_u64 v[234:235], s[52:53], 0, v[136:137]
	s_waitcnt vmcnt(6)
	s_waitcnt lgkmcnt(0)
	s_barrier
	s_setprio 1
	v_mfma_f32_16x16x32_bf16 v[92:95], v[128:131], v[192:195], v[92:95]
	v_mfma_f32_16x16x32_bf16 v[88:91], v[152:155], v[192:195], v[88:91]
	v_mfma_f32_16x16x32_bf16 v[84:87], v[128:131], v[200:203], v[84:87]
	v_mfma_f32_16x16x32_bf16 v[80:83], v[152:155], v[200:203], v[80:83]
	v_mfma_f32_16x16x32_bf16 v[76:79], v[128:131], v[208:211], v[76:79]
	v_mfma_f32_16x16x32_bf16 v[72:75], v[152:155], v[208:211], v[72:75]
	v_mfma_f32_16x16x32_bf16 v[64:67], v[128:131], v[216:219], v[64:67]
	v_mfma_f32_16x16x32_bf16 v[56:59], v[152:155], v[216:219], v[56:59]
	v_mfma_f32_16x16x32_bf16 v[92:95], v[132:135], v[196:199], v[92:95]
	v_mfma_f32_16x16x32_bf16 v[88:91], v[156:159], v[196:199], v[88:91]
	v_mfma_f32_16x16x32_bf16 v[84:87], v[132:135], v[204:207], v[84:87]
	v_mfma_f32_16x16x32_bf16 v[80:83], v[156:159], v[204:207], v[80:83]
	v_mfma_f32_16x16x32_bf16 v[76:79], v[132:135], v[212:215], v[76:79]
	v_mfma_f32_16x16x32_bf16 v[72:75], v[156:159], v[212:215], v[72:75]
	v_mfma_f32_16x16x32_bf16 v[64:67], v[132:135], v[228:231], v[64:67]
	v_mfma_f32_16x16x32_bf16 v[56:59], v[156:159], v[228:231], v[56:59]
	v_mfma_f32_16x16x32_bf16 v[28:31], v[160:163], v[192:195], v[28:31]
	v_mfma_f32_16x16x32_bf16 v[24:27], v[184:187], v[192:195], v[24:27]
	v_mfma_f32_16x16x32_bf16 v[20:23], v[160:163], v[200:203], v[20:23]
	v_mfma_f32_16x16x32_bf16 v[16:19], v[184:187], v[200:203], v[16:19]
	v_mfma_f32_16x16x32_bf16 v[12:15], v[160:163], v[208:211], v[12:15]
	v_mfma_f32_16x16x32_bf16 v[8:11], v[184:187], v[208:211], v[8:11]
	v_mfma_f32_16x16x32_bf16 v[4:7], v[160:163], v[216:219], v[4:7]
	v_mfma_f32_16x16x32_bf16 v[0:3], v[184:187], v[216:219], v[0:3]
	v_mfma_f32_16x16x32_bf16 v[28:31], v[164:167], v[196:199], v[28:31]
	v_mfma_f32_16x16x32_bf16 v[24:27], v[188:191], v[196:199], v[24:27]
	v_mfma_f32_16x16x32_bf16 v[20:23], v[164:167], v[204:207], v[20:23]
	v_mfma_f32_16x16x32_bf16 v[16:19], v[188:191], v[204:207], v[16:19]
	v_mfma_f32_16x16x32_bf16 v[12:15], v[164:167], v[212:215], v[12:15]
	v_mfma_f32_16x16x32_bf16 v[8:11], v[188:191], v[212:215], v[8:11]
	v_mfma_f32_16x16x32_bf16 v[4:7], v[164:167], v[228:231], v[4:7]
	v_mfma_f32_16x16x32_bf16 v[0:3], v[188:191], v[228:231], v[0:3]
	s_barrier
	s_setprio 0
	s_add_i32 s12, 0, 0x18000
	s_add_i32 s13, 0, 0x1c000
	v_add_u32_e32 v156, s12, v149
	v_add_u32_e32 v188, s13, v149
	ds_read_b128 v[128:131], v156
	ds_read_b128 v[132:135], v156 offset:1024
	ds_read_b128 v[152:155], v156 offset:2048
	ds_read_b128 v[156:159], v156 offset:3072
	ds_read_b128 v[160:163], v188
	ds_read_b128 v[164:167], v188 offset:1024
	ds_read_b128 v[184:187], v188 offset:2048
	ds_read_b128 v[188:191], v188 offset:3072
	s_add_u32 s0, s52, 0x40000
	s_addc_u32 s1, s53, 0
	s_mov_b32 m0, s57
	ds_read_b128 v[192:195], v151 offset:32768
	ds_read_b128 v[196:199], v151 offset:33792
	ds_read_b128 v[200:203], v151 offset:34816
	ds_read_b128 v[204:207], v151 offset:35840
	ds_read_b128 v[208:211], v151 offset:36864
	ds_read_b128 v[212:215], v151 offset:37888
	ds_read_b128 v[216:219], v151 offset:38912
	ds_read_b128 v[228:231], v151 offset:39936
	global_load_lds_dwordx4 v136, s[0:1]
	s_mov_b32 m0, s58
	s_nop 0
	global_load_lds_dwordx4 v138, s[0:1]
	s_mov_b32 m0, s45
	s_nop 0
	global_load_lds_dwordx4 v[234:235], off
	s_mov_b32 m0, s56
	s_nop 0
	global_load_lds_dwordx4 v[236:237], off
	s_waitcnt vmcnt(8)
	s_waitcnt lgkmcnt(0)
	s_barrier
	s_setprio 1
	v_mfma_f32_16x16x32_bf16 v[124:127], v[128:131], v[192:195], v[124:127]
	v_mfma_f32_16x16x32_bf16 v[120:123], v[152:155], v[192:195], v[120:123]
	v_mfma_f32_16x16x32_bf16 v[116:119], v[128:131], v[200:203], v[116:119]
	v_mfma_f32_16x16x32_bf16 v[112:115], v[152:155], v[200:203], v[112:115]
	v_mfma_f32_16x16x32_bf16 v[108:111], v[128:131], v[208:211], v[108:111]
	v_mfma_f32_16x16x32_bf16 v[104:107], v[152:155], v[208:211], v[104:107]
	v_mfma_f32_16x16x32_bf16 v[100:103], v[128:131], v[216:219], v[100:103]
	v_mfma_f32_16x16x32_bf16 v[96:99], v[152:155], v[216:219], v[96:99]
	v_mfma_f32_16x16x32_bf16 v[124:127], v[132:135], v[196:199], v[124:127]
	v_mfma_f32_16x16x32_bf16 v[120:123], v[156:159], v[196:199], v[120:123]
	v_mfma_f32_16x16x32_bf16 v[116:119], v[132:135], v[204:207], v[116:119]
	v_mfma_f32_16x16x32_bf16 v[112:115], v[156:159], v[204:207], v[112:115]
	v_mfma_f32_16x16x32_bf16 v[108:111], v[132:135], v[212:215], v[108:111]
	v_mfma_f32_16x16x32_bf16 v[104:107], v[156:159], v[212:215], v[104:107]
	v_mfma_f32_16x16x32_bf16 v[100:103], v[132:135], v[228:231], v[100:103]
	v_mfma_f32_16x16x32_bf16 v[96:99], v[156:159], v[228:231], v[96:99]
	v_mfma_f32_16x16x32_bf16 v[68:71], v[160:163], v[192:195], v[68:71]
	v_mfma_f32_16x16x32_bf16 v[60:63], v[184:187], v[192:195], v[60:63]
	v_mfma_f32_16x16x32_bf16 v[52:55], v[160:163], v[200:203], v[52:55]
	v_mfma_f32_16x16x32_bf16 v[48:51], v[184:187], v[200:203], v[48:51]
	v_mfma_f32_16x16x32_bf16 v[44:47], v[160:163], v[208:211], v[44:47]
	v_mfma_f32_16x16x32_bf16 v[40:43], v[184:187], v[208:211], v[40:43]
	v_mfma_f32_16x16x32_bf16 v[36:39], v[160:163], v[216:219], v[36:39]
	v_mfma_f32_16x16x32_bf16 v[32:35], v[184:187], v[216:219], v[32:35]
	v_mfma_f32_16x16x32_bf16 v[68:71], v[164:167], v[196:199], v[68:71]
	v_mfma_f32_16x16x32_bf16 v[60:63], v[188:191], v[196:199], v[60:63]
	v_mfma_f32_16x16x32_bf16 v[52:55], v[164:167], v[204:207], v[52:55]
	v_mfma_f32_16x16x32_bf16 v[48:51], v[188:191], v[204:207], v[48:51]
	v_mfma_f32_16x16x32_bf16 v[44:47], v[164:167], v[212:215], v[44:47]
	v_mfma_f32_16x16x32_bf16 v[40:43], v[188:191], v[212:215], v[40:43]
	v_mfma_f32_16x16x32_bf16 v[36:39], v[164:167], v[228:231], v[36:39]
	v_mfma_f32_16x16x32_bf16 v[32:35], v[188:191], v[228:231], v[32:35]
	s_barrier
	s_setprio 0
	s_add_i32 s0, s12, s55
	v_lshl_add_u64 v[146:147], v[146:147], 0, s[16:17]
	s_mov_b32 m0, s0
	ds_read_b128 v[192:195], v151 offset:49152
	ds_read_b128 v[196:199], v151 offset:50176
	ds_read_b128 v[200:203], v151 offset:51200
	ds_read_b128 v[204:207], v151 offset:52224
	ds_read_b128 v[208:211], v151 offset:53248
	ds_read_b128 v[212:215], v151 offset:54272
	ds_read_b128 v[216:219], v151 offset:55296
	ds_read_b128 v[228:231], v151 offset:56320
	global_load_lds_dwordx4 v[146:147], off
	s_add_i32 m0, s0, 0x2000
	s_add_u32 s0, s50, 0x40080
	v_lshl_add_u64 v[146:147], v[232:233], 0, s[16:17]
	s_addc_u32 s1, s51, 0
	s_add_i32 s12, s13, s55
	global_load_lds_dwordx4 v[146:147], off
	s_mov_b32 m0, s12
	s_nop 0
	global_load_lds_dwordx4 v170, s[0:1]
	s_add_i32 m0, s12, 0x2000
	s_nop 0
	global_load_lds_dwordx4 v140, s[0:1]
	v_lshl_add_u64 v[146:147], v[234:235], 0, s[16:17]
	s_mov_b32 m0, s59
	s_nop 0
	global_load_lds_dwordx4 v[146:147], off
	v_lshl_add_u64 v[146:147], v[236:237], 0, s[16:17]
	s_mov_b32 m0, s60
	s_nop 0
	global_load_lds_dwordx4 v[146:147], off
	s_waitcnt vmcnt(6)
	s_waitcnt lgkmcnt(0)
	s_barrier
	s_setprio 1
	v_mfma_f32_16x16x32_bf16 v[92:95], v[128:131], v[192:195], v[92:95]
	v_mfma_f32_16x16x32_bf16 v[88:91], v[152:155], v[192:195], v[88:91]
	v_mfma_f32_16x16x32_bf16 v[84:87], v[128:131], v[200:203], v[84:87]
	v_mfma_f32_16x16x32_bf16 v[80:83], v[152:155], v[200:203], v[80:83]
	v_mfma_f32_16x16x32_bf16 v[76:79], v[128:131], v[208:211], v[76:79]
	v_mfma_f32_16x16x32_bf16 v[72:75], v[152:155], v[208:211], v[72:75]
	v_mfma_f32_16x16x32_bf16 v[64:67], v[128:131], v[216:219], v[64:67]
	v_mfma_f32_16x16x32_bf16 v[56:59], v[152:155], v[216:219], v[56:59]
	v_mfma_f32_16x16x32_bf16 v[92:95], v[132:135], v[196:199], v[92:95]
	v_mfma_f32_16x16x32_bf16 v[88:91], v[156:159], v[196:199], v[88:91]
	v_mfma_f32_16x16x32_bf16 v[84:87], v[132:135], v[204:207], v[84:87]
	v_mfma_f32_16x16x32_bf16 v[80:83], v[156:159], v[204:207], v[80:83]
	v_mfma_f32_16x16x32_bf16 v[76:79], v[132:135], v[212:215], v[76:79]
	v_mfma_f32_16x16x32_bf16 v[72:75], v[156:159], v[212:215], v[72:75]
	v_mfma_f32_16x16x32_bf16 v[64:67], v[132:135], v[228:231], v[64:67]
	v_mfma_f32_16x16x32_bf16 v[56:59], v[156:159], v[228:231], v[56:59]
	v_mfma_f32_16x16x32_bf16 v[28:31], v[160:163], v[192:195], v[28:31]
	v_mfma_f32_16x16x32_bf16 v[24:27], v[184:187], v[192:195], v[24:27]
	v_mfma_f32_16x16x32_bf16 v[20:23], v[160:163], v[200:203], v[20:23]
	v_mfma_f32_16x16x32_bf16 v[16:19], v[184:187], v[200:203], v[16:19]
	v_mfma_f32_16x16x32_bf16 v[12:15], v[160:163], v[208:211], v[12:15]
	v_mfma_f32_16x16x32_bf16 v[8:11], v[184:187], v[208:211], v[8:11]
	v_mfma_f32_16x16x32_bf16 v[4:7], v[160:163], v[216:219], v[4:7]
	v_mfma_f32_16x16x32_bf16 v[0:3], v[184:187], v[216:219], v[0:3]
	v_mfma_f32_16x16x32_bf16 v[28:31], v[164:167], v[196:199], v[28:31]
	v_mfma_f32_16x16x32_bf16 v[24:27], v[188:191], v[196:199], v[24:27]
	v_mfma_f32_16x16x32_bf16 v[20:23], v[164:167], v[204:207], v[20:23]
	v_mfma_f32_16x16x32_bf16 v[16:19], v[188:191], v[204:207], v[16:19]
	v_mfma_f32_16x16x32_bf16 v[12:15], v[164:167], v[212:215], v[12:15]
	v_mfma_f32_16x16x32_bf16 v[8:11], v[188:191], v[212:215], v[8:11]
	v_mfma_f32_16x16x32_bf16 v[4:7], v[164:167], v[228:231], v[4:7]
	v_mfma_f32_16x16x32_bf16 v[0:3], v[188:191], v[228:231], v[0:3]
	s_barrier
	s_setprio 0
	s_add_i32 s66, s66, 2
	s_add_u32 s64, s64, 0x100
	s_addc_u32 s65, s65, 0
	s_cmp_gt_u32 s66, 13
	s_mov_b64 s[46:47], s[48:49]
	s_cbranch_scc0 .LBB0_601
	s_and_b64 vcc, exec, s[30:31]
	s_cbranch_vccz .LBB0_604
	s_barrier

.Lrestag_776:
	s_add_u32 s50, s48, 0x100
	s_addc_u32 s51, s49, 0
	s_add_i32 s0, 0, 0x10000
	s_cmp_eq_u32 s66, 12
	s_cselect_b32 s55, s37, s51
	s_cselect_b32 s54, s45, s50
	s_cselect_b32 s53, s35, s65
	s_cselect_b32 s52, s63, s64
	s_add_i32 s12, 0, 0x14000
	v_add_u32_e32 v140, s0, v197
	v_add_u32_e32 v184, s12, v197
	ds_read_b128 v[128:131], v140
	ds_read_b128 v[132:135], v140 offset:1024
	ds_read_b128 v[136:139], v140 offset:2048
	ds_read_b128 v[140:143], v140 offset:3072
	ds_read_b128 v[144:147], v184
	ds_read_b128 v[148:151], v184 offset:1024
	ds_read_b128 v[164:167], v184 offset:2048
	ds_read_b128 v[184:187], v184 offset:3072
	s_add_i32 m0, s47, 0xc000
	ds_read_b128 v[188:191], v198
	ds_read_b128 v[192:195], v198 offset:1024
	ds_read_b128 v[200:203], v198 offset:2048
	ds_read_b128 v[204:207], v198 offset:3072
	ds_read_b128 v[208:211], v198 offset:4096
	ds_read_b128 v[212:215], v198 offset:5120
	ds_read_b128 v[216:219], v198 offset:6144
	ds_read_b128 v[228:231], v198 offset:7168
	global_load_lds_dwordx4 v160, s[48:49]
	s_add_i32 m0, s47, 0xe000
	s_nop 0
	global_load_lds_dwordx4 v162, s[48:49]
	s_nop 0
	s_waitcnt lgkmcnt(0)
	s_barrier
	s_setprio 1
	v_mfma_f32_16x16x32_bf16 v[124:127], v[128:131], v[188:191], 0
	v_mfma_f32_16x16x32_bf16 v[120:123], v[136:139], v[188:191], 0
	v_mfma_f32_16x16x32_bf16 v[108:111], v[128:131], v[200:203], 0
	v_mfma_f32_16x16x32_bf16 v[104:107], v[136:139], v[200:203], 0
	v_mfma_f32_16x16x32_bf16 v[92:95], v[128:131], v[208:211], 0
	v_mfma_f32_16x16x32_bf16 v[88:91], v[136:139], v[208:211], 0
	v_mfma_f32_16x16x32_bf16 v[76:79], v[128:131], v[216:219], 0
	v_mfma_f32_16x16x32_bf16 v[72:75], v[136:139], v[216:219], 0
	v_mfma_f32_16x16x32_bf16 v[124:127], v[132:135], v[192:195], v[124:127]
	v_mfma_f32_16x16x32_bf16 v[120:123], v[140:143], v[192:195], v[120:123]
	v_mfma_f32_16x16x32_bf16 v[108:111], v[132:135], v[204:207], v[108:111]
	v_mfma_f32_16x16x32_bf16 v[104:107], v[140:143], v[204:207], v[104:107]
	v_mfma_f32_16x16x32_bf16 v[92:95], v[132:135], v[212:215], v[92:95]
	v_mfma_f32_16x16x32_bf16 v[88:91], v[140:143], v[212:215], v[88:91]
	v_mfma_f32_16x16x32_bf16 v[76:79], v[132:135], v[228:231], v[76:79]
	v_mfma_f32_16x16x32_bf16 v[72:75], v[140:143], v[228:231], v[72:75]
	v_mfma_f32_16x16x32_bf16 v[116:119], v[144:147], v[188:191], 0
	v_mfma_f32_16x16x32_bf16 v[112:115], v[164:167], v[188:191], 0
	v_mfma_f32_16x16x32_bf16 v[100:103], v[144:147], v[200:203], 0
	v_mfma_f32_16x16x32_bf16 v[96:99], v[164:167], v[200:203], 0
	v_mfma_f32_16x16x32_bf16 v[84:87], v[144:147], v[208:211], 0
	v_mfma_f32_16x16x32_bf16 v[80:83], v[164:167], v[208:211], 0
	v_mfma_f32_16x16x32_bf16 v[68:71], v[144:147], v[216:219], 0
	v_mfma_f32_16x16x32_bf16 v[64:67], v[164:167], v[216:219], 0
	v_mfma_f32_16x16x32_bf16 v[116:119], v[148:151], v[192:195], v[116:119]
	v_mfma_f32_16x16x32_bf16 v[112:115], v[184:187], v[192:195], v[112:115]
	v_mfma_f32_16x16x32_bf16 v[100:103], v[148:151], v[204:207], v[100:103]
	v_mfma_f32_16x16x32_bf16 v[96:99], v[184:187], v[204:207], v[96:99]
	v_mfma_f32_16x16x32_bf16 v[84:87], v[148:151], v[212:215], v[84:87]
	v_mfma_f32_16x16x32_bf16 v[80:83], v[184:187], v[212:215], v[80:83]
	v_mfma_f32_16x16x32_bf16 v[68:71], v[148:151], v[228:231], v[68:71]
	v_mfma_f32_16x16x32_bf16 v[64:67], v[184:187], v[228:231], v[64:67]
	s_barrier
	s_setprio 0
	s_add_i32 s0, s0, s56
	v_lshl_add_u64 v[232:233], s[52:53], 0, v[170:171]
	s_mov_b32 m0, s0
	ds_read_b128 v[188:191], v198 offset:16384
	ds_read_b128 v[192:195], v198 offset:17408
	ds_read_b128 v[200:203], v198 offset:18432
	ds_read_b128 v[204:207], v198 offset:19456
	ds_read_b128 v[208:211], v198 offset:20480
	ds_read_b128 v[212:215], v198 offset:21504
	ds_read_b128 v[216:219], v198 offset:22528
	ds_read_b128 v[228:231], v198 offset:23552
	global_load_lds_dwordx4 v[232:233], off
	s_add_i32 m0, s0, 0x2000
	s_add_u32 s0, s52, 0x40000
	v_lshl_add_u64 v[234:235], s[52:53], 0, v[156:157]
	s_addc_u32 s1, s53, 0
	s_add_i32 s12, s12, s56
	global_load_lds_dwordx4 v[234:235], off
	s_mov_b32 m0, s12
	v_lshl_add_u64 v[238:239], s[54:55], 0, v[154:155]
	global_load_lds_dwordx4 v170, s[0:1]
	s_add_i32 m0, s12, 0x2000
	s_nop 0
	global_load_lds_dwordx4 v156, s[0:1]
	v_lshl_add_u64 v[236:237], s[54:55], 0, v[152:153]
	s_nop 0
	s_waitcnt lgkmcnt(0)
	s_barrier
	s_setprio 1
	v_mfma_f32_16x16x32_bf16 v[60:63], v[128:131], v[188:191], 0
	v_mfma_f32_16x16x32_bf16 v[56:59], v[136:139], v[188:191], 0
	v_mfma_f32_16x16x32_bf16 v[44:47], v[128:131], v[200:203], 0
	v_mfma_f32_16x16x32_bf16 v[40:43], v[136:139], v[200:203], 0
	v_mfma_f32_16x16x32_bf16 v[28:31], v[128:131], v[208:211], 0
	v_mfma_f32_16x16x32_bf16 v[24:27], v[136:139], v[208:211], 0
	v_mfma_f32_16x16x32_bf16 v[12:15], v[128:131], v[216:219], 0
	v_mfma_f32_16x16x32_bf16 v[8:11], v[136:139], v[216:219], 0
	v_mfma_f32_16x16x32_bf16 v[60:63], v[132:135], v[192:195], v[60:63]
	v_mfma_f32_16x16x32_bf16 v[56:59], v[140:143], v[192:195], v[56:59]
	v_mfma_f32_16x16x32_bf16 v[44:47], v[132:135], v[204:207], v[44:47]
	v_mfma_f32_16x16x32_bf16 v[40:43], v[140:143], v[204:207], v[40:43]
	v_mfma_f32_16x16x32_bf16 v[28:31], v[132:135], v[212:215], v[28:31]
	v_mfma_f32_16x16x32_bf16 v[24:27], v[140:143], v[212:215], v[24:27]
	v_mfma_f32_16x16x32_bf16 v[12:15], v[132:135], v[228:231], v[12:15]
	v_mfma_f32_16x16x32_bf16 v[8:11], v[140:143], v[228:231], v[8:11]
	v_mfma_f32_16x16x32_bf16 v[52:55], v[144:147], v[188:191], 0
	v_mfma_f32_16x16x32_bf16 v[48:51], v[164:167], v[188:191], 0
	v_mfma_f32_16x16x32_bf16 v[36:39], v[144:147], v[200:203], 0
	v_mfma_f32_16x16x32_bf16 v[32:35], v[164:167], v[200:203], 0
	v_mfma_f32_16x16x32_bf16 v[20:23], v[144:147], v[208:211], 0
	v_mfma_f32_16x16x32_bf16 v[16:19], v[164:167], v[208:211], 0
	v_mfma_f32_16x16x32_bf16 v[4:7], v[144:147], v[216:219], 0
	v_mfma_f32_16x16x32_bf16 v[0:3], v[164:167], v[216:219], 0
	v_mfma_f32_16x16x32_bf16 v[52:55], v[148:151], v[192:195], v[52:55]
	v_mfma_f32_16x16x32_bf16 v[48:51], v[184:187], v[192:195], v[48:51]
	v_mfma_f32_16x16x32_bf16 v[36:39], v[148:151], v[204:207], v[36:39]
	v_mfma_f32_16x16x32_bf16 v[32:35], v[184:187], v[204:207], v[32:35]
	v_mfma_f32_16x16x32_bf16 v[20:23], v[148:151], v[212:215], v[20:23]
	v_mfma_f32_16x16x32_bf16 v[16:19], v[184:187], v[212:215], v[16:19]
	v_mfma_f32_16x16x32_bf16 v[4:7], v[148:151], v[228:231], v[4:7]
	v_mfma_f32_16x16x32_bf16 v[0:3], v[184:187], v[228:231], v[0:3]
	s_barrier
	s_setprio 0
	s_add_i32 s12, 0, 0x18000
	s_add_i32 s13, 0, 0x1c000
	v_add_u32_e32 v140, s12, v197
	v_add_u32_e32 v184, s13, v197
	ds_read_b128 v[128:131], v140
	ds_read_b128 v[132:135], v140 offset:1024
	ds_read_b128 v[136:139], v140 offset:2048
	ds_read_b128 v[140:143], v140 offset:3072
	ds_read_b128 v[144:147], v184
	ds_read_b128 v[148:151], v184 offset:1024
	ds_read_b128 v[164:167], v184 offset:2048
	ds_read_b128 v[184:187], v184 offset:3072
	s_add_u32 s0, s54, 0x40000
	s_addc_u32 s1, s55, 0
	s_mov_b32 m0, s58
	ds_read_b128 v[188:191], v198 offset:32768
	ds_read_b128 v[192:195], v198 offset:33792
	ds_read_b128 v[200:203], v198 offset:34816
	ds_read_b128 v[204:207], v198 offset:35840
	ds_read_b128 v[208:211], v198 offset:36864
	ds_read_b128 v[212:215], v198 offset:37888
	ds_read_b128 v[216:219], v198 offset:38912
	ds_read_b128 v[228:231], v198 offset:39936
	global_load_lds_dwordx4 v152, s[0:1]
	s_mov_b32 m0, s59
	s_nop 0
	global_load_lds_dwordx4 v154, s[0:1]
	s_mov_b32 m0, s47
	s_nop 0
	global_load_lds_dwordx4 v[236:237], off
	s_mov_b32 m0, s57
	s_nop 0
	global_load_lds_dwordx4 v[238:239], off
	s_waitcnt vmcnt(8)
	s_waitcnt lgkmcnt(0)
	s_barrier
	s_setprio 1
	v_mfma_f32_16x16x32_bf16 v[124:127], v[128:131], v[188:191], v[124:127]
	v_mfma_f32_16x16x32_bf16 v[120:123], v[136:139], v[188:191], v[120:123]
	v_mfma_f32_16x16x32_bf16 v[108:111], v[128:131], v[200:203], v[108:111]
	v_mfma_f32_16x16x32_bf16 v[104:107], v[136:139], v[200:203], v[104:107]
	v_mfma_f32_16x16x32_bf16 v[92:95], v[128:131], v[208:211], v[92:95]
	v_mfma_f32_16x16x32_bf16 v[88:91], v[136:139], v[208:211], v[88:91]
	v_mfma_f32_16x16x32_bf16 v[76:79], v[128:131], v[216:219], v[76:79]
	v_mfma_f32_16x16x32_bf16 v[72:75], v[136:139], v[216:219], v[72:75]
	v_mfma_f32_16x16x32_bf16 v[124:127], v[132:135], v[192:195], v[124:127]
	v_mfma_f32_16x16x32_bf16 v[120:123], v[140:143], v[192:195], v[120:123]
	v_mfma_f32_16x16x32_bf16 v[108:111], v[132:135], v[204:207], v[108:111]
	v_mfma_f32_16x16x32_bf16 v[104:107], v[140:143], v[204:207], v[104:107]
	v_mfma_f32_16x16x32_bf16 v[92:95], v[132:135], v[212:215], v[92:95]
	v_mfma_f32_16x16x32_bf16 v[88:91], v[140:143], v[212:215], v[88:91]
	v_mfma_f32_16x16x32_bf16 v[76:79], v[132:135], v[228:231], v[76:79]
	v_mfma_f32_16x16x32_bf16 v[72:75], v[140:143], v[228:231], v[72:75]
	v_mfma_f32_16x16x32_bf16 v[116:119], v[144:147], v[188:191], v[116:119]
	v_mfma_f32_16x16x32_bf16 v[112:115], v[164:167], v[188:191], v[112:115]
	v_mfma_f32_16x16x32_bf16 v[100:103], v[144:147], v[200:203], v[100:103]
	v_mfma_f32_16x16x32_bf16 v[96:99], v[164:167], v[200:203], v[96:99]
	v_mfma_f32_16x16x32_bf16 v[84:87], v[144:147], v[208:211], v[84:87]
	v_mfma_f32_16x16x32_bf16 v[80:83], v[164:167], v[208:211], v[80:83]
	v_mfma_f32_16x16x32_bf16 v[68:71], v[144:147], v[216:219], v[68:71]
	v_mfma_f32_16x16x32_bf16 v[64:67], v[164:167], v[216:219], v[64:67]
	v_mfma_f32_16x16x32_bf16 v[116:119], v[148:151], v[192:195], v[116:119]
	v_mfma_f32_16x16x32_bf16 v[112:115], v[184:187], v[192:195], v[112:115]
	v_mfma_f32_16x16x32_bf16 v[100:103], v[148:151], v[204:207], v[100:103]
	v_mfma_f32_16x16x32_bf16 v[96:99], v[184:187], v[204:207], v[96:99]
	v_mfma_f32_16x16x32_bf16 v[84:87], v[148:151], v[212:215], v[84:87]
	v_mfma_f32_16x16x32_bf16 v[80:83], v[184:187], v[212:215], v[80:83]
	v_mfma_f32_16x16x32_bf16 v[68:71], v[148:151], v[228:231], v[68:71]
	v_mfma_f32_16x16x32_bf16 v[64:67], v[184:187], v[228:231], v[64:67]
	s_barrier
	s_setprio 0
	s_add_i32 s0, s12, s56
	v_lshl_add_u64 v[232:233], v[232:233], 0, s[16:17]
	s_mov_b32 m0, s0
	ds_read_b128 v[188:191], v198 offset:49152
	ds_read_b128 v[192:195], v198 offset:50176
	ds_read_b128 v[200:203], v198 offset:51200
	ds_read_b128 v[204:207], v198 offset:52224
	ds_read_b128 v[208:211], v198 offset:53248
	ds_read_b128 v[212:215], v198 offset:54272
	ds_read_b128 v[216:219], v198 offset:55296
	ds_read_b128 v[228:231], v198 offset:56320
	global_load_lds_dwordx4 v[232:233], off
	s_add_i32 m0, s0, 0x2000
	s_add_u32 s0, s52, 0x40080
	v_lshl_add_u64 v[232:233], v[234:235], 0, s[16:17]
	s_addc_u32 s1, s53, 0
	s_add_i32 s12, s13, s56
	global_load_lds_dwordx4 v[232:233], off
	s_mov_b32 m0, s12
	s_nop 0
	global_load_lds_dwordx4 v170, s[0:1]
	s_add_i32 m0, s12, 0x2000
	s_nop 0
	global_load_lds_dwordx4 v156, s[0:1]
	v_lshl_add_u64 v[232:233], v[236:237], 0, s[16:17]
	s_mov_b32 m0, s60
	s_nop 0
	global_load_lds_dwordx4 v[232:233], off
	v_lshl_add_u64 v[232:233], v[238:239], 0, s[16:17]
	s_mov_b32 m0, s61
	s_nop 0
	global_load_lds_dwordx4 v[232:233], off
	s_waitcnt vmcnt(6)
	s_waitcnt lgkmcnt(0)
	s_barrier
	s_setprio 1
	v_mfma_f32_16x16x32_bf16 v[60:63], v[128:131], v[188:191], v[60:63]
	v_mfma_f32_16x16x32_bf16 v[56:59], v[136:139], v[188:191], v[56:59]
	v_mfma_f32_16x16x32_bf16 v[44:47], v[128:131], v[200:203], v[44:47]
	v_mfma_f32_16x16x32_bf16 v[40:43], v[136:139], v[200:203], v[40:43]
	v_mfma_f32_16x16x32_bf16 v[28:31], v[128:131], v[208:211], v[28:31]
	v_mfma_f32_16x16x32_bf16 v[24:27], v[136:139], v[208:211], v[24:27]
	v_mfma_f32_16x16x32_bf16 v[12:15], v[128:131], v[216:219], v[12:15]
	v_mfma_f32_16x16x32_bf16 v[8:11], v[136:139], v[216:219], v[8:11]
	v_mfma_f32_16x16x32_bf16 v[60:63], v[132:135], v[192:195], v[60:63]
	v_mfma_f32_16x16x32_bf16 v[56:59], v[140:143], v[192:195], v[56:59]
	v_mfma_f32_16x16x32_bf16 v[44:47], v[132:135], v[204:207], v[44:47]
	v_mfma_f32_16x16x32_bf16 v[40:43], v[140:143], v[204:207], v[40:43]
	v_mfma_f32_16x16x32_bf16 v[28:31], v[132:135], v[212:215], v[28:31]
	v_mfma_f32_16x16x32_bf16 v[24:27], v[140:143], v[212:215], v[24:27]
	v_mfma_f32_16x16x32_bf16 v[12:15], v[132:135], v[228:231], v[12:15]
	v_mfma_f32_16x16x32_bf16 v[8:11], v[140:143], v[228:231], v[8:11]
	v_mfma_f32_16x16x32_bf16 v[52:55], v[144:147], v[188:191], v[52:55]
	v_mfma_f32_16x16x32_bf16 v[48:51], v[164:167], v[188:191], v[48:51]
	v_mfma_f32_16x16x32_bf16 v[36:39], v[144:147], v[200:203], v[36:39]
	v_mfma_f32_16x16x32_bf16 v[32:35], v[164:167], v[200:203], v[32:35]
	v_mfma_f32_16x16x32_bf16 v[20:23], v[144:147], v[208:211], v[20:23]
	v_mfma_f32_16x16x32_bf16 v[16:19], v[164:167], v[208:211], v[16:19]
	v_mfma_f32_16x16x32_bf16 v[4:7], v[144:147], v[216:219], v[4:7]
	v_mfma_f32_16x16x32_bf16 v[0:3], v[164:167], v[216:219], v[0:3]
	v_mfma_f32_16x16x32_bf16 v[52:55], v[148:151], v[192:195], v[52:55]
	v_mfma_f32_16x16x32_bf16 v[48:51], v[184:187], v[192:195], v[48:51]
	v_mfma_f32_16x16x32_bf16 v[36:39], v[148:151], v[204:207], v[36:39]
	v_mfma_f32_16x16x32_bf16 v[32:35], v[184:187], v[204:207], v[32:35]
	v_mfma_f32_16x16x32_bf16 v[20:23], v[148:151], v[212:215], v[20:23]
	v_mfma_f32_16x16x32_bf16 v[16:19], v[184:187], v[212:215], v[16:19]
	v_mfma_f32_16x16x32_bf16 v[4:7], v[148:151], v[228:231], v[4:7]
	v_mfma_f32_16x16x32_bf16 v[0:3], v[184:187], v[228:231], v[0:3]
	s_barrier
	s_setprio 0
	s_add_i32 s66, s66, 2
	s_add_u32 s64, s64, 0x100
	s_addc_u32 s65, s65, 0
	s_cmp_gt_u32 s66, 13
	s_mov_b64 s[48:49], s[50:51]
.LBB0_776:
	s_add_u32 s50, s48, 0x100
	s_addc_u32 s51, s49, 0
	s_add_i32 s0, 0, 0x10000
	s_cmp_eq_u32 s66, 12
	s_cselect_b32 s55, s37, s51
	s_cselect_b32 s54, s45, s50
	s_cselect_b32 s53, s35, s65
	s_cselect_b32 s52, s63, s64
	s_add_i32 s12, 0, 0x14000
	v_add_u32_e32 v140, s0, v197
	v_add_u32_e32 v184, s12, v197
	ds_read_b128 v[128:131], v140
	ds_read_b128 v[132:135], v140 offset:1024
	ds_read_b128 v[136:139], v140 offset:2048
	ds_read_b128 v[140:143], v140 offset:3072
	ds_read_b128 v[144:147], v184
	ds_read_b128 v[148:151], v184 offset:1024
	ds_read_b128 v[164:167], v184 offset:2048
	ds_read_b128 v[184:187], v184 offset:3072
	s_add_i32 m0, s47, 0xc000
	ds_read_b128 v[188:191], v198
	ds_read_b128 v[192:195], v198 offset:1024
	ds_read_b128 v[200:203], v198 offset:2048
	ds_read_b128 v[204:207], v198 offset:3072
	ds_read_b128 v[208:211], v198 offset:4096
	ds_read_b128 v[212:215], v198 offset:5120
	ds_read_b128 v[216:219], v198 offset:6144
	ds_read_b128 v[228:231], v198 offset:7168
	global_load_lds_dwordx4 v160, s[48:49]
	s_add_i32 m0, s47, 0xe000
	s_nop 0
	global_load_lds_dwordx4 v162, s[48:49]
	s_waitcnt vmcnt(8)
	s_waitcnt lgkmcnt(0)
	s_barrier
	s_setprio 1
	v_mfma_f32_16x16x32_bf16 v[124:127], v[128:131], v[188:191], v[124:127]
	v_mfma_f32_16x16x32_bf16 v[120:123], v[136:139], v[188:191], v[120:123]
	v_mfma_f32_16x16x32_bf16 v[108:111], v[128:131], v[200:203], v[108:111]
	v_mfma_f32_16x16x32_bf16 v[104:107], v[136:139], v[200:203], v[104:107]
	v_mfma_f32_16x16x32_bf16 v[92:95], v[128:131], v[208:211], v[92:95]
	v_mfma_f32_16x16x32_bf16 v[88:91], v[136:139], v[208:211], v[88:91]
	v_mfma_f32_16x16x32_bf16 v[76:79], v[128:131], v[216:219], v[76:79]
	v_mfma_f32_16x16x32_bf16 v[72:75], v[136:139], v[216:219], v[72:75]
	v_mfma_f32_16x16x32_bf16 v[124:127], v[132:135], v[192:195], v[124:127]
	v_mfma_f32_16x16x32_bf16 v[120:123], v[140:143], v[192:195], v[120:123]
	v_mfma_f32_16x16x32_bf16 v[108:111], v[132:135], v[204:207], v[108:111]
	v_mfma_f32_16x16x32_bf16 v[104:107], v[140:143], v[204:207], v[104:107]
	v_mfma_f32_16x16x32_bf16 v[92:95], v[132:135], v[212:215], v[92:95]
	v_mfma_f32_16x16x32_bf16 v[88:91], v[140:143], v[212:215], v[88:91]
	v_mfma_f32_16x16x32_bf16 v[76:79], v[132:135], v[228:231], v[76:79]
	v_mfma_f32_16x16x32_bf16 v[72:75], v[140:143], v[228:231], v[72:75]
	v_mfma_f32_16x16x32_bf16 v[116:119], v[144:147], v[188:191], v[116:119]
	v_mfma_f32_16x16x32_bf16 v[112:115], v[164:167], v[188:191], v[112:115]
	v_mfma_f32_16x16x32_bf16 v[100:103], v[144:147], v[200:203], v[100:103]
	v_mfma_f32_16x16x32_bf16 v[96:99], v[164:167], v[200:203], v[96:99]
	v_mfma_f32_16x16x32_bf16 v[84:87], v[144:147], v[208:211], v[84:87]
	v_mfma_f32_16x16x32_bf16 v[80:83], v[164:167], v[208:211], v[80:83]
	v_mfma_f32_16x16x32_bf16 v[68:71], v[144:147], v[216:219], v[68:71]
	v_mfma_f32_16x16x32_bf16 v[64:67], v[164:167], v[216:219], v[64:67]
	v_mfma_f32_16x16x32_bf16 v[116:119], v[148:151], v[192:195], v[116:119]
	v_mfma_f32_16x16x32_bf16 v[112:115], v[184:187], v[192:195], v[112:115]
	v_mfma_f32_16x16x32_bf16 v[100:103], v[148:151], v[204:207], v[100:103]
	v_mfma_f32_16x16x32_bf16 v[96:99], v[184:187], v[204:207], v[96:99]
	v_mfma_f32_16x16x32_bf16 v[84:87], v[148:151], v[212:215], v[84:87]
	v_mfma_f32_16x16x32_bf16 v[80:83], v[184:187], v[212:215], v[80:83]
	v_mfma_f32_16x16x32_bf16 v[68:71], v[148:151], v[228:231], v[68:71]
	v_mfma_f32_16x16x32_bf16 v[64:67], v[184:187], v[228:231], v[64:67]
	s_barrier
	s_setprio 0
	s_add_i32 s0, s0, s56
	v_lshl_add_u64 v[232:233], s[52:53], 0, v[170:171]
	s_mov_b32 m0, s0
	ds_read_b128 v[188:191], v198 offset:16384
	ds_read_b128 v[192:195], v198 offset:17408
	ds_read_b128 v[200:203], v198 offset:18432
	ds_read_b128 v[204:207], v198 offset:19456
	ds_read_b128 v[208:211], v198 offset:20480
	ds_read_b128 v[212:215], v198 offset:21504
	ds_read_b128 v[216:219], v198 offset:22528
	ds_read_b128 v[228:231], v198 offset:23552
	global_load_lds_dwordx4 v[232:233], off
	s_add_i32 m0, s0, 0x2000
	s_add_u32 s0, s52, 0x40000
	v_lshl_add_u64 v[234:235], s[52:53], 0, v[156:157]
	s_addc_u32 s1, s53, 0
	s_add_i32 s12, s12, s56
	global_load_lds_dwordx4 v[234:235], off
	s_mov_b32 m0, s12
	v_lshl_add_u64 v[238:239], s[54:55], 0, v[154:155]
	global_load_lds_dwordx4 v170, s[0:1]
	s_add_i32 m0, s12, 0x2000
	s_nop 0
	global_load_lds_dwordx4 v156, s[0:1]
	v_lshl_add_u64 v[236:237], s[54:55], 0, v[152:153]
	s_waitcnt vmcnt(6)
	s_waitcnt lgkmcnt(0)
	s_barrier
	s_setprio 1
	v_mfma_f32_16x16x32_bf16 v[60:63], v[128:131], v[188:191], v[60:63]
	v_mfma_f32_16x16x32_bf16 v[56:59], v[136:139], v[188:191], v[56:59]
	v_mfma_f32_16x16x32_bf16 v[44:47], v[128:131], v[200:203], v[44:47]
	v_mfma_f32_16x16x32_bf16 v[40:43], v[136:139], v[200:203], v[40:43]
	v_mfma_f32_16x16x32_bf16 v[28:31], v[128:131], v[208:211], v[28:31]
	v_mfma_f32_16x16x32_bf16 v[24:27], v[136:139], v[208:211], v[24:27]
	v_mfma_f32_16x16x32_bf16 v[12:15], v[128:131], v[216:219], v[12:15]
	v_mfma_f32_16x16x32_bf16 v[8:11], v[136:139], v[216:219], v[8:11]
	v_mfma_f32_16x16x32_bf16 v[60:63], v[132:135], v[192:195], v[60:63]
	v_mfma_f32_16x16x32_bf16 v[56:59], v[140:143], v[192:195], v[56:59]
	v_mfma_f32_16x16x32_bf16 v[44:47], v[132:135], v[204:207], v[44:47]
	v_mfma_f32_16x16x32_bf16 v[40:43], v[140:143], v[204:207], v[40:43]
	v_mfma_f32_16x16x32_bf16 v[28:31], v[132:135], v[212:215], v[28:31]
	v_mfma_f32_16x16x32_bf16 v[24:27], v[140:143], v[212:215], v[24:27]
	v_mfma_f32_16x16x32_bf16 v[12:15], v[132:135], v[228:231], v[12:15]
	v_mfma_f32_16x16x32_bf16 v[8:11], v[140:143], v[228:231], v[8:11]
	v_mfma_f32_16x16x32_bf16 v[52:55], v[144:147], v[188:191], v[52:55]
	v_mfma_f32_16x16x32_bf16 v[48:51], v[164:167], v[188:191], v[48:51]
	v_mfma_f32_16x16x32_bf16 v[36:39], v[144:147], v[200:203], v[36:39]
	v_mfma_f32_16x16x32_bf16 v[32:35], v[164:167], v[200:203], v[32:35]
	v_mfma_f32_16x16x32_bf16 v[20:23], v[144:147], v[208:211], v[20:23]
	v_mfma_f32_16x16x32_bf16 v[16:19], v[164:167], v[208:211], v[16:19]
	v_mfma_f32_16x16x32_bf16 v[4:7], v[144:147], v[216:219], v[4:7]
	v_mfma_f32_16x16x32_bf16 v[0:3], v[164:167], v[216:219], v[0:3]
	v_mfma_f32_16x16x32_bf16 v[52:55], v[148:151], v[192:195], v[52:55]
	v_mfma_f32_16x16x32_bf16 v[48:51], v[184:187], v[192:195], v[48:51]
	v_mfma_f32_16x16x32_bf16 v[36:39], v[148:151], v[204:207], v[36:39]
	v_mfma_f32_16x16x32_bf16 v[32:35], v[184:187], v[204:207], v[32:35]
	v_mfma_f32_16x16x32_bf16 v[20:23], v[148:151], v[212:215], v[20:23]
	v_mfma_f32_16x16x32_bf16 v[16:19], v[184:187], v[212:215], v[16:19]
	v_mfma_f32_16x16x32_bf16 v[4:7], v[148:151], v[228:231], v[4:7]
	v_mfma_f32_16x16x32_bf16 v[0:3], v[184:187], v[228:231], v[0:3]
	s_barrier
	s_setprio 0
	s_add_i32 s12, 0, 0x18000
	s_add_i32 s13, 0, 0x1c000
	v_add_u32_e32 v140, s12, v197
	v_add_u32_e32 v184, s13, v197
	ds_read_b128 v[128:131], v140
	ds_read_b128 v[132:135], v140 offset:1024
	ds_read_b128 v[136:139], v140 offset:2048
	ds_read_b128 v[140:143], v140 offset:3072
	ds_read_b128 v[144:147], v184
	ds_read_b128 v[148:151], v184 offset:1024
	ds_read_b128 v[164:167], v184 offset:2048
	ds_read_b128 v[184:187], v184 offset:3072
	s_add_u32 s0, s54, 0x40000
	s_addc_u32 s1, s55, 0
	s_mov_b32 m0, s58
	ds_read_b128 v[188:191], v198 offset:32768
	ds_read_b128 v[192:195], v198 offset:33792
	ds_read_b128 v[200:203], v198 offset:34816
	ds_read_b128 v[204:207], v198 offset:35840
	ds_read_b128 v[208:211], v198 offset:36864
	ds_read_b128 v[212:215], v198 offset:37888
	ds_read_b128 v[216:219], v198 offset:38912
	ds_read_b128 v[228:231], v198 offset:39936
	global_load_lds_dwordx4 v152, s[0:1]
	s_mov_b32 m0, s59
	s_nop 0
	global_load_lds_dwordx4 v154, s[0:1]
	s_mov_b32 m0, s47
	s_nop 0
	global_load_lds_dwordx4 v[236:237], off
	s_mov_b32 m0, s57
	s_nop 0
	global_load_lds_dwordx4 v[238:239], off
	s_waitcnt vmcnt(8)
	s_waitcnt lgkmcnt(0)
	s_barrier
	s_setprio 1
	v_mfma_f32_16x16x32_bf16 v[124:127], v[128:131], v[188:191], v[124:127]
	v_mfma_f32_16x16x32_bf16 v[120:123], v[136:139], v[188:191], v[120:123]
	v_mfma_f32_16x16x32_bf16 v[108:111], v[128:131], v[200:203], v[108:111]
	v_mfma_f32_16x16x32_bf16 v[104:107], v[136:139], v[200:203], v[104:107]
	v_mfma_f32_16x16x32_bf16 v[92:95], v[128:131], v[208:211], v[92:95]
	v_mfma_f32_16x16x32_bf16 v[88:91], v[136:139], v[208:211], v[88:91]
	v_mfma_f32_16x16x32_bf16 v[76:79], v[128:131], v[216:219], v[76:79]
	v_mfma_f32_16x16x32_bf16 v[72:75], v[136:139], v[216:219], v[72:75]
	v_mfma_f32_16x16x32_bf16 v[124:127], v[132:135], v[192:195], v[124:127]
	v_mfma_f32_16x16x32_bf16 v[120:123], v[140:143], v[192:195], v[120:123]
	v_mfma_f32_16x16x32_bf16 v[108:111], v[132:135], v[204:207], v[108:111]
	v_mfma_f32_16x16x32_bf16 v[104:107], v[140:143], v[204:207], v[104:107]
	v_mfma_f32_16x16x32_bf16 v[92:95], v[132:135], v[212:215], v[92:95]
	v_mfma_f32_16x16x32_bf16 v[88:91], v[140:143], v[212:215], v[88:91]
	v_mfma_f32_16x16x32_bf16 v[76:79], v[132:135], v[228:231], v[76:79]
	v_mfma_f32_16x16x32_bf16 v[72:75], v[140:143], v[228:231], v[72:75]
	v_mfma_f32_16x16x32_bf16 v[116:119], v[144:147], v[188:191], v[116:119]
	v_mfma_f32_16x16x32_bf16 v[112:115], v[164:167], v[188:191], v[112:115]
	v_mfma_f32_16x16x32_bf16 v[100:103], v[144:147], v[200:203], v[100:103]
	v_mfma_f32_16x16x32_bf16 v[96:99], v[164:167], v[200:203], v[96:99]
	v_mfma_f32_16x16x32_bf16 v[84:87], v[144:147], v[208:211], v[84:87]
	v_mfma_f32_16x16x32_bf16 v[80:83], v[164:167], v[208:211], v[80:83]
	v_mfma_f32_16x16x32_bf16 v[68:71], v[144:147], v[216:219], v[68:71]
	v_mfma_f32_16x16x32_bf16 v[64:67], v[164:167], v[216:219], v[64:67]
	v_mfma_f32_16x16x32_bf16 v[116:119], v[148:151], v[192:195], v[116:119]
	v_mfma_f32_16x16x32_bf16 v[112:115], v[184:187], v[192:195], v[112:115]
	v_mfma_f32_16x16x32_bf16 v[100:103], v[148:151], v[204:207], v[100:103]
	v_mfma_f32_16x16x32_bf16 v[96:99], v[184:187], v[204:207], v[96:99]
	v_mfma_f32_16x16x32_bf16 v[84:87], v[148:151], v[212:215], v[84:87]
	v_mfma_f32_16x16x32_bf16 v[80:83], v[184:187], v[212:215], v[80:83]
	v_mfma_f32_16x16x32_bf16 v[68:71], v[148:151], v[228:231], v[68:71]
	v_mfma_f32_16x16x32_bf16 v[64:67], v[184:187], v[228:231], v[64:67]
	s_barrier
	s_setprio 0
	s_add_i32 s0, s12, s56
	v_lshl_add_u64 v[232:233], v[232:233], 0, s[16:17]
	s_mov_b32 m0, s0
	ds_read_b128 v[188:191], v198 offset:49152
	ds_read_b128 v[192:195], v198 offset:50176
	ds_read_b128 v[200:203], v198 offset:51200
	ds_read_b128 v[204:207], v198 offset:52224
	ds_read_b128 v[208:211], v198 offset:53248
	ds_read_b128 v[212:215], v198 offset:54272
	ds_read_b128 v[216:219], v198 offset:55296
	ds_read_b128 v[228:231], v198 offset:56320
	global_load_lds_dwordx4 v[232:233], off
	s_add_i32 m0, s0, 0x2000
	s_add_u32 s0, s52, 0x40080
	v_lshl_add_u64 v[232:233], v[234:235], 0, s[16:17]
	s_addc_u32 s1, s53, 0
	s_add_i32 s12, s13, s56
	global_load_lds_dwordx4 v[232:233], off
	s_mov_b32 m0, s12
	s_nop 0
	global_load_lds_dwordx4 v170, s[0:1]
	s_add_i32 m0, s12, 0x2000
	s_nop 0
	global_load_lds_dwordx4 v156, s[0:1]
	v_lshl_add_u64 v[232:233], v[236:237], 0, s[16:17]
	s_mov_b32 m0, s60
	s_nop 0
	global_load_lds_dwordx4 v[232:233], off
	v_lshl_add_u64 v[232:233], v[238:239], 0, s[16:17]
	s_mov_b32 m0, s61
	s_nop 0
	global_load_lds_dwordx4 v[232:233], off
	s_waitcnt vmcnt(6)
	s_waitcnt lgkmcnt(0)
	s_barrier
	s_setprio 1
	v_mfma_f32_16x16x32_bf16 v[60:63], v[128:131], v[188:191], v[60:63]
	v_mfma_f32_16x16x32_bf16 v[56:59], v[136:139], v[188:191], v[56:59]
	v_mfma_f32_16x16x32_bf16 v[44:47], v[128:131], v[200:203], v[44:47]
	v_mfma_f32_16x16x32_bf16 v[40:43], v[136:139], v[200:203], v[40:43]
	v_mfma_f32_16x16x32_bf16 v[28:31], v[128:131], v[208:211], v[28:31]
	v_mfma_f32_16x16x32_bf16 v[24:27], v[136:139], v[208:211], v[24:27]
	v_mfma_f32_16x16x32_bf16 v[12:15], v[128:131], v[216:219], v[12:15]
	v_mfma_f32_16x16x32_bf16 v[8:11], v[136:139], v[216:219], v[8:11]
	v_mfma_f32_16x16x32_bf16 v[60:63], v[132:135], v[192:195], v[60:63]
	v_mfma_f32_16x16x32_bf16 v[56:59], v[140:143], v[192:195], v[56:59]
	v_mfma_f32_16x16x32_bf16 v[44:47], v[132:135], v[204:207], v[44:47]
	v_mfma_f32_16x16x32_bf16 v[40:43], v[140:143], v[204:207], v[40:43]
	v_mfma_f32_16x16x32_bf16 v[28:31], v[132:135], v[212:215], v[28:31]
	v_mfma_f32_16x16x32_bf16 v[24:27], v[140:143], v[212:215], v[24:27]
	v_mfma_f32_16x16x32_bf16 v[12:15], v[132:135], v[228:231], v[12:15]
	v_mfma_f32_16x16x32_bf16 v[8:11], v[140:143], v[228:231], v[8:11]
	v_mfma_f32_16x16x32_bf16 v[52:55], v[144:147], v[188:191], v[52:55]
	v_mfma_f32_16x16x32_bf16 v[48:51], v[164:167], v[188:191], v[48:51]
	v_mfma_f32_16x16x32_bf16 v[36:39], v[144:147], v[200:203], v[36:39]
	v_mfma_f32_16x16x32_bf16 v[32:35], v[164:167], v[200:203], v[32:35]
	v_mfma_f32_16x16x32_bf16 v[20:23], v[144:147], v[208:211], v[20:23]
	v_mfma_f32_16x16x32_bf16 v[16:19], v[164:167], v[208:211], v[16:19]
	v_mfma_f32_16x16x32_bf16 v[4:7], v[144:147], v[216:219], v[4:7]
	v_mfma_f32_16x16x32_bf16 v[0:3], v[164:167], v[216:219], v[0:3]
	v_mfma_f32_16x16x32_bf16 v[52:55], v[148:151], v[192:195], v[52:55]
	v_mfma_f32_16x16x32_bf16 v[48:51], v[184:187], v[192:195], v[48:51]
	v_mfma_f32_16x16x32_bf16 v[36:39], v[148:151], v[204:207], v[36:39]
	v_mfma_f32_16x16x32_bf16 v[32:35], v[184:187], v[204:207], v[32:35]
	v_mfma_f32_16x16x32_bf16 v[20:23], v[148:151], v[212:215], v[20:23]
	v_mfma_f32_16x16x32_bf16 v[16:19], v[184:187], v[212:215], v[16:19]
	v_mfma_f32_16x16x32_bf16 v[4:7], v[148:151], v[228:231], v[4:7]
	v_mfma_f32_16x16x32_bf16 v[0:3], v[184:187], v[228:231], v[0:3]
	s_barrier
	s_setprio 0
	s_add_i32 s66, s66, 2
	s_add_u32 s64, s64, 0x100
	s_addc_u32 s65, s65, 0
	s_cmp_gt_u32 s66, 13
	s_mov_b64 s[48:49], s[50:51]
	s_cbranch_scc0 .LBB0_776
	s_and_b64 vcc, exec, s[30:31]
	s_cbranch_vccz .LBB0_779
	s_barrier

.Lrestag_863:
	s_add_u32 s62, s60, 0x100
	s_addc_u32 s63, s61, 0
	s_add_i32 s0, 0, 0x10000
	s_cmp_eq_u32 s12, 12
	s_cselect_b32 s67, s23, s63
	s_cselect_b32 s66, s51, s62
	s_cselect_b32 s65, s49, vcc_hi
	s_cselect_b32 s64, s57, vcc_lo
	s_add_i32 s13, 0, 0x14000
	v_add_u32_e32 v64, s0, v228
	v_add_u32_e32 v92, s13, v228
	ds_read_b128 v[48:51], v64
	ds_read_b128 v[52:55], v64 offset:1024
	ds_read_b128 v[60:63], v64 offset:2048
	ds_read_b128 v[64:67], v64 offset:3072
	ds_read_b128 v[72:75], v92
	ds_read_b128 v[80:83], v92 offset:1024
	ds_read_b128 v[84:87], v92 offset:2048
	ds_read_b128 v[92:95], v92 offset:3072
	s_add_i32 m0, s59, 0xc000
	ds_read_b128 v[112:115], v230
	ds_read_b128 v[164:167], v230 offset:1024
	ds_read_b128 v[194:197], v230 offset:2048
	ds_read_b128 v[198:201], v230 offset:3072
	ds_read_b128 v[202:205], v230 offset:4096
	ds_read_b128 v[206:209], v230 offset:5120
	ds_read_b128 v[210:213], v230 offset:6144
	ds_read_b128 v[214:217], v230 offset:7168
	global_load_lds_dwordx4 v190, s[60:61]
	s_add_i32 m0, s59, 0xe000
	s_nop 0
	global_load_lds_dwordx4 v192, s[60:61]
	s_nop 0
	s_waitcnt lgkmcnt(0)
	s_barrier
	s_setprio 1
	v_mfma_f32_16x16x32_bf16 v[160:163], v[48:51], v[112:115], 0
	v_mfma_f32_16x16x32_bf16 v[156:159], v[60:63], v[112:115], 0
	v_mfma_f32_16x16x32_bf16 v[128:131], v[48:51], v[194:197], 0
	v_mfma_f32_16x16x32_bf16 v[124:127], v[60:63], v[194:197], 0
	v_mfma_f32_16x16x32_bf16 v[108:111], v[48:51], v[202:205], 0
	v_mfma_f32_16x16x32_bf16 v[104:107], v[60:63], v[202:205], 0
	v_mfma_f32_16x16x32_bf16 v[100:103], v[48:51], v[210:213], 0
	v_mfma_f32_16x16x32_bf16 v[96:99], v[60:63], v[210:213], 0
	v_mfma_f32_16x16x32_bf16 v[160:163], v[52:55], v[164:167], v[160:163]
	v_mfma_f32_16x16x32_bf16 v[156:159], v[64:67], v[164:167], v[156:159]
	v_mfma_f32_16x16x32_bf16 v[128:131], v[52:55], v[198:201], v[128:131]
	v_mfma_f32_16x16x32_bf16 v[124:127], v[64:67], v[198:201], v[124:127]
	v_mfma_f32_16x16x32_bf16 v[108:111], v[52:55], v[206:209], v[108:111]
	v_mfma_f32_16x16x32_bf16 v[104:107], v[64:67], v[206:209], v[104:107]
	v_mfma_f32_16x16x32_bf16 v[100:103], v[52:55], v[214:217], v[100:103]
	v_mfma_f32_16x16x32_bf16 v[96:99], v[64:67], v[214:217], v[96:99]
	v_mfma_f32_16x16x32_bf16 v[152:155], v[72:75], v[112:115], 0
	v_mfma_f32_16x16x32_bf16 v[120:123], v[72:75], v[194:197], 0
	v_mfma_f32_16x16x32_bf16 v[116:119], v[84:87], v[194:197], 0
	v_mfma_f32_16x16x32_bf16 v[144:147], v[72:75], v[202:205], 0
	v_mfma_f32_16x16x32_bf16 v[140:143], v[84:87], v[202:205], 0
	v_mfma_f32_16x16x32_bf16 v[136:139], v[72:75], v[210:213], 0
	v_mfma_f32_16x16x32_bf16 v[132:135], v[84:87], v[210:213], 0
	v_mfma_f32_16x16x32_bf16 v[152:155], v[80:83], v[164:167], v[152:155]
	v_mfma_f32_16x16x32_bf16 v[112:115], v[84:87], v[112:115], 0
	v_mfma_f32_16x16x32_bf16 v[120:123], v[80:83], v[198:201], v[120:123]
	v_mfma_f32_16x16x32_bf16 v[116:119], v[92:95], v[198:201], v[116:119]
	v_mfma_f32_16x16x32_bf16 v[144:147], v[80:83], v[206:209], v[144:147]
	v_mfma_f32_16x16x32_bf16 v[140:143], v[92:95], v[206:209], v[140:143]
	v_mfma_f32_16x16x32_bf16 v[136:139], v[80:83], v[214:217], v[136:139]
	v_mfma_f32_16x16x32_bf16 v[132:135], v[92:95], v[214:217], v[132:135]
	v_mfma_f32_16x16x32_bf16 v[112:115], v[92:95], v[164:167], v[112:115]
	s_barrier
	s_setprio 0
	s_add_i32 s0, s0, s96
	v_lshl_add_u64 v[218:219], s[64:65], 0, v[170:171]
	s_mov_b32 m0, s0
	ds_read_b128 v[148:151], v230 offset:16384
	ds_read_b128 v[164:167], v230 offset:17408
	ds_read_b128 v[194:197], v230 offset:18432
	ds_read_b128 v[198:201], v230 offset:19456
	ds_read_b128 v[202:205], v230 offset:20480
	ds_read_b128 v[206:209], v230 offset:21504
	ds_read_b128 v[210:213], v230 offset:22528
	ds_read_b128 v[214:217], v230 offset:23552
	global_load_lds_dwordx4 v[218:219], off
	s_add_i32 m0, s0, 0x2000
	s_add_u32 s0, s64, 0x40000
	v_lshl_add_u64 v[232:233], s[64:65], 0, v[188:189]
	s_addc_u32 s1, s65, 0
	s_add_i32 s13, s13, s96
	global_load_lds_dwordx4 v[232:233], off
	s_mov_b32 m0, s13
	v_lshl_add_u64 v[236:237], s[66:67], 0, v[186:187]
	global_load_lds_dwordx4 v170, s[0:1]
	s_add_i32 m0, s13, 0x2000
	s_nop 0
	global_load_lds_dwordx4 v188, s[0:1]
	v_lshl_add_u64 v[234:235], s[66:67], 0, v[184:185]
	s_nop 0
	s_waitcnt lgkmcnt(0)
	s_barrier
	s_setprio 1
	v_mfma_f32_16x16x32_bf16 v[88:91], v[48:51], v[148:151], 0
	v_mfma_f32_16x16x32_bf16 v[76:79], v[60:63], v[148:151], 0
	v_mfma_f32_16x16x32_bf16 v[28:31], v[48:51], v[194:197], 0
	v_mfma_f32_16x16x32_bf16 v[24:27], v[60:63], v[194:197], 0
	v_mfma_f32_16x16x32_bf16 v[12:15], v[48:51], v[202:205], 0
	v_mfma_f32_16x16x32_bf16 v[8:11], v[60:63], v[202:205], 0
	v_mfma_f32_16x16x32_bf16 v[4:7], v[48:51], v[210:213], 0
	v_mfma_f32_16x16x32_bf16 v[0:3], v[60:63], v[210:213], 0
	v_mfma_f32_16x16x32_bf16 v[88:91], v[52:55], v[164:167], v[88:91]
	v_mfma_f32_16x16x32_bf16 v[76:79], v[64:67], v[164:167], v[76:79]
	v_mfma_f32_16x16x32_bf16 v[28:31], v[52:55], v[198:201], v[28:31]
	v_mfma_f32_16x16x32_bf16 v[24:27], v[64:67], v[198:201], v[24:27]
	v_mfma_f32_16x16x32_bf16 v[12:15], v[52:55], v[206:209], v[12:15]
	v_mfma_f32_16x16x32_bf16 v[8:11], v[64:67], v[206:209], v[8:11]
	v_mfma_f32_16x16x32_bf16 v[4:7], v[52:55], v[214:217], v[4:7]
	v_mfma_f32_16x16x32_bf16 v[0:3], v[64:67], v[214:217], v[0:3]
	v_mfma_f32_16x16x32_bf16 v[20:23], v[72:75], v[194:197], 0
	v_mfma_f32_16x16x32_bf16 v[16:19], v[84:87], v[194:197], 0
	v_mfma_f32_16x16x32_bf16 v[44:47], v[72:75], v[202:205], 0
	v_mfma_f32_16x16x32_bf16 v[40:43], v[84:87], v[202:205], 0
	v_mfma_f32_16x16x32_bf16 v[36:39], v[72:75], v[210:213], 0
	v_mfma_f32_16x16x32_bf16 v[32:35], v[84:87], v[210:213], 0
	v_mfma_f32_16x16x32_bf16 v[48:51], v[72:75], v[148:151], 0
	v_mfma_f32_16x16x32_bf16 v[52:55], v[84:87], v[148:151], 0
	v_mfma_f32_16x16x32_bf16 v[20:23], v[80:83], v[198:201], v[20:23]
	v_mfma_f32_16x16x32_bf16 v[16:19], v[92:95], v[198:201], v[16:19]
	v_mfma_f32_16x16x32_bf16 v[44:47], v[80:83], v[206:209], v[44:47]
	v_mfma_f32_16x16x32_bf16 v[40:43], v[92:95], v[206:209], v[40:43]
	v_mfma_f32_16x16x32_bf16 v[36:39], v[80:83], v[214:217], v[36:39]
	v_mfma_f32_16x16x32_bf16 v[32:35], v[92:95], v[214:217], v[32:35]
	v_mfma_f32_16x16x32_bf16 v[48:51], v[80:83], v[164:167], v[48:51]
	v_mfma_f32_16x16x32_bf16 v[52:55], v[92:95], v[164:167], v[52:55]
	s_barrier
	s_setprio 0
	s_add_i32 s13, 0, 0x18000
	s_add_i32 s60, 0, 0x1c000
	v_add_u32_e32 v68, s13, v228
	v_add_u32_e32 v92, s60, v228
	ds_read_b128 v[56:59], v68
	ds_read_b128 v[60:63], v68 offset:1024
	ds_read_b128 v[64:67], v68 offset:2048
	ds_read_b128 v[68:71], v68 offset:3072
	ds_read_b128 v[72:75], v92
	ds_read_b128 v[80:83], v92 offset:1024
	ds_read_b128 v[84:87], v92 offset:2048
	ds_read_b128 v[92:95], v92 offset:3072
	s_add_u32 s0, s66, 0x40000
	s_addc_u32 s1, s67, 0
	s_mov_b32 m0, s39
	ds_read_b128 v[148:151], v230 offset:32768
	ds_read_b128 v[164:167], v230 offset:33792
	ds_read_b128 v[194:197], v230 offset:34816
	ds_read_b128 v[198:201], v230 offset:35840
	ds_read_b128 v[202:205], v230 offset:36864
	ds_read_b128 v[206:209], v230 offset:37888
	ds_read_b128 v[210:213], v230 offset:38912
	ds_read_b128 v[214:217], v230 offset:39936
	global_load_lds_dwordx4 v184, s[0:1]
	s_mov_b32 m0, s76
	s_nop 0
	global_load_lds_dwordx4 v186, s[0:1]
	s_mov_b32 m0, s59
	s_nop 0
	global_load_lds_dwordx4 v[234:235], off
	s_mov_b32 m0, s97
	s_nop 0
	global_load_lds_dwordx4 v[236:237], off
	s_waitcnt vmcnt(8)
	s_waitcnt lgkmcnt(0)
	s_barrier
	s_setprio 1
	v_mfma_f32_16x16x32_bf16 v[160:163], v[56:59], v[148:151], v[160:163]
	v_mfma_f32_16x16x32_bf16 v[156:159], v[64:67], v[148:151], v[156:159]
	v_mfma_f32_16x16x32_bf16 v[128:131], v[56:59], v[194:197], v[128:131]
	v_mfma_f32_16x16x32_bf16 v[124:127], v[64:67], v[194:197], v[124:127]
	v_mfma_f32_16x16x32_bf16 v[108:111], v[56:59], v[202:205], v[108:111]
	v_mfma_f32_16x16x32_bf16 v[104:107], v[64:67], v[202:205], v[104:107]
	v_mfma_f32_16x16x32_bf16 v[100:103], v[56:59], v[210:213], v[100:103]
	v_mfma_f32_16x16x32_bf16 v[96:99], v[64:67], v[210:213], v[96:99]
	v_mfma_f32_16x16x32_bf16 v[160:163], v[60:63], v[164:167], v[160:163]
	v_mfma_f32_16x16x32_bf16 v[156:159], v[68:71], v[164:167], v[156:159]
	v_mfma_f32_16x16x32_bf16 v[128:131], v[60:63], v[198:201], v[128:131]
	v_mfma_f32_16x16x32_bf16 v[124:127], v[68:71], v[198:201], v[124:127]
	v_mfma_f32_16x16x32_bf16 v[108:111], v[60:63], v[206:209], v[108:111]
	v_mfma_f32_16x16x32_bf16 v[104:107], v[68:71], v[206:209], v[104:107]
	v_mfma_f32_16x16x32_bf16 v[100:103], v[60:63], v[214:217], v[100:103]
	v_mfma_f32_16x16x32_bf16 v[96:99], v[68:71], v[214:217], v[96:99]
	v_mfma_f32_16x16x32_bf16 v[112:115], v[84:87], v[148:151], v[112:115]
	v_mfma_f32_16x16x32_bf16 v[152:155], v[72:75], v[148:151], v[152:155]
	v_mfma_f32_16x16x32_bf16 v[148:151], v[92:95], v[164:167], v[112:115]
	v_mfma_f32_16x16x32_bf16 v[112:115], v[72:75], v[194:197], v[120:123]
	v_mfma_f32_16x16x32_bf16 v[120:123], v[80:83], v[198:201], v[112:115]
	v_mfma_f32_16x16x32_bf16 v[112:115], v[84:87], v[194:197], v[116:119]
	v_mfma_f32_16x16x32_bf16 v[116:119], v[92:95], v[198:201], v[112:115]
	v_mfma_f32_16x16x32_bf16 v[112:115], v[72:75], v[202:205], v[144:147]
	v_mfma_f32_16x16x32_bf16 v[144:147], v[80:83], v[206:209], v[112:115]
	v_mfma_f32_16x16x32_bf16 v[112:115], v[84:87], v[202:205], v[140:143]
	v_mfma_f32_16x16x32_bf16 v[140:143], v[92:95], v[206:209], v[112:115]
	v_mfma_f32_16x16x32_bf16 v[112:115], v[72:75], v[210:213], v[136:139]
	v_mfma_f32_16x16x32_bf16 v[136:139], v[80:83], v[214:217], v[112:115]
	v_mfma_f32_16x16x32_bf16 v[112:115], v[84:87], v[210:213], v[132:135]
	v_mfma_f32_16x16x32_bf16 v[152:155], v[80:83], v[164:167], v[152:155]
	v_mfma_f32_16x16x32_bf16 v[132:135], v[92:95], v[214:217], v[112:115]
	s_barrier
	s_setprio 0
	s_add_i32 s0, s13, s96
	v_lshl_add_u64 v[218:219], v[218:219], 0, s[16:17]
	s_mov_b32 m0, s0
	s_nop 0
	ds_read_b128 v[112:115], v230 offset:49152
	ds_read_b128 v[164:167], v230 offset:50176
	ds_read_b128 v[194:197], v230 offset:51200
	ds_read_b128 v[198:201], v230 offset:52224
	ds_read_b128 v[202:205], v230 offset:53248
	ds_read_b128 v[206:209], v230 offset:54272
	ds_read_b128 v[210:213], v230 offset:55296
	ds_read_b128 v[214:217], v230 offset:56320
	global_load_lds_dwordx4 v[218:219], off
	s_add_i32 m0, s0, 0x2000
	s_add_u32 s0, s64, 0x40080
	v_lshl_add_u64 v[218:219], v[232:233], 0, s[16:17]
	s_addc_u32 s1, s65, 0
	s_add_i32 s13, s60, s96
	global_load_lds_dwordx4 v[218:219], off
	s_mov_b32 m0, s13
	s_nop 0
	global_load_lds_dwordx4 v170, s[0:1]
	s_add_i32 m0, s13, 0x2000
	s_nop 0
	global_load_lds_dwordx4 v188, s[0:1]
	v_lshl_add_u64 v[218:219], v[234:235], 0, s[16:17]
	s_mov_b32 m0, s75
	s_nop 0
	global_load_lds_dwordx4 v[218:219], off
	v_lshl_add_u64 v[218:219], v[236:237], 0, s[16:17]
	s_mov_b32 m0, s91
	s_nop 0
	global_load_lds_dwordx4 v[218:219], off
	s_waitcnt vmcnt(6)
	s_waitcnt lgkmcnt(0)
	s_barrier
	s_setprio 1
	v_mfma_f32_16x16x32_bf16 v[88:91], v[56:59], v[112:115], v[88:91]
	v_mfma_f32_16x16x32_bf16 v[76:79], v[64:67], v[112:115], v[76:79]
	v_mfma_f32_16x16x32_bf16 v[28:31], v[56:59], v[194:197], v[28:31]
	v_mfma_f32_16x16x32_bf16 v[24:27], v[64:67], v[194:197], v[24:27]
	v_mfma_f32_16x16x32_bf16 v[12:15], v[56:59], v[202:205], v[12:15]
	v_mfma_f32_16x16x32_bf16 v[8:11], v[64:67], v[202:205], v[8:11]
	v_mfma_f32_16x16x32_bf16 v[4:7], v[56:59], v[210:213], v[4:7]
	v_mfma_f32_16x16x32_bf16 v[0:3], v[64:67], v[210:213], v[0:3]
	v_mfma_f32_16x16x32_bf16 v[88:91], v[60:63], v[164:167], v[88:91]
	v_mfma_f32_16x16x32_bf16 v[76:79], v[68:71], v[164:167], v[76:79]
	v_mfma_f32_16x16x32_bf16 v[28:31], v[60:63], v[198:201], v[28:31]
	v_mfma_f32_16x16x32_bf16 v[24:27], v[68:71], v[198:201], v[24:27]
	v_mfma_f32_16x16x32_bf16 v[12:15], v[60:63], v[206:209], v[12:15]
	v_mfma_f32_16x16x32_bf16 v[8:11], v[68:71], v[206:209], v[8:11]
	v_mfma_f32_16x16x32_bf16 v[4:7], v[60:63], v[214:217], v[4:7]
	v_mfma_f32_16x16x32_bf16 v[0:3], v[68:71], v[214:217], v[0:3]
	v_mfma_f32_16x16x32_bf16 v[48:51], v[72:75], v[112:115], v[48:51]
	v_mfma_f32_16x16x32_bf16 v[68:71], v[80:83], v[164:167], v[48:51]
	v_mfma_f32_16x16x32_bf16 v[48:51], v[84:87], v[112:115], v[52:55]
	v_mfma_f32_16x16x32_bf16 v[20:23], v[72:75], v[194:197], v[20:23]
	v_mfma_f32_16x16x32_bf16 v[16:19], v[84:87], v[194:197], v[16:19]
	v_mfma_f32_16x16x32_bf16 v[44:47], v[72:75], v[202:205], v[44:47]
	v_mfma_f32_16x16x32_bf16 v[40:43], v[84:87], v[202:205], v[40:43]
	v_mfma_f32_16x16x32_bf16 v[36:39], v[72:75], v[210:213], v[36:39]
	v_mfma_f32_16x16x32_bf16 v[32:35], v[84:87], v[210:213], v[32:35]
	v_mfma_f32_16x16x32_bf16 v[56:59], v[92:95], v[164:167], v[48:51]
	v_mfma_f32_16x16x32_bf16 v[20:23], v[80:83], v[198:201], v[20:23]
	v_mfma_f32_16x16x32_bf16 v[16:19], v[92:95], v[198:201], v[16:19]
	v_mfma_f32_16x16x32_bf16 v[44:47], v[80:83], v[206:209], v[44:47]
	v_mfma_f32_16x16x32_bf16 v[40:43], v[92:95], v[206:209], v[40:43]
	v_mfma_f32_16x16x32_bf16 v[36:39], v[80:83], v[214:217], v[36:39]
	v_mfma_f32_16x16x32_bf16 v[32:35], v[92:95], v[214:217], v[32:35]
	s_barrier
	s_setprio 0
	s_add_i32 s12, s12, 2
	s_add_u32 vcc_lo, vcc_lo, 0x100
	s_addc_u32 vcc_hi, vcc_hi, 0
	s_cmp_gt_u32 s12, 13
	s_mov_b64 s[60:61], s[62:63]
.LBB0_863:
	s_add_u32 s62, s60, 0x100
	s_addc_u32 s63, s61, 0
	s_add_i32 s0, 0, 0x10000
	s_cmp_eq_u32 s12, 12
	s_cselect_b32 s67, s23, s63
	s_cselect_b32 s66, s51, s62
	s_cselect_b32 s65, s49, vcc_hi
	s_cselect_b32 s64, s57, vcc_lo
	s_add_i32 s13, 0, 0x14000
	v_add_u32_e32 v64, s0, v228
	v_add_u32_e32 v92, s13, v228
	ds_read_b128 v[48:51], v64
	ds_read_b128 v[52:55], v64 offset:1024
	ds_read_b128 v[60:63], v64 offset:2048
	ds_read_b128 v[64:67], v64 offset:3072
	ds_read_b128 v[72:75], v92
	ds_read_b128 v[80:83], v92 offset:1024
	ds_read_b128 v[84:87], v92 offset:2048
	ds_read_b128 v[92:95], v92 offset:3072
	s_add_i32 m0, s59, 0xc000
	ds_read_b128 v[112:115], v230
	ds_read_b128 v[164:167], v230 offset:1024
	ds_read_b128 v[194:197], v230 offset:2048
	ds_read_b128 v[198:201], v230 offset:3072
	ds_read_b128 v[202:205], v230 offset:4096
	ds_read_b128 v[206:209], v230 offset:5120
	ds_read_b128 v[210:213], v230 offset:6144
	ds_read_b128 v[214:217], v230 offset:7168
	global_load_lds_dwordx4 v190, s[60:61]
	s_add_i32 m0, s59, 0xe000
	s_nop 0
	global_load_lds_dwordx4 v192, s[60:61]
	s_waitcnt vmcnt(8)
	s_waitcnt lgkmcnt(0)
	s_barrier
	s_setprio 1
	v_mfma_f32_16x16x32_bf16 v[160:163], v[48:51], v[112:115], v[160:163]
	v_mfma_f32_16x16x32_bf16 v[156:159], v[60:63], v[112:115], v[156:159]
	v_mfma_f32_16x16x32_bf16 v[128:131], v[48:51], v[194:197], v[128:131]
	v_mfma_f32_16x16x32_bf16 v[124:127], v[60:63], v[194:197], v[124:127]
	v_mfma_f32_16x16x32_bf16 v[108:111], v[48:51], v[202:205], v[108:111]
	v_mfma_f32_16x16x32_bf16 v[104:107], v[60:63], v[202:205], v[104:107]
	v_mfma_f32_16x16x32_bf16 v[100:103], v[48:51], v[210:213], v[100:103]
	v_mfma_f32_16x16x32_bf16 v[96:99], v[60:63], v[210:213], v[96:99]
	v_mfma_f32_16x16x32_bf16 v[160:163], v[52:55], v[164:167], v[160:163]
	v_mfma_f32_16x16x32_bf16 v[156:159], v[64:67], v[164:167], v[156:159]
	v_mfma_f32_16x16x32_bf16 v[128:131], v[52:55], v[198:201], v[128:131]
	v_mfma_f32_16x16x32_bf16 v[124:127], v[64:67], v[198:201], v[124:127]
	v_mfma_f32_16x16x32_bf16 v[108:111], v[52:55], v[206:209], v[108:111]
	v_mfma_f32_16x16x32_bf16 v[104:107], v[64:67], v[206:209], v[104:107]
	v_mfma_f32_16x16x32_bf16 v[100:103], v[52:55], v[214:217], v[100:103]
	v_mfma_f32_16x16x32_bf16 v[96:99], v[64:67], v[214:217], v[96:99]
	v_mfma_f32_16x16x32_bf16 v[152:155], v[72:75], v[112:115], v[152:155]
	v_mfma_f32_16x16x32_bf16 v[120:123], v[72:75], v[194:197], v[120:123]
	v_mfma_f32_16x16x32_bf16 v[116:119], v[84:87], v[194:197], v[116:119]
	v_mfma_f32_16x16x32_bf16 v[144:147], v[72:75], v[202:205], v[144:147]
	v_mfma_f32_16x16x32_bf16 v[140:143], v[84:87], v[202:205], v[140:143]
	v_mfma_f32_16x16x32_bf16 v[136:139], v[72:75], v[210:213], v[136:139]
	v_mfma_f32_16x16x32_bf16 v[132:135], v[84:87], v[210:213], v[132:135]
	v_mfma_f32_16x16x32_bf16 v[152:155], v[80:83], v[164:167], v[152:155]
	v_mfma_f32_16x16x32_bf16 v[112:115], v[84:87], v[112:115], v[148:151]
	v_mfma_f32_16x16x32_bf16 v[120:123], v[80:83], v[198:201], v[120:123]
	v_mfma_f32_16x16x32_bf16 v[116:119], v[92:95], v[198:201], v[116:119]
	v_mfma_f32_16x16x32_bf16 v[144:147], v[80:83], v[206:209], v[144:147]
	v_mfma_f32_16x16x32_bf16 v[140:143], v[92:95], v[206:209], v[140:143]
	v_mfma_f32_16x16x32_bf16 v[136:139], v[80:83], v[214:217], v[136:139]
	v_mfma_f32_16x16x32_bf16 v[132:135], v[92:95], v[214:217], v[132:135]
	v_mfma_f32_16x16x32_bf16 v[112:115], v[92:95], v[164:167], v[112:115]
	s_barrier
	s_setprio 0
	s_add_i32 s0, s0, s96
	v_lshl_add_u64 v[218:219], s[64:65], 0, v[170:171]
	s_mov_b32 m0, s0
	ds_read_b128 v[148:151], v230 offset:16384
	ds_read_b128 v[164:167], v230 offset:17408
	ds_read_b128 v[194:197], v230 offset:18432
	ds_read_b128 v[198:201], v230 offset:19456
	ds_read_b128 v[202:205], v230 offset:20480
	ds_read_b128 v[206:209], v230 offset:21504
	ds_read_b128 v[210:213], v230 offset:22528
	ds_read_b128 v[214:217], v230 offset:23552
	global_load_lds_dwordx4 v[218:219], off
	s_add_i32 m0, s0, 0x2000
	s_add_u32 s0, s64, 0x40000
	v_lshl_add_u64 v[232:233], s[64:65], 0, v[188:189]
	s_addc_u32 s1, s65, 0
	s_add_i32 s13, s13, s96
	global_load_lds_dwordx4 v[232:233], off
	s_mov_b32 m0, s13
	v_lshl_add_u64 v[236:237], s[66:67], 0, v[186:187]
	global_load_lds_dwordx4 v170, s[0:1]
	s_add_i32 m0, s13, 0x2000
	s_nop 0
	global_load_lds_dwordx4 v188, s[0:1]
	v_lshl_add_u64 v[234:235], s[66:67], 0, v[184:185]
	s_waitcnt vmcnt(6)
	s_waitcnt lgkmcnt(0)
	s_barrier
	s_setprio 1
	v_mfma_f32_16x16x32_bf16 v[88:91], v[48:51], v[148:151], v[88:91]
	v_mfma_f32_16x16x32_bf16 v[76:79], v[60:63], v[148:151], v[76:79]
	v_mfma_f32_16x16x32_bf16 v[28:31], v[48:51], v[194:197], v[28:31]
	v_mfma_f32_16x16x32_bf16 v[24:27], v[60:63], v[194:197], v[24:27]
	v_mfma_f32_16x16x32_bf16 v[12:15], v[48:51], v[202:205], v[12:15]
	v_mfma_f32_16x16x32_bf16 v[8:11], v[60:63], v[202:205], v[8:11]
	v_mfma_f32_16x16x32_bf16 v[4:7], v[48:51], v[210:213], v[4:7]
	v_mfma_f32_16x16x32_bf16 v[0:3], v[60:63], v[210:213], v[0:3]
	v_mfma_f32_16x16x32_bf16 v[88:91], v[52:55], v[164:167], v[88:91]
	v_mfma_f32_16x16x32_bf16 v[76:79], v[64:67], v[164:167], v[76:79]
	v_mfma_f32_16x16x32_bf16 v[28:31], v[52:55], v[198:201], v[28:31]
	v_mfma_f32_16x16x32_bf16 v[24:27], v[64:67], v[198:201], v[24:27]
	v_mfma_f32_16x16x32_bf16 v[12:15], v[52:55], v[206:209], v[12:15]
	v_mfma_f32_16x16x32_bf16 v[8:11], v[64:67], v[206:209], v[8:11]
	v_mfma_f32_16x16x32_bf16 v[4:7], v[52:55], v[214:217], v[4:7]
	v_mfma_f32_16x16x32_bf16 v[0:3], v[64:67], v[214:217], v[0:3]
	v_mfma_f32_16x16x32_bf16 v[20:23], v[72:75], v[194:197], v[20:23]
	v_mfma_f32_16x16x32_bf16 v[16:19], v[84:87], v[194:197], v[16:19]
	v_mfma_f32_16x16x32_bf16 v[44:47], v[72:75], v[202:205], v[44:47]
	v_mfma_f32_16x16x32_bf16 v[40:43], v[84:87], v[202:205], v[40:43]
	v_mfma_f32_16x16x32_bf16 v[36:39], v[72:75], v[210:213], v[36:39]
	v_mfma_f32_16x16x32_bf16 v[32:35], v[84:87], v[210:213], v[32:35]
	v_mfma_f32_16x16x32_bf16 v[48:51], v[72:75], v[148:151], v[68:71]
	v_mfma_f32_16x16x32_bf16 v[52:55], v[84:87], v[148:151], v[56:59]
	v_mfma_f32_16x16x32_bf16 v[20:23], v[80:83], v[198:201], v[20:23]
	v_mfma_f32_16x16x32_bf16 v[16:19], v[92:95], v[198:201], v[16:19]
	v_mfma_f32_16x16x32_bf16 v[44:47], v[80:83], v[206:209], v[44:47]
	v_mfma_f32_16x16x32_bf16 v[40:43], v[92:95], v[206:209], v[40:43]
	v_mfma_f32_16x16x32_bf16 v[36:39], v[80:83], v[214:217], v[36:39]
	v_mfma_f32_16x16x32_bf16 v[32:35], v[92:95], v[214:217], v[32:35]
	v_mfma_f32_16x16x32_bf16 v[48:51], v[80:83], v[164:167], v[48:51]
	v_mfma_f32_16x16x32_bf16 v[52:55], v[92:95], v[164:167], v[52:55]
	s_barrier
	s_setprio 0
	s_add_i32 s13, 0, 0x18000
	s_add_i32 s60, 0, 0x1c000
	v_add_u32_e32 v68, s13, v228
	v_add_u32_e32 v92, s60, v228
	ds_read_b128 v[56:59], v68
	ds_read_b128 v[60:63], v68 offset:1024
	ds_read_b128 v[64:67], v68 offset:2048
	ds_read_b128 v[68:71], v68 offset:3072
	ds_read_b128 v[72:75], v92
	ds_read_b128 v[80:83], v92 offset:1024
	ds_read_b128 v[84:87], v92 offset:2048
	ds_read_b128 v[92:95], v92 offset:3072
	s_add_u32 s0, s66, 0x40000
	s_addc_u32 s1, s67, 0
	s_mov_b32 m0, s39
	ds_read_b128 v[148:151], v230 offset:32768
	ds_read_b128 v[164:167], v230 offset:33792
	ds_read_b128 v[194:197], v230 offset:34816
	ds_read_b128 v[198:201], v230 offset:35840
	ds_read_b128 v[202:205], v230 offset:36864
	ds_read_b128 v[206:209], v230 offset:37888
	ds_read_b128 v[210:213], v230 offset:38912
	ds_read_b128 v[214:217], v230 offset:39936
	global_load_lds_dwordx4 v184, s[0:1]
	s_mov_b32 m0, s76
	s_nop 0
	global_load_lds_dwordx4 v186, s[0:1]
	s_mov_b32 m0, s59
	s_nop 0
	global_load_lds_dwordx4 v[234:235], off
	s_mov_b32 m0, s97
	s_nop 0
	global_load_lds_dwordx4 v[236:237], off
	s_waitcnt vmcnt(8)
	s_waitcnt lgkmcnt(0)
	s_barrier
	s_setprio 1
	v_mfma_f32_16x16x32_bf16 v[160:163], v[56:59], v[148:151], v[160:163]
	v_mfma_f32_16x16x32_bf16 v[156:159], v[64:67], v[148:151], v[156:159]
	v_mfma_f32_16x16x32_bf16 v[128:131], v[56:59], v[194:197], v[128:131]
	v_mfma_f32_16x16x32_bf16 v[124:127], v[64:67], v[194:197], v[124:127]
	v_mfma_f32_16x16x32_bf16 v[108:111], v[56:59], v[202:205], v[108:111]
	v_mfma_f32_16x16x32_bf16 v[104:107], v[64:67], v[202:205], v[104:107]
	v_mfma_f32_16x16x32_bf16 v[100:103], v[56:59], v[210:213], v[100:103]
	v_mfma_f32_16x16x32_bf16 v[96:99], v[64:67], v[210:213], v[96:99]
	v_mfma_f32_16x16x32_bf16 v[160:163], v[60:63], v[164:167], v[160:163]
	v_mfma_f32_16x16x32_bf16 v[156:159], v[68:71], v[164:167], v[156:159]
	v_mfma_f32_16x16x32_bf16 v[128:131], v[60:63], v[198:201], v[128:131]
	v_mfma_f32_16x16x32_bf16 v[124:127], v[68:71], v[198:201], v[124:127]
	v_mfma_f32_16x16x32_bf16 v[108:111], v[60:63], v[206:209], v[108:111]
	v_mfma_f32_16x16x32_bf16 v[104:107], v[68:71], v[206:209], v[104:107]
	v_mfma_f32_16x16x32_bf16 v[100:103], v[60:63], v[214:217], v[100:103]
	v_mfma_f32_16x16x32_bf16 v[96:99], v[68:71], v[214:217], v[96:99]
	v_mfma_f32_16x16x32_bf16 v[112:115], v[84:87], v[148:151], v[112:115]
	v_mfma_f32_16x16x32_bf16 v[152:155], v[72:75], v[148:151], v[152:155]
	v_mfma_f32_16x16x32_bf16 v[148:151], v[92:95], v[164:167], v[112:115]
	v_mfma_f32_16x16x32_bf16 v[112:115], v[72:75], v[194:197], v[120:123]
	v_mfma_f32_16x16x32_bf16 v[120:123], v[80:83], v[198:201], v[112:115]
	v_mfma_f32_16x16x32_bf16 v[112:115], v[84:87], v[194:197], v[116:119]
	v_mfma_f32_16x16x32_bf16 v[116:119], v[92:95], v[198:201], v[112:115]
	v_mfma_f32_16x16x32_bf16 v[112:115], v[72:75], v[202:205], v[144:147]
	v_mfma_f32_16x16x32_bf16 v[144:147], v[80:83], v[206:209], v[112:115]
	v_mfma_f32_16x16x32_bf16 v[112:115], v[84:87], v[202:205], v[140:143]
	v_mfma_f32_16x16x32_bf16 v[140:143], v[92:95], v[206:209], v[112:115]
	v_mfma_f32_16x16x32_bf16 v[112:115], v[72:75], v[210:213], v[136:139]
	v_mfma_f32_16x16x32_bf16 v[136:139], v[80:83], v[214:217], v[112:115]
	v_mfma_f32_16x16x32_bf16 v[112:115], v[84:87], v[210:213], v[132:135]
	v_mfma_f32_16x16x32_bf16 v[152:155], v[80:83], v[164:167], v[152:155]
	v_mfma_f32_16x16x32_bf16 v[132:135], v[92:95], v[214:217], v[112:115]
	s_barrier
	s_setprio 0
	s_add_i32 s0, s13, s96
	v_lshl_add_u64 v[218:219], v[218:219], 0, s[16:17]
	s_mov_b32 m0, s0
	s_nop 0
	ds_read_b128 v[112:115], v230 offset:49152
	ds_read_b128 v[164:167], v230 offset:50176
	ds_read_b128 v[194:197], v230 offset:51200
	ds_read_b128 v[198:201], v230 offset:52224
	ds_read_b128 v[202:205], v230 offset:53248
	ds_read_b128 v[206:209], v230 offset:54272
	ds_read_b128 v[210:213], v230 offset:55296
	ds_read_b128 v[214:217], v230 offset:56320
	global_load_lds_dwordx4 v[218:219], off
	s_add_i32 m0, s0, 0x2000
	s_add_u32 s0, s64, 0x40080
	v_lshl_add_u64 v[218:219], v[232:233], 0, s[16:17]
	s_addc_u32 s1, s65, 0
	s_add_i32 s13, s60, s96
	global_load_lds_dwordx4 v[218:219], off
	s_mov_b32 m0, s13
	s_nop 0
	global_load_lds_dwordx4 v170, s[0:1]
	s_add_i32 m0, s13, 0x2000
	s_nop 0
	global_load_lds_dwordx4 v188, s[0:1]
	v_lshl_add_u64 v[218:219], v[234:235], 0, s[16:17]
	s_mov_b32 m0, s75
	s_nop 0
	global_load_lds_dwordx4 v[218:219], off
	v_lshl_add_u64 v[218:219], v[236:237], 0, s[16:17]
	s_mov_b32 m0, s91
	s_nop 0
	global_load_lds_dwordx4 v[218:219], off
	s_waitcnt vmcnt(6)
	s_waitcnt lgkmcnt(0)
	s_barrier
	s_setprio 1
	v_mfma_f32_16x16x32_bf16 v[88:91], v[56:59], v[112:115], v[88:91]
	v_mfma_f32_16x16x32_bf16 v[76:79], v[64:67], v[112:115], v[76:79]
	v_mfma_f32_16x16x32_bf16 v[28:31], v[56:59], v[194:197], v[28:31]
	v_mfma_f32_16x16x32_bf16 v[24:27], v[64:67], v[194:197], v[24:27]
	v_mfma_f32_16x16x32_bf16 v[12:15], v[56:59], v[202:205], v[12:15]
	v_mfma_f32_16x16x32_bf16 v[8:11], v[64:67], v[202:205], v[8:11]
	v_mfma_f32_16x16x32_bf16 v[4:7], v[56:59], v[210:213], v[4:7]
	v_mfma_f32_16x16x32_bf16 v[0:3], v[64:67], v[210:213], v[0:3]
	v_mfma_f32_16x16x32_bf16 v[88:91], v[60:63], v[164:167], v[88:91]
	v_mfma_f32_16x16x32_bf16 v[76:79], v[68:71], v[164:167], v[76:79]
	v_mfma_f32_16x16x32_bf16 v[28:31], v[60:63], v[198:201], v[28:31]
	v_mfma_f32_16x16x32_bf16 v[24:27], v[68:71], v[198:201], v[24:27]
	v_mfma_f32_16x16x32_bf16 v[12:15], v[60:63], v[206:209], v[12:15]
	v_mfma_f32_16x16x32_bf16 v[8:11], v[68:71], v[206:209], v[8:11]
	v_mfma_f32_16x16x32_bf16 v[4:7], v[60:63], v[214:217], v[4:7]
	v_mfma_f32_16x16x32_bf16 v[0:3], v[68:71], v[214:217], v[0:3]
	v_mfma_f32_16x16x32_bf16 v[48:51], v[72:75], v[112:115], v[48:51]
	v_mfma_f32_16x16x32_bf16 v[68:71], v[80:83], v[164:167], v[48:51]
	v_mfma_f32_16x16x32_bf16 v[48:51], v[84:87], v[112:115], v[52:55]
	v_mfma_f32_16x16x32_bf16 v[20:23], v[72:75], v[194:197], v[20:23]
	v_mfma_f32_16x16x32_bf16 v[16:19], v[84:87], v[194:197], v[16:19]
	v_mfma_f32_16x16x32_bf16 v[44:47], v[72:75], v[202:205], v[44:47]
	v_mfma_f32_16x16x32_bf16 v[40:43], v[84:87], v[202:205], v[40:43]
	v_mfma_f32_16x16x32_bf16 v[36:39], v[72:75], v[210:213], v[36:39]
	v_mfma_f32_16x16x32_bf16 v[32:35], v[84:87], v[210:213], v[32:35]
	v_mfma_f32_16x16x32_bf16 v[56:59], v[92:95], v[164:167], v[48:51]
	v_mfma_f32_16x16x32_bf16 v[20:23], v[80:83], v[198:201], v[20:23]
	v_mfma_f32_16x16x32_bf16 v[16:19], v[92:95], v[198:201], v[16:19]
	v_mfma_f32_16x16x32_bf16 v[44:47], v[80:83], v[206:209], v[44:47]
	v_mfma_f32_16x16x32_bf16 v[40:43], v[92:95], v[206:209], v[40:43]
	v_mfma_f32_16x16x32_bf16 v[36:39], v[80:83], v[214:217], v[36:39]
	v_mfma_f32_16x16x32_bf16 v[32:35], v[92:95], v[214:217], v[32:35]
	s_barrier
	s_setprio 0
	s_add_i32 s12, s12, 2
	s_add_u32 vcc_lo, vcc_lo, 0x100
	s_addc_u32 vcc_hi, vcc_hi, 0
	s_cmp_gt_u32 s12, 13
	s_mov_b64 s[60:61], s[62:63]
	s_cbranch_scc0 .LBB0_863
	s_and_b64 vcc, exec, s[42:43]
	s_cbranch_vccz .LBB0_866
	s_barrier

.Lrestag_1029:
	s_add_u32 s34, s30, 0x100
	s_addc_u32 s35, s31, 0
	s_add_i32 s0, 0, 0x10000
	s_cmp_eq_u32 s12, 40
	s_cselect_b32 s41, s7, s35
	s_cselect_b32 s40, s6, s34
	v_add_u32_e32 v150, s0, v153
	s_cselect_b32 s37, s27, s55
	s_cselect_b32 s36, s26, s54
	s_add_i32 s13, 0, 0x14000
	ds_read_b128 v[128:131], v150
	ds_read_b128 v[146:149], v150 offset:1024
	ds_read_b128 v[156:159], v150 offset:2048
	ds_read_b128 v[160:163], v150 offset:3072
	v_add_u32_e32 v150, s13, v153
	ds_read_b128 v[164:167], v150
	ds_read_b128 v[184:187], v150 offset:1024
	ds_read_b128 v[188:191], v150 offset:2048
	ds_read_b128 v[192:195], v150 offset:3072
	s_add_i32 m0, s43, 0xc000
	ds_read_b128 v[196:199], v154
	ds_read_b128 v[200:203], v154 offset:1024
	ds_read_b128 v[204:207], v154 offset:2048
	ds_read_b128 v[208:211], v154 offset:3072
	ds_read_b128 v[212:215], v154 offset:4096
	ds_read_b128 v[216:219], v154 offset:5120
	ds_read_b128 v[228:231], v154 offset:6144
	ds_read_b128 v[232:235], v154 offset:7168
	global_load_lds_dwordx4 v142, s[30:31]
	s_add_i32 m0, s43, 0xe000
	s_nop 0
	global_load_lds_dwordx4 v144, s[30:31]
	s_nop 0
	s_waitcnt lgkmcnt(0)
	s_barrier
	s_setprio 1
	v_mfma_f32_16x16x32_bf16 v[124:127], v[128:131], v[196:199], 0
	v_mfma_f32_16x16x32_bf16 v[120:123], v[156:159], v[196:199], 0
	v_mfma_f32_16x16x32_bf16 v[112:115], v[128:131], v[204:207], 0
	v_mfma_f32_16x16x32_bf16 v[104:107], v[156:159], v[204:207], 0
	v_mfma_f32_16x16x32_bf16 v[96:99], v[128:131], v[212:215], 0
	v_mfma_f32_16x16x32_bf16 v[88:91], v[156:159], v[212:215], 0
	v_mfma_f32_16x16x32_bf16 v[80:83], v[128:131], v[228:231], 0
	v_mfma_f32_16x16x32_bf16 v[72:75], v[156:159], v[228:231], 0
	v_mfma_f32_16x16x32_bf16 v[124:127], v[146:149], v[200:203], v[124:127]
	v_mfma_f32_16x16x32_bf16 v[120:123], v[160:163], v[200:203], v[120:123]
	v_mfma_f32_16x16x32_bf16 v[112:115], v[146:149], v[208:211], v[112:115]
	v_mfma_f32_16x16x32_bf16 v[104:107], v[160:163], v[208:211], v[104:107]
	v_mfma_f32_16x16x32_bf16 v[96:99], v[146:149], v[216:219], v[96:99]
	v_mfma_f32_16x16x32_bf16 v[88:91], v[160:163], v[216:219], v[88:91]
	v_mfma_f32_16x16x32_bf16 v[80:83], v[146:149], v[232:235], v[80:83]
	v_mfma_f32_16x16x32_bf16 v[72:75], v[160:163], v[232:235], v[72:75]
	v_mfma_f32_16x16x32_bf16 v[116:119], v[164:167], v[196:199], 0
	v_mfma_f32_16x16x32_bf16 v[108:111], v[188:191], v[196:199], 0
	v_mfma_f32_16x16x32_bf16 v[100:103], v[164:167], v[204:207], 0
	v_mfma_f32_16x16x32_bf16 v[92:95], v[188:191], v[204:207], 0
	v_mfma_f32_16x16x32_bf16 v[84:87], v[164:167], v[212:215], 0
	v_mfma_f32_16x16x32_bf16 v[76:79], v[188:191], v[212:215], 0
	v_mfma_f32_16x16x32_bf16 v[68:71], v[164:167], v[228:231], 0
	v_mfma_f32_16x16x32_bf16 v[64:67], v[188:191], v[228:231], 0
	v_mfma_f32_16x16x32_bf16 v[116:119], v[184:187], v[200:203], v[116:119]
	v_mfma_f32_16x16x32_bf16 v[108:111], v[192:195], v[200:203], v[108:111]
	v_mfma_f32_16x16x32_bf16 v[100:103], v[184:187], v[208:211], v[100:103]
	v_mfma_f32_16x16x32_bf16 v[92:95], v[192:195], v[208:211], v[92:95]
	v_mfma_f32_16x16x32_bf16 v[84:87], v[184:187], v[216:219], v[84:87]
	v_mfma_f32_16x16x32_bf16 v[76:79], v[192:195], v[216:219], v[76:79]
	v_mfma_f32_16x16x32_bf16 v[68:71], v[184:187], v[232:235], v[68:71]
	v_mfma_f32_16x16x32_bf16 v[64:67], v[192:195], v[232:235], v[64:67]
	s_barrier
	s_setprio 0
	s_add_i32 s0, s0, s42
	v_lshl_add_u64 v[150:151], s[36:37], 0, v[170:171]
	s_mov_b32 m0, s0
	ds_read_b128 v[196:199], v154 offset:16384
	ds_read_b128 v[200:203], v154 offset:17408
	ds_read_b128 v[204:207], v154 offset:18432
	ds_read_b128 v[208:211], v154 offset:19456
	ds_read_b128 v[212:215], v154 offset:20480
	ds_read_b128 v[216:219], v154 offset:21504
	ds_read_b128 v[228:231], v154 offset:22528
	ds_read_b128 v[232:235], v154 offset:23552
	global_load_lds_dwordx4 v[150:151], off
	s_add_i32 m0, s0, 0x2000
	s_add_u32 s0, s36, 0xb0000
	v_lshl_add_u64 v[236:237], s[36:37], 0, v[136:137]
	s_addc_u32 s1, s37, 0
	s_add_i32 s13, s13, s42
	global_load_lds_dwordx4 v[236:237], off
	s_mov_b32 m0, s13
	v_lshl_add_u64 v[240:241], s[40:41], 0, v[134:135]
	global_load_lds_dwordx4 v170, s[0:1]
	s_add_i32 m0, s13, 0x2000
	s_nop 0
	global_load_lds_dwordx4 v136, s[0:1]
	v_lshl_add_u64 v[238:239], s[40:41], 0, v[132:133]
	s_nop 0
	s_waitcnt lgkmcnt(0)
	s_barrier
	s_setprio 1
	v_mfma_f32_16x16x32_bf16 v[60:63], v[128:131], v[196:199], 0
	v_mfma_f32_16x16x32_bf16 v[56:59], v[156:159], v[196:199], 0
	v_mfma_f32_16x16x32_bf16 v[48:51], v[128:131], v[204:207], 0
	v_mfma_f32_16x16x32_bf16 v[40:43], v[156:159], v[204:207], 0
	v_mfma_f32_16x16x32_bf16 v[32:35], v[128:131], v[212:215], 0
	v_mfma_f32_16x16x32_bf16 v[24:27], v[156:159], v[212:215], 0
	v_mfma_f32_16x16x32_bf16 v[16:19], v[128:131], v[228:231], 0
	v_mfma_f32_16x16x32_bf16 v[8:11], v[156:159], v[228:231], 0
	v_mfma_f32_16x16x32_bf16 v[60:63], v[146:149], v[200:203], v[60:63]
	v_mfma_f32_16x16x32_bf16 v[56:59], v[160:163], v[200:203], v[56:59]
	v_mfma_f32_16x16x32_bf16 v[48:51], v[146:149], v[208:211], v[48:51]
	v_mfma_f32_16x16x32_bf16 v[40:43], v[160:163], v[208:211], v[40:43]
	v_mfma_f32_16x16x32_bf16 v[32:35], v[146:149], v[216:219], v[32:35]
	v_mfma_f32_16x16x32_bf16 v[24:27], v[160:163], v[216:219], v[24:27]
	v_mfma_f32_16x16x32_bf16 v[16:19], v[146:149], v[232:235], v[16:19]
	v_mfma_f32_16x16x32_bf16 v[8:11], v[160:163], v[232:235], v[8:11]
	v_mfma_f32_16x16x32_bf16 v[52:55], v[164:167], v[196:199], 0
	v_mfma_f32_16x16x32_bf16 v[44:47], v[188:191], v[196:199], 0
	v_mfma_f32_16x16x32_bf16 v[36:39], v[164:167], v[204:207], 0
	v_mfma_f32_16x16x32_bf16 v[28:31], v[188:191], v[204:207], 0
	v_mfma_f32_16x16x32_bf16 v[20:23], v[164:167], v[212:215], 0
	v_mfma_f32_16x16x32_bf16 v[12:15], v[188:191], v[212:215], 0
	v_mfma_f32_16x16x32_bf16 v[4:7], v[164:167], v[228:231], 0
	v_mfma_f32_16x16x32_bf16 v[0:3], v[188:191], v[228:231], 0
	v_mfma_f32_16x16x32_bf16 v[52:55], v[184:187], v[200:203], v[52:55]
	v_mfma_f32_16x16x32_bf16 v[44:47], v[192:195], v[200:203], v[44:47]
	v_mfma_f32_16x16x32_bf16 v[36:39], v[184:187], v[208:211], v[36:39]
	v_mfma_f32_16x16x32_bf16 v[28:31], v[192:195], v[208:211], v[28:31]
	v_mfma_f32_16x16x32_bf16 v[20:23], v[184:187], v[216:219], v[20:23]
	v_mfma_f32_16x16x32_bf16 v[12:15], v[192:195], v[216:219], v[12:15]
	v_mfma_f32_16x16x32_bf16 v[4:7], v[184:187], v[232:235], v[4:7]
	v_mfma_f32_16x16x32_bf16 v[0:3], v[192:195], v[232:235], v[0:3]
	s_barrier
	s_setprio 0
	s_add_i32 s13, 0, 0x18000
	v_add_u32_e32 v155, s13, v153
	s_add_i32 s30, 0, 0x1c000
	ds_read_b128 v[128:131], v155
	ds_read_b128 v[146:149], v155 offset:1024
	ds_read_b128 v[156:159], v155 offset:2048
	ds_read_b128 v[160:163], v155 offset:3072
	v_add_u32_e32 v155, s30, v153
	ds_read_b128 v[164:167], v155
	ds_read_b128 v[184:187], v155 offset:1024
	ds_read_b128 v[188:191], v155 offset:2048
	ds_read_b128 v[192:195], v155 offset:3072
	s_add_u32 s0, s40, 0xb0000
	s_addc_u32 s1, s41, 0
	s_mov_b32 m0, s45
	ds_read_b128 v[196:199], v154 offset:32768
	ds_read_b128 v[200:203], v154 offset:33792
	ds_read_b128 v[204:207], v154 offset:34816
	ds_read_b128 v[208:211], v154 offset:35840
	ds_read_b128 v[212:215], v154 offset:36864
	ds_read_b128 v[216:219], v154 offset:37888
	ds_read_b128 v[228:231], v154 offset:38912
	ds_read_b128 v[232:235], v154 offset:39936
	global_load_lds_dwordx4 v132, s[0:1]
	s_mov_b32 m0, s46
	s_nop 0
	global_load_lds_dwordx4 v134, s[0:1]
	s_mov_b32 m0, s43
	s_nop 0
	global_load_lds_dwordx4 v[238:239], off
	s_mov_b32 m0, s44
	s_nop 0
	global_load_lds_dwordx4 v[240:241], off
	s_waitcnt vmcnt(8)
	s_waitcnt lgkmcnt(0)
	s_barrier
	s_setprio 1
	v_mfma_f32_16x16x32_bf16 v[124:127], v[128:131], v[196:199], v[124:127]
	v_mfma_f32_16x16x32_bf16 v[120:123], v[156:159], v[196:199], v[120:123]
	v_mfma_f32_16x16x32_bf16 v[112:115], v[128:131], v[204:207], v[112:115]
	v_mfma_f32_16x16x32_bf16 v[104:107], v[156:159], v[204:207], v[104:107]
	v_mfma_f32_16x16x32_bf16 v[96:99], v[128:131], v[212:215], v[96:99]
	v_mfma_f32_16x16x32_bf16 v[88:91], v[156:159], v[212:215], v[88:91]
	v_mfma_f32_16x16x32_bf16 v[80:83], v[128:131], v[228:231], v[80:83]
	v_mfma_f32_16x16x32_bf16 v[72:75], v[156:159], v[228:231], v[72:75]
	v_mfma_f32_16x16x32_bf16 v[124:127], v[146:149], v[200:203], v[124:127]
	v_mfma_f32_16x16x32_bf16 v[120:123], v[160:163], v[200:203], v[120:123]
	v_mfma_f32_16x16x32_bf16 v[112:115], v[146:149], v[208:211], v[112:115]
	v_mfma_f32_16x16x32_bf16 v[104:107], v[160:163], v[208:211], v[104:107]
	v_mfma_f32_16x16x32_bf16 v[96:99], v[146:149], v[216:219], v[96:99]
	v_mfma_f32_16x16x32_bf16 v[88:91], v[160:163], v[216:219], v[88:91]
	v_mfma_f32_16x16x32_bf16 v[80:83], v[146:149], v[232:235], v[80:83]
	v_mfma_f32_16x16x32_bf16 v[72:75], v[160:163], v[232:235], v[72:75]
	v_mfma_f32_16x16x32_bf16 v[116:119], v[164:167], v[196:199], v[116:119]
	v_mfma_f32_16x16x32_bf16 v[108:111], v[188:191], v[196:199], v[108:111]
	v_mfma_f32_16x16x32_bf16 v[100:103], v[164:167], v[204:207], v[100:103]
	v_mfma_f32_16x16x32_bf16 v[92:95], v[188:191], v[204:207], v[92:95]
	v_mfma_f32_16x16x32_bf16 v[84:87], v[164:167], v[212:215], v[84:87]
	v_mfma_f32_16x16x32_bf16 v[76:79], v[188:191], v[212:215], v[76:79]
	v_mfma_f32_16x16x32_bf16 v[68:71], v[164:167], v[228:231], v[68:71]
	v_mfma_f32_16x16x32_bf16 v[64:67], v[188:191], v[228:231], v[64:67]
	v_mfma_f32_16x16x32_bf16 v[116:119], v[184:187], v[200:203], v[116:119]
	v_mfma_f32_16x16x32_bf16 v[108:111], v[192:195], v[200:203], v[108:111]
	v_mfma_f32_16x16x32_bf16 v[100:103], v[184:187], v[208:211], v[100:103]
	v_mfma_f32_16x16x32_bf16 v[92:95], v[192:195], v[208:211], v[92:95]
	v_mfma_f32_16x16x32_bf16 v[84:87], v[184:187], v[216:219], v[84:87]
	v_mfma_f32_16x16x32_bf16 v[76:79], v[192:195], v[216:219], v[76:79]
	v_mfma_f32_16x16x32_bf16 v[68:71], v[184:187], v[232:235], v[68:71]
	v_mfma_f32_16x16x32_bf16 v[64:67], v[192:195], v[232:235], v[64:67]
	s_barrier
	s_setprio 0
	s_add_i32 s0, s13, s42
	v_lshl_add_u64 v[150:151], v[150:151], 0, s[16:17]
	s_mov_b32 m0, s0
	ds_read_b128 v[196:199], v154 offset:49152
	ds_read_b128 v[200:203], v154 offset:50176
	ds_read_b128 v[204:207], v154 offset:51200
	ds_read_b128 v[208:211], v154 offset:52224
	ds_read_b128 v[212:215], v154 offset:53248
	ds_read_b128 v[216:219], v154 offset:54272
	ds_read_b128 v[228:231], v154 offset:55296
	ds_read_b128 v[232:235], v154 offset:56320
	global_load_lds_dwordx4 v[150:151], off
	s_add_i32 m0, s0, 0x2000
	s_add_u32 s0, s36, 0xb0080
	v_lshl_add_u64 v[150:151], v[236:237], 0, s[16:17]
	s_addc_u32 s1, s37, 0
	s_add_i32 s13, s30, s42
	global_load_lds_dwordx4 v[150:151], off
	s_mov_b32 m0, s13
	s_nop 0
	global_load_lds_dwordx4 v170, s[0:1]
	s_add_i32 m0, s13, 0x2000
	s_nop 0
	global_load_lds_dwordx4 v136, s[0:1]
	v_lshl_add_u64 v[150:151], v[238:239], 0, s[16:17]
	s_mov_b32 m0, s47
	s_nop 0
	global_load_lds_dwordx4 v[150:151], off
	v_lshl_add_u64 v[150:151], v[240:241], 0, s[16:17]
	s_mov_b32 m0, s48
	s_nop 0
	global_load_lds_dwordx4 v[150:151], off
	s_waitcnt vmcnt(6)
	s_waitcnt lgkmcnt(0)
	s_barrier
	s_setprio 1
	v_mfma_f32_16x16x32_bf16 v[60:63], v[128:131], v[196:199], v[60:63]
	v_mfma_f32_16x16x32_bf16 v[56:59], v[156:159], v[196:199], v[56:59]
	v_mfma_f32_16x16x32_bf16 v[48:51], v[128:131], v[204:207], v[48:51]
	v_mfma_f32_16x16x32_bf16 v[40:43], v[156:159], v[204:207], v[40:43]
	v_mfma_f32_16x16x32_bf16 v[32:35], v[128:131], v[212:215], v[32:35]
	v_mfma_f32_16x16x32_bf16 v[24:27], v[156:159], v[212:215], v[24:27]
	v_mfma_f32_16x16x32_bf16 v[16:19], v[128:131], v[228:231], v[16:19]
	v_mfma_f32_16x16x32_bf16 v[8:11], v[156:159], v[228:231], v[8:11]
	v_mfma_f32_16x16x32_bf16 v[60:63], v[146:149], v[200:203], v[60:63]
	v_mfma_f32_16x16x32_bf16 v[56:59], v[160:163], v[200:203], v[56:59]
	v_mfma_f32_16x16x32_bf16 v[48:51], v[146:149], v[208:211], v[48:51]
	v_mfma_f32_16x16x32_bf16 v[40:43], v[160:163], v[208:211], v[40:43]
	v_mfma_f32_16x16x32_bf16 v[32:35], v[146:149], v[216:219], v[32:35]
	v_mfma_f32_16x16x32_bf16 v[24:27], v[160:163], v[216:219], v[24:27]
	v_mfma_f32_16x16x32_bf16 v[16:19], v[146:149], v[232:235], v[16:19]
	v_mfma_f32_16x16x32_bf16 v[8:11], v[160:163], v[232:235], v[8:11]
	v_mfma_f32_16x16x32_bf16 v[52:55], v[164:167], v[196:199], v[52:55]
	v_mfma_f32_16x16x32_bf16 v[44:47], v[188:191], v[196:199], v[44:47]
	v_mfma_f32_16x16x32_bf16 v[36:39], v[164:167], v[204:207], v[36:39]
	v_mfma_f32_16x16x32_bf16 v[28:31], v[188:191], v[204:207], v[28:31]
	v_mfma_f32_16x16x32_bf16 v[20:23], v[164:167], v[212:215], v[20:23]
	v_mfma_f32_16x16x32_bf16 v[12:15], v[188:191], v[212:215], v[12:15]
	v_mfma_f32_16x16x32_bf16 v[4:7], v[164:167], v[228:231], v[4:7]
	v_mfma_f32_16x16x32_bf16 v[0:3], v[188:191], v[228:231], v[0:3]
	v_mfma_f32_16x16x32_bf16 v[52:55], v[184:187], v[200:203], v[52:55]
	v_mfma_f32_16x16x32_bf16 v[44:47], v[192:195], v[200:203], v[44:47]
	v_mfma_f32_16x16x32_bf16 v[36:39], v[184:187], v[208:211], v[36:39]
	v_mfma_f32_16x16x32_bf16 v[28:31], v[192:195], v[208:211], v[28:31]
	v_mfma_f32_16x16x32_bf16 v[20:23], v[184:187], v[216:219], v[20:23]
	v_mfma_f32_16x16x32_bf16 v[12:15], v[192:195], v[216:219], v[12:15]
	v_mfma_f32_16x16x32_bf16 v[4:7], v[184:187], v[232:235], v[4:7]
	v_mfma_f32_16x16x32_bf16 v[0:3], v[192:195], v[232:235], v[0:3]
	s_barrier
	s_setprio 0
	s_add_i32 s12, s12, 2
	s_add_u32 s54, s54, 0x100
	s_addc_u32 s55, s55, 0
	s_cmp_gt_u32 s12, 41
	s_mov_b64 s[30:31], s[34:35]
.LBB0_1029:
	s_add_u32 s34, s30, 0x100
	s_addc_u32 s35, s31, 0
	s_add_i32 s0, 0, 0x10000
	s_cmp_eq_u32 s12, 40
	s_cselect_b32 s41, s7, s35
	s_cselect_b32 s40, s6, s34
	v_add_u32_e32 v150, s0, v153
	s_cselect_b32 s37, s27, s55
	s_cselect_b32 s36, s26, s54
	s_add_i32 s13, 0, 0x14000
	ds_read_b128 v[128:131], v150
	ds_read_b128 v[146:149], v150 offset:1024
	ds_read_b128 v[156:159], v150 offset:2048
	ds_read_b128 v[160:163], v150 offset:3072
	v_add_u32_e32 v150, s13, v153
	ds_read_b128 v[164:167], v150
	ds_read_b128 v[184:187], v150 offset:1024
	ds_read_b128 v[188:191], v150 offset:2048
	ds_read_b128 v[192:195], v150 offset:3072
	s_add_i32 m0, s43, 0xc000
	ds_read_b128 v[196:199], v154
	ds_read_b128 v[200:203], v154 offset:1024
	ds_read_b128 v[204:207], v154 offset:2048
	ds_read_b128 v[208:211], v154 offset:3072
	ds_read_b128 v[212:215], v154 offset:4096
	ds_read_b128 v[216:219], v154 offset:5120
	ds_read_b128 v[228:231], v154 offset:6144
	ds_read_b128 v[232:235], v154 offset:7168
	global_load_lds_dwordx4 v142, s[30:31]
	s_add_i32 m0, s43, 0xe000
	s_nop 0
	global_load_lds_dwordx4 v144, s[30:31]
	s_waitcnt vmcnt(8)
	s_waitcnt lgkmcnt(0)
	s_barrier
	s_setprio 1
	v_mfma_f32_16x16x32_bf16 v[124:127], v[128:131], v[196:199], v[124:127]
	v_mfma_f32_16x16x32_bf16 v[120:123], v[156:159], v[196:199], v[120:123]
	v_mfma_f32_16x16x32_bf16 v[112:115], v[128:131], v[204:207], v[112:115]
	v_mfma_f32_16x16x32_bf16 v[104:107], v[156:159], v[204:207], v[104:107]
	v_mfma_f32_16x16x32_bf16 v[96:99], v[128:131], v[212:215], v[96:99]
	v_mfma_f32_16x16x32_bf16 v[88:91], v[156:159], v[212:215], v[88:91]
	v_mfma_f32_16x16x32_bf16 v[80:83], v[128:131], v[228:231], v[80:83]
	v_mfma_f32_16x16x32_bf16 v[72:75], v[156:159], v[228:231], v[72:75]
	v_mfma_f32_16x16x32_bf16 v[124:127], v[146:149], v[200:203], v[124:127]
	v_mfma_f32_16x16x32_bf16 v[120:123], v[160:163], v[200:203], v[120:123]
	v_mfma_f32_16x16x32_bf16 v[112:115], v[146:149], v[208:211], v[112:115]
	v_mfma_f32_16x16x32_bf16 v[104:107], v[160:163], v[208:211], v[104:107]
	v_mfma_f32_16x16x32_bf16 v[96:99], v[146:149], v[216:219], v[96:99]
	v_mfma_f32_16x16x32_bf16 v[88:91], v[160:163], v[216:219], v[88:91]
	v_mfma_f32_16x16x32_bf16 v[80:83], v[146:149], v[232:235], v[80:83]
	v_mfma_f32_16x16x32_bf16 v[72:75], v[160:163], v[232:235], v[72:75]
	v_mfma_f32_16x16x32_bf16 v[116:119], v[164:167], v[196:199], v[116:119]
	v_mfma_f32_16x16x32_bf16 v[108:111], v[188:191], v[196:199], v[108:111]
	v_mfma_f32_16x16x32_bf16 v[100:103], v[164:167], v[204:207], v[100:103]
	v_mfma_f32_16x16x32_bf16 v[92:95], v[188:191], v[204:207], v[92:95]
	v_mfma_f32_16x16x32_bf16 v[84:87], v[164:167], v[212:215], v[84:87]
	v_mfma_f32_16x16x32_bf16 v[76:79], v[188:191], v[212:215], v[76:79]
	v_mfma_f32_16x16x32_bf16 v[68:71], v[164:167], v[228:231], v[68:71]
	v_mfma_f32_16x16x32_bf16 v[64:67], v[188:191], v[228:231], v[64:67]
	v_mfma_f32_16x16x32_bf16 v[116:119], v[184:187], v[200:203], v[116:119]
	v_mfma_f32_16x16x32_bf16 v[108:111], v[192:195], v[200:203], v[108:111]
	v_mfma_f32_16x16x32_bf16 v[100:103], v[184:187], v[208:211], v[100:103]
	v_mfma_f32_16x16x32_bf16 v[92:95], v[192:195], v[208:211], v[92:95]
	v_mfma_f32_16x16x32_bf16 v[84:87], v[184:187], v[216:219], v[84:87]
	v_mfma_f32_16x16x32_bf16 v[76:79], v[192:195], v[216:219], v[76:79]
	v_mfma_f32_16x16x32_bf16 v[68:71], v[184:187], v[232:235], v[68:71]
	v_mfma_f32_16x16x32_bf16 v[64:67], v[192:195], v[232:235], v[64:67]
	s_barrier
	s_setprio 0
	s_add_i32 s0, s0, s42
	v_lshl_add_u64 v[150:151], s[36:37], 0, v[170:171]
	s_mov_b32 m0, s0
	ds_read_b128 v[196:199], v154 offset:16384
	ds_read_b128 v[200:203], v154 offset:17408
	ds_read_b128 v[204:207], v154 offset:18432
	ds_read_b128 v[208:211], v154 offset:19456
	ds_read_b128 v[212:215], v154 offset:20480
	ds_read_b128 v[216:219], v154 offset:21504
	ds_read_b128 v[228:231], v154 offset:22528
	ds_read_b128 v[232:235], v154 offset:23552
	global_load_lds_dwordx4 v[150:151], off
	s_add_i32 m0, s0, 0x2000
	s_add_u32 s0, s36, 0xb0000
	v_lshl_add_u64 v[236:237], s[36:37], 0, v[136:137]
	s_addc_u32 s1, s37, 0
	s_add_i32 s13, s13, s42
	global_load_lds_dwordx4 v[236:237], off
	s_mov_b32 m0, s13
	v_lshl_add_u64 v[240:241], s[40:41], 0, v[134:135]
	global_load_lds_dwordx4 v170, s[0:1]
	s_add_i32 m0, s13, 0x2000
	s_nop 0
	global_load_lds_dwordx4 v136, s[0:1]
	v_lshl_add_u64 v[238:239], s[40:41], 0, v[132:133]
	s_waitcnt vmcnt(6)
	s_waitcnt lgkmcnt(0)
	s_barrier
	s_setprio 1
	v_mfma_f32_16x16x32_bf16 v[60:63], v[128:131], v[196:199], v[60:63]
	v_mfma_f32_16x16x32_bf16 v[56:59], v[156:159], v[196:199], v[56:59]
	v_mfma_f32_16x16x32_bf16 v[48:51], v[128:131], v[204:207], v[48:51]
	v_mfma_f32_16x16x32_bf16 v[40:43], v[156:159], v[204:207], v[40:43]
	v_mfma_f32_16x16x32_bf16 v[32:35], v[128:131], v[212:215], v[32:35]
	v_mfma_f32_16x16x32_bf16 v[24:27], v[156:159], v[212:215], v[24:27]
	v_mfma_f32_16x16x32_bf16 v[16:19], v[128:131], v[228:231], v[16:19]
	v_mfma_f32_16x16x32_bf16 v[8:11], v[156:159], v[228:231], v[8:11]
	v_mfma_f32_16x16x32_bf16 v[60:63], v[146:149], v[200:203], v[60:63]
	v_mfma_f32_16x16x32_bf16 v[56:59], v[160:163], v[200:203], v[56:59]
	v_mfma_f32_16x16x32_bf16 v[48:51], v[146:149], v[208:211], v[48:51]
	v_mfma_f32_16x16x32_bf16 v[40:43], v[160:163], v[208:211], v[40:43]
	v_mfma_f32_16x16x32_bf16 v[32:35], v[146:149], v[216:219], v[32:35]
	v_mfma_f32_16x16x32_bf16 v[24:27], v[160:163], v[216:219], v[24:27]
	v_mfma_f32_16x16x32_bf16 v[16:19], v[146:149], v[232:235], v[16:19]
	v_mfma_f32_16x16x32_bf16 v[8:11], v[160:163], v[232:235], v[8:11]
	v_mfma_f32_16x16x32_bf16 v[52:55], v[164:167], v[196:199], v[52:55]
	v_mfma_f32_16x16x32_bf16 v[44:47], v[188:191], v[196:199], v[44:47]
	v_mfma_f32_16x16x32_bf16 v[36:39], v[164:167], v[204:207], v[36:39]
	v_mfma_f32_16x16x32_bf16 v[28:31], v[188:191], v[204:207], v[28:31]
	v_mfma_f32_16x16x32_bf16 v[20:23], v[164:167], v[212:215], v[20:23]
	v_mfma_f32_16x16x32_bf16 v[12:15], v[188:191], v[212:215], v[12:15]
	v_mfma_f32_16x16x32_bf16 v[4:7], v[164:167], v[228:231], v[4:7]
	v_mfma_f32_16x16x32_bf16 v[0:3], v[188:191], v[228:231], v[0:3]
	v_mfma_f32_16x16x32_bf16 v[52:55], v[184:187], v[200:203], v[52:55]
	v_mfma_f32_16x16x32_bf16 v[44:47], v[192:195], v[200:203], v[44:47]
	v_mfma_f32_16x16x32_bf16 v[36:39], v[184:187], v[208:211], v[36:39]
	v_mfma_f32_16x16x32_bf16 v[28:31], v[192:195], v[208:211], v[28:31]
	v_mfma_f32_16x16x32_bf16 v[20:23], v[184:187], v[216:219], v[20:23]
	v_mfma_f32_16x16x32_bf16 v[12:15], v[192:195], v[216:219], v[12:15]
	v_mfma_f32_16x16x32_bf16 v[4:7], v[184:187], v[232:235], v[4:7]
	v_mfma_f32_16x16x32_bf16 v[0:3], v[192:195], v[232:235], v[0:3]
	s_barrier
	s_setprio 0
	s_add_i32 s13, 0, 0x18000
	v_add_u32_e32 v155, s13, v153
	s_add_i32 s30, 0, 0x1c000
	ds_read_b128 v[128:131], v155
	ds_read_b128 v[146:149], v155 offset:1024
	ds_read_b128 v[156:159], v155 offset:2048
	ds_read_b128 v[160:163], v155 offset:3072
	v_add_u32_e32 v155, s30, v153
	ds_read_b128 v[164:167], v155
	ds_read_b128 v[184:187], v155 offset:1024
	ds_read_b128 v[188:191], v155 offset:2048
	ds_read_b128 v[192:195], v155 offset:3072
	s_add_u32 s0, s40, 0xb0000
	s_addc_u32 s1, s41, 0
	s_mov_b32 m0, s45
	ds_read_b128 v[196:199], v154 offset:32768
	ds_read_b128 v[200:203], v154 offset:33792
	ds_read_b128 v[204:207], v154 offset:34816
	ds_read_b128 v[208:211], v154 offset:35840
	ds_read_b128 v[212:215], v154 offset:36864
	ds_read_b128 v[216:219], v154 offset:37888
	ds_read_b128 v[228:231], v154 offset:38912
	ds_read_b128 v[232:235], v154 offset:39936
	global_load_lds_dwordx4 v132, s[0:1]
	s_mov_b32 m0, s46
	s_nop 0
	global_load_lds_dwordx4 v134, s[0:1]
	s_mov_b32 m0, s43
	s_nop 0
	global_load_lds_dwordx4 v[238:239], off
	s_mov_b32 m0, s44
	s_nop 0
	global_load_lds_dwordx4 v[240:241], off
	s_waitcnt vmcnt(8)
	s_waitcnt lgkmcnt(0)
	s_barrier
	s_setprio 1
	v_mfma_f32_16x16x32_bf16 v[124:127], v[128:131], v[196:199], v[124:127]
	v_mfma_f32_16x16x32_bf16 v[120:123], v[156:159], v[196:199], v[120:123]
	v_mfma_f32_16x16x32_bf16 v[112:115], v[128:131], v[204:207], v[112:115]
	v_mfma_f32_16x16x32_bf16 v[104:107], v[156:159], v[204:207], v[104:107]
	v_mfma_f32_16x16x32_bf16 v[96:99], v[128:131], v[212:215], v[96:99]
	v_mfma_f32_16x16x32_bf16 v[88:91], v[156:159], v[212:215], v[88:91]
	v_mfma_f32_16x16x32_bf16 v[80:83], v[128:131], v[228:231], v[80:83]
	v_mfma_f32_16x16x32_bf16 v[72:75], v[156:159], v[228:231], v[72:75]
	v_mfma_f32_16x16x32_bf16 v[124:127], v[146:149], v[200:203], v[124:127]
	v_mfma_f32_16x16x32_bf16 v[120:123], v[160:163], v[200:203], v[120:123]
	v_mfma_f32_16x16x32_bf16 v[112:115], v[146:149], v[208:211], v[112:115]
	v_mfma_f32_16x16x32_bf16 v[104:107], v[160:163], v[208:211], v[104:107]
	v_mfma_f32_16x16x32_bf16 v[96:99], v[146:149], v[216:219], v[96:99]
	v_mfma_f32_16x16x32_bf16 v[88:91], v[160:163], v[216:219], v[88:91]
	v_mfma_f32_16x16x32_bf16 v[80:83], v[146:149], v[232:235], v[80:83]
	v_mfma_f32_16x16x32_bf16 v[72:75], v[160:163], v[232:235], v[72:75]
	v_mfma_f32_16x16x32_bf16 v[116:119], v[164:167], v[196:199], v[116:119]
	v_mfma_f32_16x16x32_bf16 v[108:111], v[188:191], v[196:199], v[108:111]
	v_mfma_f32_16x16x32_bf16 v[100:103], v[164:167], v[204:207], v[100:103]
	v_mfma_f32_16x16x32_bf16 v[92:95], v[188:191], v[204:207], v[92:95]
	v_mfma_f32_16x16x32_bf16 v[84:87], v[164:167], v[212:215], v[84:87]
	v_mfma_f32_16x16x32_bf16 v[76:79], v[188:191], v[212:215], v[76:79]
	v_mfma_f32_16x16x32_bf16 v[68:71], v[164:167], v[228:231], v[68:71]
	v_mfma_f32_16x16x32_bf16 v[64:67], v[188:191], v[228:231], v[64:67]
	v_mfma_f32_16x16x32_bf16 v[116:119], v[184:187], v[200:203], v[116:119]
	v_mfma_f32_16x16x32_bf16 v[108:111], v[192:195], v[200:203], v[108:111]
	v_mfma_f32_16x16x32_bf16 v[100:103], v[184:187], v[208:211], v[100:103]
	v_mfma_f32_16x16x32_bf16 v[92:95], v[192:195], v[208:211], v[92:95]
	v_mfma_f32_16x16x32_bf16 v[84:87], v[184:187], v[216:219], v[84:87]
	v_mfma_f32_16x16x32_bf16 v[76:79], v[192:195], v[216:219], v[76:79]
	v_mfma_f32_16x16x32_bf16 v[68:71], v[184:187], v[232:235], v[68:71]
	v_mfma_f32_16x16x32_bf16 v[64:67], v[192:195], v[232:235], v[64:67]
	s_barrier
	s_setprio 0
	s_add_i32 s0, s13, s42
	v_lshl_add_u64 v[150:151], v[150:151], 0, s[16:17]
	s_mov_b32 m0, s0
	ds_read_b128 v[196:199], v154 offset:49152
	ds_read_b128 v[200:203], v154 offset:50176
	ds_read_b128 v[204:207], v154 offset:51200
	ds_read_b128 v[208:211], v154 offset:52224
	ds_read_b128 v[212:215], v154 offset:53248
	ds_read_b128 v[216:219], v154 offset:54272
	ds_read_b128 v[228:231], v154 offset:55296
	ds_read_b128 v[232:235], v154 offset:56320
	global_load_lds_dwordx4 v[150:151], off
	s_add_i32 m0, s0, 0x2000
	s_add_u32 s0, s36, 0xb0080
	v_lshl_add_u64 v[150:151], v[236:237], 0, s[16:17]
	s_addc_u32 s1, s37, 0
	s_add_i32 s13, s30, s42
	global_load_lds_dwordx4 v[150:151], off
	s_mov_b32 m0, s13
	s_nop 0
	global_load_lds_dwordx4 v170, s[0:1]
	s_add_i32 m0, s13, 0x2000
	s_nop 0
	global_load_lds_dwordx4 v136, s[0:1]
	v_lshl_add_u64 v[150:151], v[238:239], 0, s[16:17]
	s_mov_b32 m0, s47
	s_nop 0
	global_load_lds_dwordx4 v[150:151], off
	v_lshl_add_u64 v[150:151], v[240:241], 0, s[16:17]
	s_mov_b32 m0, s48
	s_nop 0
	global_load_lds_dwordx4 v[150:151], off
	s_waitcnt vmcnt(6)
	s_waitcnt lgkmcnt(0)
	s_barrier
	s_setprio 1
	v_mfma_f32_16x16x32_bf16 v[60:63], v[128:131], v[196:199], v[60:63]
	v_mfma_f32_16x16x32_bf16 v[56:59], v[156:159], v[196:199], v[56:59]
	v_mfma_f32_16x16x32_bf16 v[48:51], v[128:131], v[204:207], v[48:51]
	v_mfma_f32_16x16x32_bf16 v[40:43], v[156:159], v[204:207], v[40:43]
	v_mfma_f32_16x16x32_bf16 v[32:35], v[128:131], v[212:215], v[32:35]
	v_mfma_f32_16x16x32_bf16 v[24:27], v[156:159], v[212:215], v[24:27]
	v_mfma_f32_16x16x32_bf16 v[16:19], v[128:131], v[228:231], v[16:19]
	v_mfma_f32_16x16x32_bf16 v[8:11], v[156:159], v[228:231], v[8:11]
	v_mfma_f32_16x16x32_bf16 v[60:63], v[146:149], v[200:203], v[60:63]
	v_mfma_f32_16x16x32_bf16 v[56:59], v[160:163], v[200:203], v[56:59]
	v_mfma_f32_16x16x32_bf16 v[48:51], v[146:149], v[208:211], v[48:51]
	v_mfma_f32_16x16x32_bf16 v[40:43], v[160:163], v[208:211], v[40:43]
	v_mfma_f32_16x16x32_bf16 v[32:35], v[146:149], v[216:219], v[32:35]
	v_mfma_f32_16x16x32_bf16 v[24:27], v[160:163], v[216:219], v[24:27]
	v_mfma_f32_16x16x32_bf16 v[16:19], v[146:149], v[232:235], v[16:19]
	v_mfma_f32_16x16x32_bf16 v[8:11], v[160:163], v[232:235], v[8:11]
	v_mfma_f32_16x16x32_bf16 v[52:55], v[164:167], v[196:199], v[52:55]
	v_mfma_f32_16x16x32_bf16 v[44:47], v[188:191], v[196:199], v[44:47]
	v_mfma_f32_16x16x32_bf16 v[36:39], v[164:167], v[204:207], v[36:39]
	v_mfma_f32_16x16x32_bf16 v[28:31], v[188:191], v[204:207], v[28:31]
	v_mfma_f32_16x16x32_bf16 v[20:23], v[164:167], v[212:215], v[20:23]
	v_mfma_f32_16x16x32_bf16 v[12:15], v[188:191], v[212:215], v[12:15]
	v_mfma_f32_16x16x32_bf16 v[4:7], v[164:167], v[228:231], v[4:7]
	v_mfma_f32_16x16x32_bf16 v[0:3], v[188:191], v[228:231], v[0:3]
	v_mfma_f32_16x16x32_bf16 v[52:55], v[184:187], v[200:203], v[52:55]
	v_mfma_f32_16x16x32_bf16 v[44:47], v[192:195], v[200:203], v[44:47]
	v_mfma_f32_16x16x32_bf16 v[36:39], v[184:187], v[208:211], v[36:39]
	v_mfma_f32_16x16x32_bf16 v[28:31], v[192:195], v[208:211], v[28:31]
	v_mfma_f32_16x16x32_bf16 v[20:23], v[184:187], v[216:219], v[20:23]
	v_mfma_f32_16x16x32_bf16 v[12:15], v[192:195], v[216:219], v[12:15]
	v_mfma_f32_16x16x32_bf16 v[4:7], v[184:187], v[232:235], v[4:7]
	v_mfma_f32_16x16x32_bf16 v[0:3], v[192:195], v[232:235], v[0:3]
	s_barrier
	s_setprio 0
	s_add_i32 s12, s12, 2
	s_add_u32 s54, s54, 0x100
	s_addc_u32 s55, s55, 0
	s_cmp_gt_u32 s12, 41
	s_mov_b64 s[30:31], s[34:35]
	s_cbranch_scc0 .LBB0_1029
	s_and_b64 vcc, exec, s[24:25]
	s_cbranch_vccz .LBB0_1032
	s_barrier

.Lrestag_1061:
	s_add_u32 s40, s36, 0x100
	s_addc_u32 s41, s37, 0
	s_add_i32 s0, 0, 0x10000
	s_cmp_eq_u32 s12, 40
	s_cselect_b32 s45, s9, s41
	s_cselect_b32 s44, s8, s40
	s_cselect_b32 s43, s35, s59
	s_cselect_b32 s42, s34, s58
	s_add_i32 s13, 0, 0x14000
	v_add_u32_e32 v140, s0, v197
	v_add_u32_e32 v184, s13, v197
	ds_read_b128 v[128:131], v140
	ds_read_b128 v[132:135], v140 offset:1024
	ds_read_b128 v[136:139], v140 offset:2048
	ds_read_b128 v[140:143], v140 offset:3072
	ds_read_b128 v[144:147], v184
	ds_read_b128 v[148:151], v184 offset:1024
	ds_read_b128 v[164:167], v184 offset:2048
	ds_read_b128 v[184:187], v184 offset:3072
	s_add_i32 m0, s47, 0xc000
	ds_read_b128 v[188:191], v198
	ds_read_b128 v[192:195], v198 offset:1024
	ds_read_b128 v[200:203], v198 offset:2048
	ds_read_b128 v[204:207], v198 offset:3072
	ds_read_b128 v[208:211], v198 offset:4096
	ds_read_b128 v[212:215], v198 offset:5120
	ds_read_b128 v[216:219], v198 offset:6144
	ds_read_b128 v[228:231], v198 offset:7168
	global_load_lds_dwordx4 v160, s[36:37]
	s_add_i32 m0, s47, 0xe000
	s_nop 0
	global_load_lds_dwordx4 v162, s[36:37]
	s_nop 0
	s_waitcnt lgkmcnt(0)
	s_barrier
	s_setprio 1
	v_mfma_f32_16x16x32_bf16 v[124:127], v[128:131], v[188:191], 0
	v_mfma_f32_16x16x32_bf16 v[120:123], v[136:139], v[188:191], 0
	v_mfma_f32_16x16x32_bf16 v[108:111], v[128:131], v[200:203], 0
	v_mfma_f32_16x16x32_bf16 v[104:107], v[136:139], v[200:203], 0
	v_mfma_f32_16x16x32_bf16 v[92:95], v[128:131], v[208:211], 0
	v_mfma_f32_16x16x32_bf16 v[88:91], v[136:139], v[208:211], 0
	v_mfma_f32_16x16x32_bf16 v[76:79], v[128:131], v[216:219], 0
	v_mfma_f32_16x16x32_bf16 v[72:75], v[136:139], v[216:219], 0
	v_mfma_f32_16x16x32_bf16 v[124:127], v[132:135], v[192:195], v[124:127]
	v_mfma_f32_16x16x32_bf16 v[120:123], v[140:143], v[192:195], v[120:123]
	v_mfma_f32_16x16x32_bf16 v[108:111], v[132:135], v[204:207], v[108:111]
	v_mfma_f32_16x16x32_bf16 v[104:107], v[140:143], v[204:207], v[104:107]
	v_mfma_f32_16x16x32_bf16 v[92:95], v[132:135], v[212:215], v[92:95]
	v_mfma_f32_16x16x32_bf16 v[88:91], v[140:143], v[212:215], v[88:91]
	v_mfma_f32_16x16x32_bf16 v[76:79], v[132:135], v[228:231], v[76:79]
	v_mfma_f32_16x16x32_bf16 v[72:75], v[140:143], v[228:231], v[72:75]
	v_mfma_f32_16x16x32_bf16 v[116:119], v[144:147], v[188:191], 0
	v_mfma_f32_16x16x32_bf16 v[112:115], v[164:167], v[188:191], 0
	v_mfma_f32_16x16x32_bf16 v[100:103], v[144:147], v[200:203], 0
	v_mfma_f32_16x16x32_bf16 v[96:99], v[164:167], v[200:203], 0
	v_mfma_f32_16x16x32_bf16 v[84:87], v[144:147], v[208:211], 0
	v_mfma_f32_16x16x32_bf16 v[80:83], v[164:167], v[208:211], 0
	v_mfma_f32_16x16x32_bf16 v[68:71], v[144:147], v[216:219], 0
	v_mfma_f32_16x16x32_bf16 v[64:67], v[164:167], v[216:219], 0
	v_mfma_f32_16x16x32_bf16 v[116:119], v[148:151], v[192:195], v[116:119]
	v_mfma_f32_16x16x32_bf16 v[112:115], v[184:187], v[192:195], v[112:115]
	v_mfma_f32_16x16x32_bf16 v[100:103], v[148:151], v[204:207], v[100:103]
	v_mfma_f32_16x16x32_bf16 v[96:99], v[184:187], v[204:207], v[96:99]
	v_mfma_f32_16x16x32_bf16 v[84:87], v[148:151], v[212:215], v[84:87]
	v_mfma_f32_16x16x32_bf16 v[80:83], v[184:187], v[212:215], v[80:83]
	v_mfma_f32_16x16x32_bf16 v[68:71], v[148:151], v[228:231], v[68:71]
	v_mfma_f32_16x16x32_bf16 v[64:67], v[184:187], v[228:231], v[64:67]
	s_barrier
	s_setprio 0
	s_add_i32 s0, s0, s46
	v_lshl_add_u64 v[232:233], s[42:43], 0, v[170:171]
	s_mov_b32 m0, s0
	ds_read_b128 v[188:191], v198 offset:16384
	ds_read_b128 v[192:195], v198 offset:17408
	ds_read_b128 v[200:203], v198 offset:18432
	ds_read_b128 v[204:207], v198 offset:19456
	ds_read_b128 v[208:211], v198 offset:20480
	ds_read_b128 v[212:215], v198 offset:21504
	ds_read_b128 v[216:219], v198 offset:22528
	ds_read_b128 v[228:231], v198 offset:23552
	global_load_lds_dwordx4 v[232:233], off
	s_add_i32 m0, s0, 0x2000
	s_add_u32 s0, s42, 0xb0000
	v_lshl_add_u64 v[234:235], s[42:43], 0, v[156:157]
	s_addc_u32 s1, s43, 0
	s_add_i32 s13, s13, s46
	global_load_lds_dwordx4 v[234:235], off
	s_mov_b32 m0, s13
	v_lshl_add_u64 v[238:239], s[44:45], 0, v[154:155]
	global_load_lds_dwordx4 v170, s[0:1]
	s_add_i32 m0, s13, 0x2000
	s_nop 0
	global_load_lds_dwordx4 v156, s[0:1]
	v_lshl_add_u64 v[236:237], s[44:45], 0, v[152:153]
	s_nop 0
	s_waitcnt lgkmcnt(0)
	s_barrier
	s_setprio 1
	v_mfma_f32_16x16x32_bf16 v[60:63], v[128:131], v[188:191], 0
	v_mfma_f32_16x16x32_bf16 v[56:59], v[136:139], v[188:191], 0
	v_mfma_f32_16x16x32_bf16 v[44:47], v[128:131], v[200:203], 0
	v_mfma_f32_16x16x32_bf16 v[40:43], v[136:139], v[200:203], 0
	v_mfma_f32_16x16x32_bf16 v[28:31], v[128:131], v[208:211], 0
	v_mfma_f32_16x16x32_bf16 v[24:27], v[136:139], v[208:211], 0
	v_mfma_f32_16x16x32_bf16 v[12:15], v[128:131], v[216:219], 0
	v_mfma_f32_16x16x32_bf16 v[8:11], v[136:139], v[216:219], 0
	v_mfma_f32_16x16x32_bf16 v[60:63], v[132:135], v[192:195], v[60:63]
	v_mfma_f32_16x16x32_bf16 v[56:59], v[140:143], v[192:195], v[56:59]
	v_mfma_f32_16x16x32_bf16 v[44:47], v[132:135], v[204:207], v[44:47]
	v_mfma_f32_16x16x32_bf16 v[40:43], v[140:143], v[204:207], v[40:43]
	v_mfma_f32_16x16x32_bf16 v[28:31], v[132:135], v[212:215], v[28:31]
	v_mfma_f32_16x16x32_bf16 v[24:27], v[140:143], v[212:215], v[24:27]
	v_mfma_f32_16x16x32_bf16 v[12:15], v[132:135], v[228:231], v[12:15]
	v_mfma_f32_16x16x32_bf16 v[8:11], v[140:143], v[228:231], v[8:11]
	v_mfma_f32_16x16x32_bf16 v[52:55], v[144:147], v[188:191], 0
	v_mfma_f32_16x16x32_bf16 v[48:51], v[164:167], v[188:191], 0
	v_mfma_f32_16x16x32_bf16 v[36:39], v[144:147], v[200:203], 0
	v_mfma_f32_16x16x32_bf16 v[32:35], v[164:167], v[200:203], 0
	v_mfma_f32_16x16x32_bf16 v[20:23], v[144:147], v[208:211], 0
	v_mfma_f32_16x16x32_bf16 v[16:19], v[164:167], v[208:211], 0
	v_mfma_f32_16x16x32_bf16 v[4:7], v[144:147], v[216:219], 0
	v_mfma_f32_16x16x32_bf16 v[0:3], v[164:167], v[216:219], 0
	v_mfma_f32_16x16x32_bf16 v[52:55], v[148:151], v[192:195], v[52:55]
	v_mfma_f32_16x16x32_bf16 v[48:51], v[184:187], v[192:195], v[48:51]
	v_mfma_f32_16x16x32_bf16 v[36:39], v[148:151], v[204:207], v[36:39]
	v_mfma_f32_16x16x32_bf16 v[32:35], v[184:187], v[204:207], v[32:35]
	v_mfma_f32_16x16x32_bf16 v[20:23], v[148:151], v[212:215], v[20:23]
	v_mfma_f32_16x16x32_bf16 v[16:19], v[184:187], v[212:215], v[16:19]
	v_mfma_f32_16x16x32_bf16 v[4:7], v[148:151], v[228:231], v[4:7]
	v_mfma_f32_16x16x32_bf16 v[0:3], v[184:187], v[228:231], v[0:3]
	s_barrier
	s_setprio 0
	s_add_i32 s13, 0, 0x18000
	s_add_i32 s36, 0, 0x1c000
	v_add_u32_e32 v140, s13, v197
	v_add_u32_e32 v184, s36, v197
	ds_read_b128 v[128:131], v140
	ds_read_b128 v[132:135], v140 offset:1024
	ds_read_b128 v[136:139], v140 offset:2048
	ds_read_b128 v[140:143], v140 offset:3072
	ds_read_b128 v[144:147], v184
	ds_read_b128 v[148:151], v184 offset:1024
	ds_read_b128 v[164:167], v184 offset:2048
	ds_read_b128 v[184:187], v184 offset:3072
	s_add_u32 s0, s44, 0xb0000
	s_addc_u32 s1, s45, 0
	s_mov_b32 m0, s49
	ds_read_b128 v[188:191], v198 offset:32768
	ds_read_b128 v[192:195], v198 offset:33792
	ds_read_b128 v[200:203], v198 offset:34816
	ds_read_b128 v[204:207], v198 offset:35840
	ds_read_b128 v[208:211], v198 offset:36864
	ds_read_b128 v[212:215], v198 offset:37888
	ds_read_b128 v[216:219], v198 offset:38912
	ds_read_b128 v[228:231], v198 offset:39936
	global_load_lds_dwordx4 v152, s[0:1]
	s_mov_b32 m0, s50
	s_nop 0
	global_load_lds_dwordx4 v154, s[0:1]
	s_mov_b32 m0, s47
	s_nop 0
	global_load_lds_dwordx4 v[236:237], off
	s_mov_b32 m0, s48
	s_nop 0
	global_load_lds_dwordx4 v[238:239], off
	s_waitcnt vmcnt(8)
	s_waitcnt lgkmcnt(0)
	s_barrier
	s_setprio 1
	v_mfma_f32_16x16x32_bf16 v[124:127], v[128:131], v[188:191], v[124:127]
	v_mfma_f32_16x16x32_bf16 v[120:123], v[136:139], v[188:191], v[120:123]
	v_mfma_f32_16x16x32_bf16 v[108:111], v[128:131], v[200:203], v[108:111]
	v_mfma_f32_16x16x32_bf16 v[104:107], v[136:139], v[200:203], v[104:107]
	v_mfma_f32_16x16x32_bf16 v[92:95], v[128:131], v[208:211], v[92:95]
	v_mfma_f32_16x16x32_bf16 v[88:91], v[136:139], v[208:211], v[88:91]
	v_mfma_f32_16x16x32_bf16 v[76:79], v[128:131], v[216:219], v[76:79]
	v_mfma_f32_16x16x32_bf16 v[72:75], v[136:139], v[216:219], v[72:75]
	v_mfma_f32_16x16x32_bf16 v[124:127], v[132:135], v[192:195], v[124:127]
	v_mfma_f32_16x16x32_bf16 v[120:123], v[140:143], v[192:195], v[120:123]
	v_mfma_f32_16x16x32_bf16 v[108:111], v[132:135], v[204:207], v[108:111]
	v_mfma_f32_16x16x32_bf16 v[104:107], v[140:143], v[204:207], v[104:107]
	v_mfma_f32_16x16x32_bf16 v[92:95], v[132:135], v[212:215], v[92:95]
	v_mfma_f32_16x16x32_bf16 v[88:91], v[140:143], v[212:215], v[88:91]
	v_mfma_f32_16x16x32_bf16 v[76:79], v[132:135], v[228:231], v[76:79]
	v_mfma_f32_16x16x32_bf16 v[72:75], v[140:143], v[228:231], v[72:75]
	v_mfma_f32_16x16x32_bf16 v[116:119], v[144:147], v[188:191], v[116:119]
	v_mfma_f32_16x16x32_bf16 v[112:115], v[164:167], v[188:191], v[112:115]
	v_mfma_f32_16x16x32_bf16 v[100:103], v[144:147], v[200:203], v[100:103]
	v_mfma_f32_16x16x32_bf16 v[96:99], v[164:167], v[200:203], v[96:99]
	v_mfma_f32_16x16x32_bf16 v[84:87], v[144:147], v[208:211], v[84:87]
	v_mfma_f32_16x16x32_bf16 v[80:83], v[164:167], v[208:211], v[80:83]
	v_mfma_f32_16x16x32_bf16 v[68:71], v[144:147], v[216:219], v[68:71]
	v_mfma_f32_16x16x32_bf16 v[64:67], v[164:167], v[216:219], v[64:67]
	v_mfma_f32_16x16x32_bf16 v[116:119], v[148:151], v[192:195], v[116:119]
	v_mfma_f32_16x16x32_bf16 v[112:115], v[184:187], v[192:195], v[112:115]
	v_mfma_f32_16x16x32_bf16 v[100:103], v[148:151], v[204:207], v[100:103]
	v_mfma_f32_16x16x32_bf16 v[96:99], v[184:187], v[204:207], v[96:99]
	v_mfma_f32_16x16x32_bf16 v[84:87], v[148:151], v[212:215], v[84:87]
	v_mfma_f32_16x16x32_bf16 v[80:83], v[184:187], v[212:215], v[80:83]
	v_mfma_f32_16x16x32_bf16 v[68:71], v[148:151], v[228:231], v[68:71]
	v_mfma_f32_16x16x32_bf16 v[64:67], v[184:187], v[228:231], v[64:67]
	s_barrier
	s_setprio 0
	s_add_i32 s0, s13, s46
	v_lshl_add_u64 v[232:233], v[232:233], 0, s[16:17]
	s_mov_b32 m0, s0
	ds_read_b128 v[188:191], v198 offset:49152
	ds_read_b128 v[192:195], v198 offset:50176
	ds_read_b128 v[200:203], v198 offset:51200
	ds_read_b128 v[204:207], v198 offset:52224
	ds_read_b128 v[208:211], v198 offset:53248
	ds_read_b128 v[212:215], v198 offset:54272
	ds_read_b128 v[216:219], v198 offset:55296
	ds_read_b128 v[228:231], v198 offset:56320
	global_load_lds_dwordx4 v[232:233], off
	s_add_i32 m0, s0, 0x2000
	s_add_u32 s0, s42, 0xb0080
	v_lshl_add_u64 v[232:233], v[234:235], 0, s[16:17]
	s_addc_u32 s1, s43, 0
	s_add_i32 s13, s36, s46
	global_load_lds_dwordx4 v[232:233], off
	s_mov_b32 m0, s13
	s_nop 0
	global_load_lds_dwordx4 v170, s[0:1]
	s_add_i32 m0, s13, 0x2000
	s_nop 0
	global_load_lds_dwordx4 v156, s[0:1]
	v_lshl_add_u64 v[232:233], v[236:237], 0, s[16:17]
	s_mov_b32 m0, s51
	s_nop 0
	global_load_lds_dwordx4 v[232:233], off
	v_lshl_add_u64 v[232:233], v[238:239], 0, s[16:17]
	s_mov_b32 m0, s52
	s_nop 0
	global_load_lds_dwordx4 v[232:233], off
	s_waitcnt vmcnt(6)
	s_waitcnt lgkmcnt(0)
	s_barrier
	s_setprio 1
	v_mfma_f32_16x16x32_bf16 v[60:63], v[128:131], v[188:191], v[60:63]
	v_mfma_f32_16x16x32_bf16 v[56:59], v[136:139], v[188:191], v[56:59]
	v_mfma_f32_16x16x32_bf16 v[44:47], v[128:131], v[200:203], v[44:47]
	v_mfma_f32_16x16x32_bf16 v[40:43], v[136:139], v[200:203], v[40:43]
	v_mfma_f32_16x16x32_bf16 v[28:31], v[128:131], v[208:211], v[28:31]
	v_mfma_f32_16x16x32_bf16 v[24:27], v[136:139], v[208:211], v[24:27]
	v_mfma_f32_16x16x32_bf16 v[12:15], v[128:131], v[216:219], v[12:15]
	v_mfma_f32_16x16x32_bf16 v[8:11], v[136:139], v[216:219], v[8:11]
	v_mfma_f32_16x16x32_bf16 v[60:63], v[132:135], v[192:195], v[60:63]
	v_mfma_f32_16x16x32_bf16 v[56:59], v[140:143], v[192:195], v[56:59]
	v_mfma_f32_16x16x32_bf16 v[44:47], v[132:135], v[204:207], v[44:47]
	v_mfma_f32_16x16x32_bf16 v[40:43], v[140:143], v[204:207], v[40:43]
	v_mfma_f32_16x16x32_bf16 v[28:31], v[132:135], v[212:215], v[28:31]
	v_mfma_f32_16x16x32_bf16 v[24:27], v[140:143], v[212:215], v[24:27]
	v_mfma_f32_16x16x32_bf16 v[12:15], v[132:135], v[228:231], v[12:15]
	v_mfma_f32_16x16x32_bf16 v[8:11], v[140:143], v[228:231], v[8:11]
	v_mfma_f32_16x16x32_bf16 v[52:55], v[144:147], v[188:191], v[52:55]
	v_mfma_f32_16x16x32_bf16 v[48:51], v[164:167], v[188:191], v[48:51]
	v_mfma_f32_16x16x32_bf16 v[36:39], v[144:147], v[200:203], v[36:39]
	v_mfma_f32_16x16x32_bf16 v[32:35], v[164:167], v[200:203], v[32:35]
	v_mfma_f32_16x16x32_bf16 v[20:23], v[144:147], v[208:211], v[20:23]
	v_mfma_f32_16x16x32_bf16 v[16:19], v[164:167], v[208:211], v[16:19]
	v_mfma_f32_16x16x32_bf16 v[4:7], v[144:147], v[216:219], v[4:7]
	v_mfma_f32_16x16x32_bf16 v[0:3], v[164:167], v[216:219], v[0:3]
	v_mfma_f32_16x16x32_bf16 v[52:55], v[148:151], v[192:195], v[52:55]
	v_mfma_f32_16x16x32_bf16 v[48:51], v[184:187], v[192:195], v[48:51]
	v_mfma_f32_16x16x32_bf16 v[36:39], v[148:151], v[204:207], v[36:39]
	v_mfma_f32_16x16x32_bf16 v[32:35], v[184:187], v[204:207], v[32:35]
	v_mfma_f32_16x16x32_bf16 v[20:23], v[148:151], v[212:215], v[20:23]
	v_mfma_f32_16x16x32_bf16 v[16:19], v[184:187], v[212:215], v[16:19]
	v_mfma_f32_16x16x32_bf16 v[4:7], v[148:151], v[228:231], v[4:7]
	v_mfma_f32_16x16x32_bf16 v[0:3], v[184:187], v[228:231], v[0:3]
	s_barrier
	s_setprio 0
	s_add_i32 s12, s12, 2
	s_add_u32 s58, s58, 0x100
	s_addc_u32 s59, s59, 0
	s_cmp_gt_u32 s12, 41
	s_mov_b64 s[36:37], s[40:41]
.LBB0_1061:
	s_add_u32 s40, s36, 0x100
	s_addc_u32 s41, s37, 0
	s_add_i32 s0, 0, 0x10000
	s_cmp_eq_u32 s12, 40
	s_cselect_b32 s45, s9, s41
	s_cselect_b32 s44, s8, s40
	s_cselect_b32 s43, s35, s59
	s_cselect_b32 s42, s34, s58
	s_add_i32 s13, 0, 0x14000
	v_add_u32_e32 v140, s0, v197
	v_add_u32_e32 v184, s13, v197
	ds_read_b128 v[128:131], v140
	ds_read_b128 v[132:135], v140 offset:1024
	ds_read_b128 v[136:139], v140 offset:2048
	ds_read_b128 v[140:143], v140 offset:3072
	ds_read_b128 v[144:147], v184
	ds_read_b128 v[148:151], v184 offset:1024
	ds_read_b128 v[164:167], v184 offset:2048
	ds_read_b128 v[184:187], v184 offset:3072
	s_add_i32 m0, s47, 0xc000
	ds_read_b128 v[188:191], v198
	ds_read_b128 v[192:195], v198 offset:1024
	ds_read_b128 v[200:203], v198 offset:2048
	ds_read_b128 v[204:207], v198 offset:3072
	ds_read_b128 v[208:211], v198 offset:4096
	ds_read_b128 v[212:215], v198 offset:5120
	ds_read_b128 v[216:219], v198 offset:6144
	ds_read_b128 v[228:231], v198 offset:7168
	global_load_lds_dwordx4 v160, s[36:37]
	s_add_i32 m0, s47, 0xe000
	s_nop 0
	global_load_lds_dwordx4 v162, s[36:37]
	s_waitcnt vmcnt(8)
	s_waitcnt lgkmcnt(0)
	s_barrier
	s_setprio 1
	v_mfma_f32_16x16x32_bf16 v[124:127], v[128:131], v[188:191], v[124:127]
	v_mfma_f32_16x16x32_bf16 v[120:123], v[136:139], v[188:191], v[120:123]
	v_mfma_f32_16x16x32_bf16 v[108:111], v[128:131], v[200:203], v[108:111]
	v_mfma_f32_16x16x32_bf16 v[104:107], v[136:139], v[200:203], v[104:107]
	v_mfma_f32_16x16x32_bf16 v[92:95], v[128:131], v[208:211], v[92:95]
	v_mfma_f32_16x16x32_bf16 v[88:91], v[136:139], v[208:211], v[88:91]
	v_mfma_f32_16x16x32_bf16 v[76:79], v[128:131], v[216:219], v[76:79]
	v_mfma_f32_16x16x32_bf16 v[72:75], v[136:139], v[216:219], v[72:75]
	v_mfma_f32_16x16x32_bf16 v[124:127], v[132:135], v[192:195], v[124:127]
	v_mfma_f32_16x16x32_bf16 v[120:123], v[140:143], v[192:195], v[120:123]
	v_mfma_f32_16x16x32_bf16 v[108:111], v[132:135], v[204:207], v[108:111]
	v_mfma_f32_16x16x32_bf16 v[104:107], v[140:143], v[204:207], v[104:107]
	v_mfma_f32_16x16x32_bf16 v[92:95], v[132:135], v[212:215], v[92:95]
	v_mfma_f32_16x16x32_bf16 v[88:91], v[140:143], v[212:215], v[88:91]
	v_mfma_f32_16x16x32_bf16 v[76:79], v[132:135], v[228:231], v[76:79]
	v_mfma_f32_16x16x32_bf16 v[72:75], v[140:143], v[228:231], v[72:75]
	v_mfma_f32_16x16x32_bf16 v[116:119], v[144:147], v[188:191], v[116:119]
	v_mfma_f32_16x16x32_bf16 v[112:115], v[164:167], v[188:191], v[112:115]
	v_mfma_f32_16x16x32_bf16 v[100:103], v[144:147], v[200:203], v[100:103]
	v_mfma_f32_16x16x32_bf16 v[96:99], v[164:167], v[200:203], v[96:99]
	v_mfma_f32_16x16x32_bf16 v[84:87], v[144:147], v[208:211], v[84:87]
	v_mfma_f32_16x16x32_bf16 v[80:83], v[164:167], v[208:211], v[80:83]
	v_mfma_f32_16x16x32_bf16 v[68:71], v[144:147], v[216:219], v[68:71]
	v_mfma_f32_16x16x32_bf16 v[64:67], v[164:167], v[216:219], v[64:67]
	v_mfma_f32_16x16x32_bf16 v[116:119], v[148:151], v[192:195], v[116:119]
	v_mfma_f32_16x16x32_bf16 v[112:115], v[184:187], v[192:195], v[112:115]
	v_mfma_f32_16x16x32_bf16 v[100:103], v[148:151], v[204:207], v[100:103]
	v_mfma_f32_16x16x32_bf16 v[96:99], v[184:187], v[204:207], v[96:99]
	v_mfma_f32_16x16x32_bf16 v[84:87], v[148:151], v[212:215], v[84:87]
	v_mfma_f32_16x16x32_bf16 v[80:83], v[184:187], v[212:215], v[80:83]
	v_mfma_f32_16x16x32_bf16 v[68:71], v[148:151], v[228:231], v[68:71]
	v_mfma_f32_16x16x32_bf16 v[64:67], v[184:187], v[228:231], v[64:67]
	s_barrier
	s_setprio 0
	s_add_i32 s0, s0, s46
	v_lshl_add_u64 v[232:233], s[42:43], 0, v[170:171]
	s_mov_b32 m0, s0
	ds_read_b128 v[188:191], v198 offset:16384
	ds_read_b128 v[192:195], v198 offset:17408
	ds_read_b128 v[200:203], v198 offset:18432
	ds_read_b128 v[204:207], v198 offset:19456
	ds_read_b128 v[208:211], v198 offset:20480
	ds_read_b128 v[212:215], v198 offset:21504
	ds_read_b128 v[216:219], v198 offset:22528
	ds_read_b128 v[228:231], v198 offset:23552
	global_load_lds_dwordx4 v[232:233], off
	s_add_i32 m0, s0, 0x2000
	s_add_u32 s0, s42, 0xb0000
	v_lshl_add_u64 v[234:235], s[42:43], 0, v[156:157]
	s_addc_u32 s1, s43, 0
	s_add_i32 s13, s13, s46
	global_load_lds_dwordx4 v[234:235], off
	s_mov_b32 m0, s13
	v_lshl_add_u64 v[238:239], s[44:45], 0, v[154:155]
	global_load_lds_dwordx4 v170, s[0:1]
	s_add_i32 m0, s13, 0x2000
	s_nop 0
	global_load_lds_dwordx4 v156, s[0:1]
	v_lshl_add_u64 v[236:237], s[44:45], 0, v[152:153]
	s_waitcnt vmcnt(6)
	s_waitcnt lgkmcnt(0)
	s_barrier
	s_setprio 1
	v_mfma_f32_16x16x32_bf16 v[60:63], v[128:131], v[188:191], v[60:63]
	v_mfma_f32_16x16x32_bf16 v[56:59], v[136:139], v[188:191], v[56:59]
	v_mfma_f32_16x16x32_bf16 v[44:47], v[128:131], v[200:203], v[44:47]
	v_mfma_f32_16x16x32_bf16 v[40:43], v[136:139], v[200:203], v[40:43]
	v_mfma_f32_16x16x32_bf16 v[28:31], v[128:131], v[208:211], v[28:31]
	v_mfma_f32_16x16x32_bf16 v[24:27], v[136:139], v[208:211], v[24:27]
	v_mfma_f32_16x16x32_bf16 v[12:15], v[128:131], v[216:219], v[12:15]
	v_mfma_f32_16x16x32_bf16 v[8:11], v[136:139], v[216:219], v[8:11]
	v_mfma_f32_16x16x32_bf16 v[60:63], v[132:135], v[192:195], v[60:63]
	v_mfma_f32_16x16x32_bf16 v[56:59], v[140:143], v[192:195], v[56:59]
	v_mfma_f32_16x16x32_bf16 v[44:47], v[132:135], v[204:207], v[44:47]
	v_mfma_f32_16x16x32_bf16 v[40:43], v[140:143], v[204:207], v[40:43]
	v_mfma_f32_16x16x32_bf16 v[28:31], v[132:135], v[212:215], v[28:31]
	v_mfma_f32_16x16x32_bf16 v[24:27], v[140:143], v[212:215], v[24:27]
	v_mfma_f32_16x16x32_bf16 v[12:15], v[132:135], v[228:231], v[12:15]
	v_mfma_f32_16x16x32_bf16 v[8:11], v[140:143], v[228:231], v[8:11]
	v_mfma_f32_16x16x32_bf16 v[52:55], v[144:147], v[188:191], v[52:55]
	v_mfma_f32_16x16x32_bf16 v[48:51], v[164:167], v[188:191], v[48:51]
	v_mfma_f32_16x16x32_bf16 v[36:39], v[144:147], v[200:203], v[36:39]
	v_mfma_f32_16x16x32_bf16 v[32:35], v[164:167], v[200:203], v[32:35]
	v_mfma_f32_16x16x32_bf16 v[20:23], v[144:147], v[208:211], v[20:23]
	v_mfma_f32_16x16x32_bf16 v[16:19], v[164:167], v[208:211], v[16:19]
	v_mfma_f32_16x16x32_bf16 v[4:7], v[144:147], v[216:219], v[4:7]
	v_mfma_f32_16x16x32_bf16 v[0:3], v[164:167], v[216:219], v[0:3]
	v_mfma_f32_16x16x32_bf16 v[52:55], v[148:151], v[192:195], v[52:55]
	v_mfma_f32_16x16x32_bf16 v[48:51], v[184:187], v[192:195], v[48:51]
	v_mfma_f32_16x16x32_bf16 v[36:39], v[148:151], v[204:207], v[36:39]
	v_mfma_f32_16x16x32_bf16 v[32:35], v[184:187], v[204:207], v[32:35]
	v_mfma_f32_16x16x32_bf16 v[20:23], v[148:151], v[212:215], v[20:23]
	v_mfma_f32_16x16x32_bf16 v[16:19], v[184:187], v[212:215], v[16:19]
	v_mfma_f32_16x16x32_bf16 v[4:7], v[148:151], v[228:231], v[4:7]
	v_mfma_f32_16x16x32_bf16 v[0:3], v[184:187], v[228:231], v[0:3]
	s_barrier
	s_setprio 0
	s_add_i32 s13, 0, 0x18000
	s_add_i32 s36, 0, 0x1c000
	v_add_u32_e32 v140, s13, v197
	v_add_u32_e32 v184, s36, v197
	ds_read_b128 v[128:131], v140
	ds_read_b128 v[132:135], v140 offset:1024
	ds_read_b128 v[136:139], v140 offset:2048
	ds_read_b128 v[140:143], v140 offset:3072
	ds_read_b128 v[144:147], v184
	ds_read_b128 v[148:151], v184 offset:1024
	ds_read_b128 v[164:167], v184 offset:2048
	ds_read_b128 v[184:187], v184 offset:3072
	s_add_u32 s0, s44, 0xb0000
	s_addc_u32 s1, s45, 0
	s_mov_b32 m0, s49
	ds_read_b128 v[188:191], v198 offset:32768
	ds_read_b128 v[192:195], v198 offset:33792
	ds_read_b128 v[200:203], v198 offset:34816
	ds_read_b128 v[204:207], v198 offset:35840
	ds_read_b128 v[208:211], v198 offset:36864
	ds_read_b128 v[212:215], v198 offset:37888
	ds_read_b128 v[216:219], v198 offset:38912
	ds_read_b128 v[228:231], v198 offset:39936
	global_load_lds_dwordx4 v152, s[0:1]
	s_mov_b32 m0, s50
	s_nop 0
	global_load_lds_dwordx4 v154, s[0:1]
	s_mov_b32 m0, s47
	s_nop 0
	global_load_lds_dwordx4 v[236:237], off
	s_mov_b32 m0, s48
	s_nop 0
	global_load_lds_dwordx4 v[238:239], off
	s_waitcnt vmcnt(8)
	s_waitcnt lgkmcnt(0)
	s_barrier
	s_setprio 1
	v_mfma_f32_16x16x32_bf16 v[124:127], v[128:131], v[188:191], v[124:127]
	v_mfma_f32_16x16x32_bf16 v[120:123], v[136:139], v[188:191], v[120:123]
	v_mfma_f32_16x16x32_bf16 v[108:111], v[128:131], v[200:203], v[108:111]
	v_mfma_f32_16x16x32_bf16 v[104:107], v[136:139], v[200:203], v[104:107]
	v_mfma_f32_16x16x32_bf16 v[92:95], v[128:131], v[208:211], v[92:95]
	v_mfma_f32_16x16x32_bf16 v[88:91], v[136:139], v[208:211], v[88:91]
	v_mfma_f32_16x16x32_bf16 v[76:79], v[128:131], v[216:219], v[76:79]
	v_mfma_f32_16x16x32_bf16 v[72:75], v[136:139], v[216:219], v[72:75]
	v_mfma_f32_16x16x32_bf16 v[124:127], v[132:135], v[192:195], v[124:127]
	v_mfma_f32_16x16x32_bf16 v[120:123], v[140:143], v[192:195], v[120:123]
	v_mfma_f32_16x16x32_bf16 v[108:111], v[132:135], v[204:207], v[108:111]
	v_mfma_f32_16x16x32_bf16 v[104:107], v[140:143], v[204:207], v[104:107]
	v_mfma_f32_16x16x32_bf16 v[92:95], v[132:135], v[212:215], v[92:95]
	v_mfma_f32_16x16x32_bf16 v[88:91], v[140:143], v[212:215], v[88:91]
	v_mfma_f32_16x16x32_bf16 v[76:79], v[132:135], v[228:231], v[76:79]
	v_mfma_f32_16x16x32_bf16 v[72:75], v[140:143], v[228:231], v[72:75]
	v_mfma_f32_16x16x32_bf16 v[116:119], v[144:147], v[188:191], v[116:119]
	v_mfma_f32_16x16x32_bf16 v[112:115], v[164:167], v[188:191], v[112:115]
	v_mfma_f32_16x16x32_bf16 v[100:103], v[144:147], v[200:203], v[100:103]
	v_mfma_f32_16x16x32_bf16 v[96:99], v[164:167], v[200:203], v[96:99]
	v_mfma_f32_16x16x32_bf16 v[84:87], v[144:147], v[208:211], v[84:87]
	v_mfma_f32_16x16x32_bf16 v[80:83], v[164:167], v[208:211], v[80:83]
	v_mfma_f32_16x16x32_bf16 v[68:71], v[144:147], v[216:219], v[68:71]
	v_mfma_f32_16x16x32_bf16 v[64:67], v[164:167], v[216:219], v[64:67]
	v_mfma_f32_16x16x32_bf16 v[116:119], v[148:151], v[192:195], v[116:119]
	v_mfma_f32_16x16x32_bf16 v[112:115], v[184:187], v[192:195], v[112:115]
	v_mfma_f32_16x16x32_bf16 v[100:103], v[148:151], v[204:207], v[100:103]
	v_mfma_f32_16x16x32_bf16 v[96:99], v[184:187], v[204:207], v[96:99]
	v_mfma_f32_16x16x32_bf16 v[84:87], v[148:151], v[212:215], v[84:87]
	v_mfma_f32_16x16x32_bf16 v[80:83], v[184:187], v[212:215], v[80:83]
	v_mfma_f32_16x16x32_bf16 v[68:71], v[148:151], v[228:231], v[68:71]
	v_mfma_f32_16x16x32_bf16 v[64:67], v[184:187], v[228:231], v[64:67]
	s_barrier
	s_setprio 0
	s_add_i32 s0, s13, s46
	v_lshl_add_u64 v[232:233], v[232:233], 0, s[16:17]
	s_mov_b32 m0, s0
	ds_read_b128 v[188:191], v198 offset:49152
	ds_read_b128 v[192:195], v198 offset:50176
	ds_read_b128 v[200:203], v198 offset:51200
	ds_read_b128 v[204:207], v198 offset:52224
	ds_read_b128 v[208:211], v198 offset:53248
	ds_read_b128 v[212:215], v198 offset:54272
	ds_read_b128 v[216:219], v198 offset:55296
	ds_read_b128 v[228:231], v198 offset:56320
	global_load_lds_dwordx4 v[232:233], off
	s_add_i32 m0, s0, 0x2000
	s_add_u32 s0, s42, 0xb0080
	v_lshl_add_u64 v[232:233], v[234:235], 0, s[16:17]
	s_addc_u32 s1, s43, 0
	s_add_i32 s13, s36, s46
	global_load_lds_dwordx4 v[232:233], off
	s_mov_b32 m0, s13
	s_nop 0
	global_load_lds_dwordx4 v170, s[0:1]
	s_add_i32 m0, s13, 0x2000
	s_nop 0
	global_load_lds_dwordx4 v156, s[0:1]
	v_lshl_add_u64 v[232:233], v[236:237], 0, s[16:17]
	s_mov_b32 m0, s51
	s_nop 0
	global_load_lds_dwordx4 v[232:233], off
	v_lshl_add_u64 v[232:233], v[238:239], 0, s[16:17]
	s_mov_b32 m0, s52
	s_nop 0
	global_load_lds_dwordx4 v[232:233], off
	s_waitcnt vmcnt(6)
	s_waitcnt lgkmcnt(0)
	s_barrier
	s_setprio 1
	v_mfma_f32_16x16x32_bf16 v[60:63], v[128:131], v[188:191], v[60:63]
	v_mfma_f32_16x16x32_bf16 v[56:59], v[136:139], v[188:191], v[56:59]
	v_mfma_f32_16x16x32_bf16 v[44:47], v[128:131], v[200:203], v[44:47]
	v_mfma_f32_16x16x32_bf16 v[40:43], v[136:139], v[200:203], v[40:43]
	v_mfma_f32_16x16x32_bf16 v[28:31], v[128:131], v[208:211], v[28:31]
	v_mfma_f32_16x16x32_bf16 v[24:27], v[136:139], v[208:211], v[24:27]
	v_mfma_f32_16x16x32_bf16 v[12:15], v[128:131], v[216:219], v[12:15]
	v_mfma_f32_16x16x32_bf16 v[8:11], v[136:139], v[216:219], v[8:11]
	v_mfma_f32_16x16x32_bf16 v[60:63], v[132:135], v[192:195], v[60:63]
	v_mfma_f32_16x16x32_bf16 v[56:59], v[140:143], v[192:195], v[56:59]
	v_mfma_f32_16x16x32_bf16 v[44:47], v[132:135], v[204:207], v[44:47]
	v_mfma_f32_16x16x32_bf16 v[40:43], v[140:143], v[204:207], v[40:43]
	v_mfma_f32_16x16x32_bf16 v[28:31], v[132:135], v[212:215], v[28:31]
	v_mfma_f32_16x16x32_bf16 v[24:27], v[140:143], v[212:215], v[24:27]
	v_mfma_f32_16x16x32_bf16 v[12:15], v[132:135], v[228:231], v[12:15]
	v_mfma_f32_16x16x32_bf16 v[8:11], v[140:143], v[228:231], v[8:11]
	v_mfma_f32_16x16x32_bf16 v[52:55], v[144:147], v[188:191], v[52:55]
	v_mfma_f32_16x16x32_bf16 v[48:51], v[164:167], v[188:191], v[48:51]
	v_mfma_f32_16x16x32_bf16 v[36:39], v[144:147], v[200:203], v[36:39]
	v_mfma_f32_16x16x32_bf16 v[32:35], v[164:167], v[200:203], v[32:35]
	v_mfma_f32_16x16x32_bf16 v[20:23], v[144:147], v[208:211], v[20:23]
	v_mfma_f32_16x16x32_bf16 v[16:19], v[164:167], v[208:211], v[16:19]
	v_mfma_f32_16x16x32_bf16 v[4:7], v[144:147], v[216:219], v[4:7]
	v_mfma_f32_16x16x32_bf16 v[0:3], v[164:167], v[216:219], v[0:3]
	v_mfma_f32_16x16x32_bf16 v[52:55], v[148:151], v[192:195], v[52:55]
	v_mfma_f32_16x16x32_bf16 v[48:51], v[184:187], v[192:195], v[48:51]
	v_mfma_f32_16x16x32_bf16 v[36:39], v[148:151], v[204:207], v[36:39]
	v_mfma_f32_16x16x32_bf16 v[32:35], v[184:187], v[204:207], v[32:35]
	v_mfma_f32_16x16x32_bf16 v[20:23], v[148:151], v[212:215], v[20:23]
	v_mfma_f32_16x16x32_bf16 v[16:19], v[184:187], v[212:215], v[16:19]
	v_mfma_f32_16x16x32_bf16 v[4:7], v[148:151], v[228:231], v[4:7]
	v_mfma_f32_16x16x32_bf16 v[0:3], v[184:187], v[228:231], v[0:3]
	s_barrier
	s_setprio 0
	s_add_i32 s12, s12, 2
	s_add_u32 s58, s58, 0x100
	s_addc_u32 s59, s59, 0
	s_cmp_gt_u32 s12, 41
	s_mov_b64 s[36:37], s[40:41]
	s_cbranch_scc0 .LBB0_1061
	s_and_b64 vcc, exec, s[30:31]
	s_cbranch_vccz .LBB0_1064
	s_barrier
